# prologue weight-transpose row loads issued all at once; non-temporal policy on read-once streams (x rows, f32 weights, S5 u, attention Q, epilogue residual/Y tiles); redundant L1 invalidate dropped
# speedup vs baseline: 1.0921x; 1.0597x over previous
.LBB0_123:
	s_andn2_b64 vcc, exec, s[12:13]
	s_cbranch_vccnz .LBB0_125
	s_lshl_b32 s12, s40, 1
	s_add_i32 s12, s12, 0x1dd80
	s_and_b32 s13, s12, 0x1ffc0
	s_lshl_b32 s12, s40, 5
	s_and_b32 s12, s12, 0x3e0
	s_lshl_b32 s20, s12, 2
	v_or_b32_e32 v2, s13, v61
	v_lshl_add_u64 v[0:1], v[14:15], 0, s[20:21]
	v_lshlrev_b32_e32 v10, 12, v2
	v_or_b32_e32 v4, s13, v64
	v_lshl_add_u64 v[2:3], v[0:1], 0, v[10:11]
	v_lshlrev_b32_e32 v10, 12, v4
	v_or_b32_e32 v6, s13, v66
	v_lshl_add_u64 v[4:5], v[0:1], 0, v[10:11]
	v_lshlrev_b32_e32 v10, 12, v6
	v_lshl_add_u64 v[6:7], v[0:1], 0, v[10:11]
	v_or_b32_e32 v10, s13, v68
	v_lshlrev_b32_e32 v10, 12, v10
	v_lshl_add_u64 v[50:51], v[0:1], 0, v[10:11]
	v_or_b32_e32 v10, s13, v70
	v_lshlrev_b32_e32 v10, 12, v10
	v_lshl_add_u64 v[52:53], v[0:1], 0, v[10:11]
	v_or_b32_e32 v10, s13, v72
	v_lshlrev_b32_e32 v10, 12, v10
	v_lshl_add_u64 v[54:55], v[0:1], 0, v[10:11]
	v_or_b32_e32 v10, s13, v74
	v_lshlrev_b32_e32 v10, 12, v10
	v_lshl_add_u64 v[56:57], v[0:1], 0, v[10:11]
	v_or_b32_e32 v10, s13, v76
	v_lshlrev_b32_e32 v10, 12, v10
	v_lshl_add_u64 v[138:139], v[0:1], 0, v[10:11]
	global_load_dword v47, v[2:3], off nt
	global_load_dword v137, v[4:5], off nt
	global_load_dword v140, v[6:7], off nt
	global_load_dword v141, v[50:51], off nt
	global_load_dword v142, v[52:53], off nt
	global_load_dword v143, v[54:55], off nt
	global_load_dword v150, v[56:57], off nt
	global_load_dword v151, v[138:139], off nt
	v_or_b32_e32 v2, s13, v78
	v_lshlrev_b32_e32 v10, 12, v2
	v_or_b32_e32 v4, s13, v80
	v_lshl_add_u64 v[2:3], v[0:1], 0, v[10:11]
	v_lshlrev_b32_e32 v10, 12, v4
	v_or_b32_e32 v6, s13, v82
	v_lshl_add_u64 v[4:5], v[0:1], 0, v[10:11]
	v_lshlrev_b32_e32 v10, 12, v6
	v_lshl_add_u64 v[6:7], v[0:1], 0, v[10:11]
	v_or_b32_e32 v10, s13, v84
	v_lshlrev_b32_e32 v10, 12, v10
	v_lshl_add_u64 v[50:51], v[0:1], 0, v[10:11]
	v_or_b32_e32 v10, s13, v86
	v_lshlrev_b32_e32 v10, 12, v10
	v_lshl_add_u64 v[52:53], v[0:1], 0, v[10:11]
	v_or_b32_e32 v10, s13, v88
	v_lshlrev_b32_e32 v10, 12, v10
	v_lshl_add_u64 v[54:55], v[0:1], 0, v[10:11]
	v_or_b32_e32 v10, s13, v90
	v_lshlrev_b32_e32 v10, 12, v10
	v_lshl_add_u64 v[56:57], v[0:1], 0, v[10:11]
	v_or_b32_e32 v10, s13, v92
	v_lshlrev_b32_e32 v10, 12, v10
	v_lshl_add_u64 v[138:139], v[0:1], 0, v[10:11]
	global_load_dword v152, v[2:3], off nt
	global_load_dword v153, v[4:5], off nt
	global_load_dword v154, v[6:7], off nt
	global_load_dword v155, v[50:51], off nt
	global_load_dword v156, v[52:53], off nt
	global_load_dword v157, v[54:55], off nt
	global_load_dword v158, v[56:57], off nt
	global_load_dword v159, v[138:139], off nt
	v_or_b32_e32 v2, s13, v94
	v_lshlrev_b32_e32 v10, 12, v2
	v_or_b32_e32 v4, s13, v96
	v_lshl_add_u64 v[2:3], v[0:1], 0, v[10:11]
	v_lshlrev_b32_e32 v10, 12, v4
	v_or_b32_e32 v6, s13, v98
	v_lshl_add_u64 v[4:5], v[0:1], 0, v[10:11]
	v_lshlrev_b32_e32 v10, 12, v6
	v_lshl_add_u64 v[6:7], v[0:1], 0, v[10:11]
	v_or_b32_e32 v10, s13, v100
	v_lshlrev_b32_e32 v10, 12, v10
	v_lshl_add_u64 v[50:51], v[0:1], 0, v[10:11]
	v_or_b32_e32 v10, s13, v102
	v_lshlrev_b32_e32 v10, 12, v10
	v_lshl_add_u64 v[52:53], v[0:1], 0, v[10:11]
	v_or_b32_e32 v10, s13, v104
	v_lshlrev_b32_e32 v10, 12, v10
	v_lshl_add_u64 v[54:55], v[0:1], 0, v[10:11]
	v_or_b32_e32 v10, s13, v106
	v_lshlrev_b32_e32 v10, 12, v10
	v_lshl_add_u64 v[56:57], v[0:1], 0, v[10:11]
	v_or_b32_e32 v10, s13, v108
	v_lshlrev_b32_e32 v10, 12, v10
	v_lshl_add_u64 v[138:139], v[0:1], 0, v[10:11]
	global_load_dword v160, v[2:3], off nt
	global_load_dword v161, v[4:5], off nt
	global_load_dword v162, v[6:7], off nt
	global_load_dword v163, v[50:51], off nt
	global_load_dword v164, v[52:53], off nt
	global_load_dword v165, v[54:55], off nt
	global_load_dword v166, v[56:57], off nt
	s_nop 0
	global_load_dword v138, v[138:139], off nt
	v_or_b32_e32 v2, s13, v110
	v_lshlrev_b32_e32 v10, 12, v2
	v_or_b32_e32 v4, s13, v112
	v_lshl_add_u64 v[2:3], v[0:1], 0, v[10:11]
	v_lshlrev_b32_e32 v10, 12, v4
	v_or_b32_e32 v6, s13, v113
	v_lshl_add_u64 v[4:5], v[0:1], 0, v[10:11]
	v_lshlrev_b32_e32 v10, 12, v6
	v_lshl_add_u64 v[6:7], v[0:1], 0, v[10:11]
	v_or_b32_e32 v10, s13, v114
	v_lshlrev_b32_e32 v10, 12, v10
	v_lshl_add_u64 v[50:51], v[0:1], 0, v[10:11]
	v_or_b32_e32 v10, s13, v115
	v_lshlrev_b32_e32 v10, 12, v10
	v_lshl_add_u64 v[52:53], v[0:1], 0, v[10:11]
	v_or_b32_e32 v10, s13, v116
	v_lshlrev_b32_e32 v10, 12, v10
	v_lshl_add_u64 v[54:55], v[0:1], 0, v[10:11]
	v_or_b32_e32 v10, s13, v117
	v_lshlrev_b32_e32 v10, 12, v10
	v_lshl_add_u64 v[56:57], v[0:1], 0, v[10:11]
	v_or_b32_e32 v10, s13, v118
	v_lshlrev_b32_e32 v10, 12, v10
	v_lshl_add_u64 v[0:1], v[0:1], 0, v[10:11]
	global_load_dword v2, v[2:3], off nt
	s_nop 0
	global_load_dword v3, v[4:5], off nt
	s_nop 0
	global_load_dword v4, v[6:7], off nt
	global_load_dword v5, v[50:51], off nt
	s_nop 0
	global_load_dword v6, v[52:53], off nt
	global_load_dword v7, v[54:55], off nt
	global_load_dword v10, v[56:57], off nt
	s_nop 0
	global_load_dword v0, v[0:1], off nt
	v_add_u32_e32 v1, v62, v63
	s_waitcnt vmcnt(30)
	ds_write2_b32 v1, v47, v137 offset1:66
	s_waitcnt vmcnt(28)
	ds_write2_b32 v1, v140, v141 offset0:132 offset1:198
	v_add_u32_e32 v1, 0x400, v1
	s_waitcnt vmcnt(26)
	ds_write2_b32 v1, v142, v143 offset0:8 offset1:74
	v_add_u32_e32 v1, v62, v75
	s_waitcnt vmcnt(24)
	ds_write2_b32 v1, v150, v151 offset1:66
	s_waitcnt vmcnt(22)
	ds_write2_b32 v1, v152, v153 offset0:132 offset1:198
	v_add_u32_e32 v1, 0x400, v1
	s_waitcnt vmcnt(20)
	ds_write2_b32 v1, v154, v155 offset0:8 offset1:74
	v_add_u32_e32 v1, v62, v87
	s_waitcnt vmcnt(18)
	ds_write2_b32 v1, v156, v157 offset1:66
	s_waitcnt vmcnt(16)
	ds_write2_b32 v1, v158, v159 offset0:132 offset1:198
	v_add_u32_e32 v1, 0x400, v1
	s_lshl_b32 s20, s13, 1
	s_waitcnt vmcnt(14)
	ds_write2_b32 v1, v160, v161 offset0:8 offset1:74
	v_add_u32_e32 v1, v62, v99
	s_waitcnt vmcnt(12)
	ds_write2_b32 v1, v162, v163 offset1:66
	s_waitcnt vmcnt(10)
	ds_write2_b32 v1, v164, v165 offset0:132 offset1:198
	v_add_u32_e32 v1, 0x400, v1
	s_waitcnt vmcnt(8)
	ds_write2_b32 v1, v166, v138 offset0:8 offset1:74
	v_add_u32_e32 v1, v62, v111
	s_waitcnt vmcnt(6)
	ds_write2_b32 v1, v2, v3 offset1:66
	s_waitcnt vmcnt(4)
	ds_write2_b32 v1, v4, v5 offset0:132 offset1:198
	v_add_u32_e32 v1, 0x400, v1
	s_waitcnt vmcnt(2)
	ds_write2_b32 v1, v6, v7 offset0:8 offset1:74
	s_waitcnt vmcnt(0)
	ds_write2_b32 v1, v10, v0 offset0:140 offset1:206
	s_waitcnt lgkmcnt(0)
	ds_read2_b32 v[0:1], v120 offset1:33
	v_or_b32_e32 v10, s12, v119
	s_waitcnt lgkmcnt(0)
	v_cvt_pk_bf16_f32 v0, v0, v1
	ds_read2_b32 v[2:3], v120 offset0:66 offset1:99
	v_mul_u32_u24_e32 v10, 0xb00, v10
	s_waitcnt lgkmcnt(0)
	v_cvt_pk_bf16_f32 v1, v2, v3
	ds_read2_b32 v[2:3], v120 offset0:132 offset1:165
	v_lshl_add_u64 v[6:7], v[20:21], 0, s[20:21]
	v_lshlrev_b32_e32 v10, 1, v10
	s_waitcnt lgkmcnt(0)
	v_cvt_pk_bf16_f32 v2, v2, v3
	ds_read2_b32 v[4:5], v120 offset0:198 offset1:231
	s_waitcnt lgkmcnt(0)
	v_cvt_pk_bf16_f32 v3, v4, v5
	v_lshl_add_u64 v[50:51], v[6:7], 0, v[10:11]
	v_or_b32_e32 v10, s12, v121
	ds_read2_b32 v[4:5], v120 offset0:8 offset1:41
	global_store_dwordx4 v[50:51], v[0:3], off
	v_mul_u32_u24_e32 v10, 0xb00, v10
	v_lshlrev_b32_e32 v10, 1, v10
	s_waitcnt lgkmcnt(0)
	v_cvt_pk_bf16_f32 v0, v4, v5
	ds_read2_b32 v[2:3], v120 offset0:74 offset1:107
	s_waitcnt lgkmcnt(0)
	v_cvt_pk_bf16_f32 v1, v2, v3
	ds_read2_b32 v[2:3], v120 offset0:140 offset1:173
	s_waitcnt lgkmcnt(0)
	v_cvt_pk_bf16_f32 v2, v2, v3
	ds_read2_b32 v[4:5], v120 offset0:206 offset1:239
	s_waitcnt lgkmcnt(0)
	v_cvt_pk_bf16_f32 v3, v4, v5
	v_lshl_add_u64 v[50:51], v[6:7], 0, v[10:11]
	v_or_b32_e32 v10, s12, v122
	ds_read2_b32 v[4:5], v120 offset0:16 offset1:49
	global_store_dwordx4 v[50:51], v[0:3], off
	v_mul_u32_u24_e32 v10, 0xb00, v10
	v_lshlrev_b32_e32 v10, 1, v10
	s_waitcnt lgkmcnt(0)
	v_cvt_pk_bf16_f32 v0, v4, v5
	ds_read2_b32 v[2:3], v120 offset0:82 offset1:115
	s_waitcnt lgkmcnt(0)
	v_cvt_pk_bf16_f32 v1, v2, v3
	ds_read2_b32 v[2:3], v120 offset0:148 offset1:181
	s_waitcnt lgkmcnt(0)
	v_cvt_pk_bf16_f32 v2, v2, v3
	ds_read2_b32 v[4:5], v120 offset0:214 offset1:247
	s_waitcnt lgkmcnt(0)
	v_cvt_pk_bf16_f32 v3, v4, v5
	v_lshl_add_u64 v[50:51], v[6:7], 0, v[10:11]
	ds_read2_b32 v[4:5], v120 offset0:24 offset1:57
	global_store_dwordx4 v[50:51], v[0:3], off
	s_waitcnt lgkmcnt(0)
	s_nop 0
	v_cvt_pk_bf16_f32 v0, v4, v5
	ds_read2_b32 v[2:3], v120 offset0:90 offset1:123
	s_waitcnt lgkmcnt(0)
	v_cvt_pk_bf16_f32 v1, v2, v3
	ds_read2_b32 v[2:3], v120 offset0:156 offset1:189
	s_waitcnt lgkmcnt(0)
	v_cvt_pk_bf16_f32 v2, v2, v3
	ds_read2_b32 v[4:5], v120 offset0:222 offset1:255
	s_waitcnt lgkmcnt(0)
	v_cvt_pk_bf16_f32 v3, v4, v5
	v_or_b32_e32 v4, s12, v123
	v_mul_u32_u24_e32 v4, 0xb00, v4
	v_lshlrev_b32_e32 v10, 1, v4
	v_lshl_add_u64 v[4:5], v[6:7], 0, v[10:11]
	global_store_dwordx4 v[4:5], v[0:3], off
	s_waitcnt lgkmcnt(0)

.LBB0_131:
	s_lshl_b32 s12, s15, 6
	s_and_b32 s15, s12, 0x7fc0
	s_lshl_b32 s20, s16, 2
	v_lshl_add_u64 v[0:1], v[22:23], 0, s[20:21]
	v_or_b32_e32 v4, s15, v61
	v_mad_u64_u32 v[2:3], s[12:13], v4, s51, v[0:1]
	s_mov_b32 s16, 0xac00
	s_mov_b32 s17, 0
	v_lshlrev_b32_e32 v4, 2, v4
	global_load_dword v176, v[2:3], off nt
	v_lshl_add_u64 v[2:3], v[2:3], 0, s[16:17]
	global_load_dword v177, v[2:3], off nt
	v_lshl_add_u64 v[2:3], v[2:3], 0, s[16:17]
	global_load_dword v178, v[2:3], off nt
	v_lshl_add_u64 v[2:3], v[2:3], 0, s[16:17]
	global_load_dword v179, v[2:3], off nt
	v_lshl_add_u64 v[2:3], v[2:3], 0, s[16:17]
	global_load_dword v180, v[2:3], off nt
	v_lshl_add_u64 v[2:3], v[2:3], 0, s[16:17]
	global_load_dword v181, v[2:3], off nt
	v_lshl_add_u64 v[2:3], v[2:3], 0, s[16:17]
	global_load_dword v182, v[2:3], off nt
	v_lshl_add_u64 v[2:3], v[2:3], 0, s[16:17]
	global_load_dword v183, v[2:3], off nt
	v_lshl_add_u64 v[2:3], v[2:3], 0, s[16:17]
	global_load_dword v184, v[2:3], off nt
	v_lshl_add_u64 v[2:3], v[2:3], 0, s[16:17]
	global_load_dword v185, v[2:3], off nt
	v_lshl_add_u64 v[2:3], v[2:3], 0, s[16:17]
	global_load_dword v186, v[2:3], off nt
	v_lshl_add_u64 v[2:3], v[2:3], 0, s[16:17]
	global_load_dword v187, v[2:3], off nt
	v_lshl_add_u64 v[2:3], v[2:3], 0, s[16:17]
	global_load_dword v188, v[2:3], off nt
	v_lshl_add_u64 v[2:3], v[2:3], 0, s[16:17]
	global_load_dword v189, v[2:3], off nt
	v_lshl_add_u64 v[2:3], v[2:3], 0, s[16:17]
	global_load_dword v190, v[2:3], off nt
	v_lshl_add_u64 v[2:3], v[2:3], 0, s[16:17]
	global_load_dword v191, v[2:3], off nt
	v_lshl_add_u64 v[2:3], v[2:3], 0, s[16:17]
	global_load_dword v192, v[2:3], off nt
	v_lshl_add_u64 v[2:3], v[2:3], 0, s[16:17]
	global_load_dword v193, v[2:3], off nt
	v_lshl_add_u64 v[2:3], v[2:3], 0, s[16:17]
	global_load_dword v194, v[2:3], off nt
	v_lshl_add_u64 v[2:3], v[2:3], 0, s[16:17]
	global_load_dword v195, v[2:3], off nt
	v_lshl_add_u64 v[2:3], v[2:3], 0, s[16:17]
	global_load_dword v196, v[2:3], off nt
	v_lshl_add_u64 v[2:3], v[2:3], 0, s[16:17]
	global_load_dword v197, v[2:3], off nt
	v_lshl_add_u64 v[2:3], v[2:3], 0, s[16:17]
	global_load_dword v198, v[2:3], off nt
	v_lshl_add_u64 v[2:3], v[2:3], 0, s[16:17]
	global_load_dword v199, v[2:3], off nt
	v_lshl_add_u64 v[2:3], v[2:3], 0, s[16:17]
	global_load_dword v200, v[2:3], off nt
	v_lshl_add_u64 v[2:3], v[2:3], 0, s[16:17]
	global_load_dword v201, v[2:3], off nt
	v_lshl_add_u64 v[2:3], v[2:3], 0, s[16:17]
	global_load_dword v202, v[2:3], off nt
	v_lshl_add_u64 v[2:3], v[2:3], 0, s[16:17]
	global_load_dword v203, v[2:3], off nt
	v_lshl_add_u64 v[2:3], v[2:3], 0, s[16:17]
	global_load_dword v204, v[2:3], off nt
	v_lshl_add_u64 v[2:3], v[2:3], 0, s[16:17]
	global_load_dword v205, v[2:3], off nt
	v_lshl_add_u64 v[2:3], v[2:3], 0, s[16:17]
	global_load_dword v206, v[2:3], off nt
	v_lshl_add_u64 v[2:3], v[2:3], 0, s[16:17]
	global_load_dword v207, v[2:3], off nt
	v_mov_b32_e32 v208, 1.0
	v_mov_b32_e32 v209, 1.0
	v_mov_b32_e32 v210, 1.0
	v_mov_b32_e32 v211, 1.0
	v_mov_b32_e32 v212, 1.0
	v_mov_b32_e32 v213, 1.0
	v_mov_b32_e32 v214, 1.0
	v_mov_b32_e32 v215, 1.0
	v_mov_b32_e32 v216, 1.0
	v_mov_b32_e32 v217, 1.0
	v_mov_b32_e32 v218, 1.0
	v_mov_b32_e32 v219, 1.0
	v_mov_b32_e32 v220, 1.0
	v_mov_b32_e32 v221, 1.0
	v_mov_b32_e32 v222, 1.0
	v_mov_b32_e32 v223, 1.0
	v_mov_b32_e32 v224, 1.0
	v_mov_b32_e32 v225, 1.0
	v_mov_b32_e32 v226, 1.0
	v_mov_b32_e32 v227, 1.0
	v_mov_b32_e32 v228, 1.0
	v_mov_b32_e32 v229, 1.0
	v_mov_b32_e32 v230, 1.0
	v_mov_b32_e32 v231, 1.0
	v_mov_b32_e32 v232, 1.0
	v_mov_b32_e32 v233, 1.0
	v_mov_b32_e32 v234, 1.0
	v_mov_b32_e32 v235, 1.0
	v_mov_b32_e32 v236, 1.0
	v_mov_b32_e32 v237, 1.0
	v_mov_b32_e32 v238, 1.0
	v_mov_b32_e32 v239, 1.0
	s_andn2_b64 vcc, exec, s[18:19]
	s_cbranch_vccnz .Lladder_up_nog
	global_load_dword v208, v4, s[42:43]
	global_load_dword v209, v4, s[42:43] offset:8
	global_load_dword v210, v4, s[42:43] offset:16
	global_load_dword v211, v4, s[42:43] offset:24
	global_load_dword v212, v4, s[42:43] offset:32
	global_load_dword v213, v4, s[42:43] offset:40
	global_load_dword v214, v4, s[42:43] offset:48
	global_load_dword v215, v4, s[42:43] offset:56
	global_load_dword v216, v4, s[42:43] offset:64
	global_load_dword v217, v4, s[42:43] offset:72
	global_load_dword v218, v4, s[42:43] offset:80
	global_load_dword v219, v4, s[42:43] offset:88
	global_load_dword v220, v4, s[42:43] offset:96
	global_load_dword v221, v4, s[42:43] offset:104
	global_load_dword v222, v4, s[42:43] offset:112
	global_load_dword v223, v4, s[42:43] offset:120
	global_load_dword v224, v4, s[42:43] offset:128
	global_load_dword v225, v4, s[42:43] offset:136
	global_load_dword v226, v4, s[42:43] offset:144
	global_load_dword v227, v4, s[42:43] offset:152
	global_load_dword v228, v4, s[42:43] offset:160
	global_load_dword v229, v4, s[42:43] offset:168
	global_load_dword v230, v4, s[42:43] offset:176
	global_load_dword v231, v4, s[42:43] offset:184
	s_waitcnt vmcnt(32)
	global_load_dword v232, v4, s[42:43] offset:192
	global_load_dword v233, v4, s[42:43] offset:200
	global_load_dword v234, v4, s[42:43] offset:208
	global_load_dword v235, v4, s[42:43] offset:216
	global_load_dword v236, v4, s[42:43] offset:224
	global_load_dword v237, v4, s[42:43] offset:232
	global_load_dword v238, v4, s[42:43] offset:240
	global_load_dword v239, v4, s[42:43] offset:248
.Lladder_up_nog:
	v_add_u32_e32 v5, v62, v63
	s_waitcnt vmcnt(0)
	v_mul_f32_e32 v176, v176, v208
	ds_write_b32 v5, v176
	v_mul_f32_e32 v177, v177, v209
	ds_write_b32 v5, v177 offset:264
	v_mul_f32_e32 v178, v178, v210
	ds_write_b32 v5, v178 offset:528
	v_mul_f32_e32 v179, v179, v211
	ds_write_b32 v5, v179 offset:792
	v_mul_f32_e32 v180, v180, v212
	ds_write_b32 v5, v180 offset:1056
	v_mul_f32_e32 v181, v181, v213
	ds_write_b32 v5, v181 offset:1320
	v_mul_f32_e32 v182, v182, v214
	ds_write_b32 v5, v182 offset:1584
	v_mul_f32_e32 v183, v183, v215
	ds_write_b32 v5, v183 offset:1848
	v_mul_f32_e32 v184, v184, v216
	ds_write_b32 v5, v184 offset:2112
	v_mul_f32_e32 v185, v185, v217
	ds_write_b32 v5, v185 offset:2376
	v_mul_f32_e32 v186, v186, v218
	ds_write_b32 v5, v186 offset:2640
	v_mul_f32_e32 v187, v187, v219
	ds_write_b32 v5, v187 offset:2904
	v_mul_f32_e32 v188, v188, v220
	ds_write_b32 v5, v188 offset:3168
	v_mul_f32_e32 v189, v189, v221
	ds_write_b32 v5, v189 offset:3432
	v_mul_f32_e32 v190, v190, v222
	ds_write_b32 v5, v190 offset:3696
	v_mul_f32_e32 v191, v191, v223
	ds_write_b32 v5, v191 offset:3960
	v_mul_f32_e32 v192, v192, v224
	ds_write_b32 v5, v192 offset:4224
	v_mul_f32_e32 v193, v193, v225
	ds_write_b32 v5, v193 offset:4488
	v_mul_f32_e32 v194, v194, v226
	ds_write_b32 v5, v194 offset:4752
	v_mul_f32_e32 v195, v195, v227
	ds_write_b32 v5, v195 offset:5016
	v_mul_f32_e32 v196, v196, v228
	ds_write_b32 v5, v196 offset:5280
	v_mul_f32_e32 v197, v197, v229
	ds_write_b32 v5, v197 offset:5544
	v_mul_f32_e32 v198, v198, v230
	ds_write_b32 v5, v198 offset:5808
	v_mul_f32_e32 v199, v199, v231
	ds_write_b32 v5, v199 offset:6072
	v_mul_f32_e32 v200, v200, v232
	ds_write_b32 v5, v200 offset:6336
	v_mul_f32_e32 v201, v201, v233
	ds_write_b32 v5, v201 offset:6600
	v_mul_f32_e32 v202, v202, v234
	ds_write_b32 v5, v202 offset:6864
	v_mul_f32_e32 v203, v203, v235
	ds_write_b32 v5, v203 offset:7128
	v_mul_f32_e32 v204, v204, v236
	ds_write_b32 v5, v204 offset:7392
	v_mul_f32_e32 v205, v205, v237
	ds_write_b32 v5, v205 offset:7656
	v_mul_f32_e32 v206, v206, v238
	ds_write_b32 v5, v206 offset:7920
	v_mul_f32_e32 v207, v207, v239
	ds_write_b32 v5, v207 offset:8184
	s_waitcnt lgkmcnt(0)
	ds_read2_b32 v[0:1], v120 offset1:33
	s_waitcnt lgkmcnt(0)
	v_cvt_pk_bf16_f32 v0, v0, v1
	ds_read2_b32 v[2:3], v120 offset0:66 offset1:99
	s_lshl_b32 s20, s15, 1
	v_add_u32_e32 v10, s14, v119
	s_waitcnt lgkmcnt(0)
	v_cvt_pk_bf16_f32 v1, v2, v3
	ds_read2_b32 v[2:3], v120 offset0:132 offset1:165
	v_lshl_add_u64 v[6:7], v[24:25], 0, s[20:21]
	v_lshlrev_b64 v[50:51], 11, v[10:11]
	s_waitcnt lgkmcnt(0)
	v_cvt_pk_bf16_f32 v2, v2, v3
	ds_read2_b32 v[4:5], v120 offset0:198 offset1:231
	s_waitcnt lgkmcnt(0)
	v_cvt_pk_bf16_f32 v3, v4, v5
	v_lshl_add_u64 v[50:51], v[6:7], 0, v[50:51]
	ds_read2_b32 v[4:5], v120 offset0:8 offset1:41
	global_store_dwordx4 v[50:51], v[0:3], off
	v_add_u32_e32 v10, s14, v121
	v_lshlrev_b64 v[50:51], 11, v[10:11]
	s_waitcnt lgkmcnt(0)
	v_cvt_pk_bf16_f32 v0, v4, v5
	ds_read2_b32 v[2:3], v120 offset0:74 offset1:107
	s_waitcnt lgkmcnt(0)
	v_cvt_pk_bf16_f32 v1, v2, v3
	ds_read2_b32 v[2:3], v120 offset0:140 offset1:173
	s_waitcnt lgkmcnt(0)
	v_cvt_pk_bf16_f32 v2, v2, v3
	ds_read2_b32 v[4:5], v120 offset0:206 offset1:239
	s_waitcnt lgkmcnt(0)
	v_cvt_pk_bf16_f32 v3, v4, v5
	v_lshl_add_u64 v[50:51], v[6:7], 0, v[50:51]
	ds_read2_b32 v[4:5], v120 offset0:16 offset1:49
	global_store_dwordx4 v[50:51], v[0:3], off
	v_add_u32_e32 v10, s14, v122
	v_lshlrev_b64 v[50:51], 11, v[10:11]
	s_waitcnt lgkmcnt(0)
	v_cvt_pk_bf16_f32 v0, v4, v5
	ds_read2_b32 v[2:3], v120 offset0:82 offset1:115
	s_waitcnt lgkmcnt(0)
	v_cvt_pk_bf16_f32 v1, v2, v3
	ds_read2_b32 v[2:3], v120 offset0:148 offset1:181
	s_waitcnt lgkmcnt(0)
	v_cvt_pk_bf16_f32 v2, v2, v3
	ds_read2_b32 v[4:5], v120 offset0:214 offset1:247
	s_waitcnt lgkmcnt(0)
	v_cvt_pk_bf16_f32 v3, v4, v5
	v_lshl_add_u64 v[50:51], v[6:7], 0, v[50:51]
	ds_read2_b32 v[4:5], v120 offset0:24 offset1:57
	global_store_dwordx4 v[50:51], v[0:3], off
	v_add_u32_e32 v10, s14, v123
	v_lshlrev_b64 v[50:51], 11, v[10:11]
	s_waitcnt lgkmcnt(0)
	v_cvt_pk_bf16_f32 v0, v4, v5
	ds_read2_b32 v[2:3], v120 offset0:90 offset1:123
	s_waitcnt lgkmcnt(0)
	v_cvt_pk_bf16_f32 v1, v2, v3
	ds_read2_b32 v[2:3], v120 offset0:156 offset1:189
	s_waitcnt lgkmcnt(0)
	v_cvt_pk_bf16_f32 v2, v2, v3
	ds_read2_b32 v[4:5], v120 offset0:222 offset1:255
	s_waitcnt lgkmcnt(0)
	v_cvt_pk_bf16_f32 v3, v4, v5
	v_lshl_add_u64 v[4:5], v[6:7], 0, v[50:51]
	global_store_dwordx4 v[4:5], v[0:3], off
	s_waitcnt lgkmcnt(0)

.LBB0_197:
	s_andn2_b64 vcc, exec, s[12:13]
	s_cbranch_vccnz .LBB0_265
	s_add_i32 s12, s40, 0xfffffb80
	s_cmpk_lt_u32 s12, 0x100
	s_cselect_b32 s15, s37, s44
	s_cselect_b32 s14, s36, s1
	s_lshl_b32 s12, s12, 1
	s_and_b32 s25, s12, 0x1ffc0
	s_lshl_b32 s12, s40, 5
	s_and_b32 s24, s12, 0x3e0
	s_lshl_b32 s20, s24, 2
	v_or_b32_e32 v4, s25, v61
	v_lshl_add_u64 v[0:1], v[26:27], 0, s[20:21]
	v_lshlrev_b32_e32 v10, 12, v4
	v_lshl_add_u64 v[2:3], v[0:1], 0, v[10:11]
	s_mov_b32 s16, 0x2000
	s_mov_b32 s17, 0
	v_lshlrev_b32_e32 v4, 2, v4
	global_load_dword v176, v[2:3], off nt
	v_lshl_add_u64 v[2:3], v[2:3], 0, s[16:17]
	global_load_dword v177, v[2:3], off nt
	v_lshl_add_u64 v[2:3], v[2:3], 0, s[16:17]
	global_load_dword v178, v[2:3], off nt
	v_lshl_add_u64 v[2:3], v[2:3], 0, s[16:17]
	global_load_dword v179, v[2:3], off nt
	v_lshl_add_u64 v[2:3], v[2:3], 0, s[16:17]
	global_load_dword v180, v[2:3], off nt
	v_lshl_add_u64 v[2:3], v[2:3], 0, s[16:17]
	global_load_dword v181, v[2:3], off nt
	v_lshl_add_u64 v[2:3], v[2:3], 0, s[16:17]
	global_load_dword v182, v[2:3], off nt
	v_lshl_add_u64 v[2:3], v[2:3], 0, s[16:17]
	global_load_dword v183, v[2:3], off nt
	v_lshl_add_u64 v[2:3], v[2:3], 0, s[16:17]
	global_load_dword v184, v[2:3], off nt
	v_lshl_add_u64 v[2:3], v[2:3], 0, s[16:17]
	global_load_dword v185, v[2:3], off nt
	v_lshl_add_u64 v[2:3], v[2:3], 0, s[16:17]
	global_load_dword v186, v[2:3], off nt
	v_lshl_add_u64 v[2:3], v[2:3], 0, s[16:17]
	global_load_dword v187, v[2:3], off nt
	v_lshl_add_u64 v[2:3], v[2:3], 0, s[16:17]
	global_load_dword v188, v[2:3], off nt
	v_lshl_add_u64 v[2:3], v[2:3], 0, s[16:17]
	global_load_dword v189, v[2:3], off nt
	v_lshl_add_u64 v[2:3], v[2:3], 0, s[16:17]
	global_load_dword v190, v[2:3], off nt
	v_lshl_add_u64 v[2:3], v[2:3], 0, s[16:17]
	global_load_dword v191, v[2:3], off nt
	v_lshl_add_u64 v[2:3], v[2:3], 0, s[16:17]
	global_load_dword v192, v[2:3], off nt
	v_lshl_add_u64 v[2:3], v[2:3], 0, s[16:17]
	global_load_dword v193, v[2:3], off nt
	v_lshl_add_u64 v[2:3], v[2:3], 0, s[16:17]
	global_load_dword v194, v[2:3], off nt
	v_lshl_add_u64 v[2:3], v[2:3], 0, s[16:17]
	global_load_dword v195, v[2:3], off nt
	v_lshl_add_u64 v[2:3], v[2:3], 0, s[16:17]
	global_load_dword v196, v[2:3], off nt
	v_lshl_add_u64 v[2:3], v[2:3], 0, s[16:17]
	global_load_dword v197, v[2:3], off nt
	v_lshl_add_u64 v[2:3], v[2:3], 0, s[16:17]
	global_load_dword v198, v[2:3], off nt
	v_lshl_add_u64 v[2:3], v[2:3], 0, s[16:17]
	global_load_dword v199, v[2:3], off nt
	v_lshl_add_u64 v[2:3], v[2:3], 0, s[16:17]
	global_load_dword v200, v[2:3], off nt
	v_lshl_add_u64 v[2:3], v[2:3], 0, s[16:17]
	global_load_dword v201, v[2:3], off nt
	v_lshl_add_u64 v[2:3], v[2:3], 0, s[16:17]
	global_load_dword v202, v[2:3], off nt
	v_lshl_add_u64 v[2:3], v[2:3], 0, s[16:17]
	global_load_dword v203, v[2:3], off nt
	v_lshl_add_u64 v[2:3], v[2:3], 0, s[16:17]
	global_load_dword v204, v[2:3], off nt
	v_lshl_add_u64 v[2:3], v[2:3], 0, s[16:17]
	global_load_dword v205, v[2:3], off nt
	v_lshl_add_u64 v[2:3], v[2:3], 0, s[16:17]
	global_load_dword v206, v[2:3], off nt
	v_lshl_add_u64 v[2:3], v[2:3], 0, s[16:17]
	global_load_dword v207, v[2:3], off nt
	v_mov_b32_e32 v208, 1.0
	v_mov_b32_e32 v209, 1.0
	v_mov_b32_e32 v210, 1.0
	v_mov_b32_e32 v211, 1.0
	v_mov_b32_e32 v212, 1.0
	v_mov_b32_e32 v213, 1.0
	v_mov_b32_e32 v214, 1.0
	v_mov_b32_e32 v215, 1.0
	v_mov_b32_e32 v216, 1.0
	v_mov_b32_e32 v217, 1.0
	v_mov_b32_e32 v218, 1.0
	v_mov_b32_e32 v219, 1.0
	v_mov_b32_e32 v220, 1.0
	v_mov_b32_e32 v221, 1.0
	v_mov_b32_e32 v222, 1.0
	v_mov_b32_e32 v223, 1.0
	v_mov_b32_e32 v224, 1.0
	v_mov_b32_e32 v225, 1.0
	v_mov_b32_e32 v226, 1.0
	v_mov_b32_e32 v227, 1.0
	v_mov_b32_e32 v228, 1.0
	v_mov_b32_e32 v229, 1.0
	v_mov_b32_e32 v230, 1.0
	v_mov_b32_e32 v231, 1.0
	v_mov_b32_e32 v232, 1.0
	v_mov_b32_e32 v233, 1.0
	v_mov_b32_e32 v234, 1.0
	v_mov_b32_e32 v235, 1.0
	v_mov_b32_e32 v236, 1.0
	v_mov_b32_e32 v237, 1.0
	v_mov_b32_e32 v238, 1.0
	v_mov_b32_e32 v239, 1.0
	s_cmp_eq_u64 s[14:15], 0
	s_cbranch_scc1 .Lladder_out_nog
	global_load_dword v208, v4, s[14:15]
	global_load_dword v209, v4, s[14:15] offset:8
	global_load_dword v210, v4, s[14:15] offset:16
	global_load_dword v211, v4, s[14:15] offset:24
	global_load_dword v212, v4, s[14:15] offset:32
	global_load_dword v213, v4, s[14:15] offset:40
	global_load_dword v214, v4, s[14:15] offset:48
	global_load_dword v215, v4, s[14:15] offset:56
	global_load_dword v216, v4, s[14:15] offset:64
	global_load_dword v217, v4, s[14:15] offset:72
	global_load_dword v218, v4, s[14:15] offset:80
	global_load_dword v219, v4, s[14:15] offset:88
	global_load_dword v220, v4, s[14:15] offset:96
	global_load_dword v221, v4, s[14:15] offset:104
	global_load_dword v222, v4, s[14:15] offset:112
	global_load_dword v223, v4, s[14:15] offset:120
	global_load_dword v224, v4, s[14:15] offset:128
	global_load_dword v225, v4, s[14:15] offset:136
	global_load_dword v226, v4, s[14:15] offset:144
	global_load_dword v227, v4, s[14:15] offset:152
	global_load_dword v228, v4, s[14:15] offset:160
	global_load_dword v229, v4, s[14:15] offset:168
	global_load_dword v230, v4, s[14:15] offset:176
	global_load_dword v231, v4, s[14:15] offset:184
	s_waitcnt vmcnt(32)
	global_load_dword v232, v4, s[14:15] offset:192
	global_load_dword v233, v4, s[14:15] offset:200
	global_load_dword v234, v4, s[14:15] offset:208
	global_load_dword v235, v4, s[14:15] offset:216
	global_load_dword v236, v4, s[14:15] offset:224
	global_load_dword v237, v4, s[14:15] offset:232
	global_load_dword v238, v4, s[14:15] offset:240
	global_load_dword v239, v4, s[14:15] offset:248
.Lladder_out_nog:
	v_add_u32_e32 v5, v62, v63
	s_waitcnt vmcnt(0)
	v_mul_f32_e32 v176, v176, v208
	ds_write_b32 v5, v176
	v_mul_f32_e32 v177, v177, v209
	ds_write_b32 v5, v177 offset:264
	v_mul_f32_e32 v178, v178, v210
	ds_write_b32 v5, v178 offset:528
	v_mul_f32_e32 v179, v179, v211
	ds_write_b32 v5, v179 offset:792
	v_mul_f32_e32 v180, v180, v212
	ds_write_b32 v5, v180 offset:1056
	v_mul_f32_e32 v181, v181, v213
	ds_write_b32 v5, v181 offset:1320
	v_mul_f32_e32 v182, v182, v214
	ds_write_b32 v5, v182 offset:1584
	v_mul_f32_e32 v183, v183, v215
	ds_write_b32 v5, v183 offset:1848
	v_mul_f32_e32 v184, v184, v216
	ds_write_b32 v5, v184 offset:2112
	v_mul_f32_e32 v185, v185, v217
	ds_write_b32 v5, v185 offset:2376
	v_mul_f32_e32 v186, v186, v218
	ds_write_b32 v5, v186 offset:2640
	v_mul_f32_e32 v187, v187, v219
	ds_write_b32 v5, v187 offset:2904
	v_mul_f32_e32 v188, v188, v220
	ds_write_b32 v5, v188 offset:3168
	v_mul_f32_e32 v189, v189, v221
	ds_write_b32 v5, v189 offset:3432
	v_mul_f32_e32 v190, v190, v222
	ds_write_b32 v5, v190 offset:3696
	v_mul_f32_e32 v191, v191, v223
	ds_write_b32 v5, v191 offset:3960
	v_mul_f32_e32 v192, v192, v224
	ds_write_b32 v5, v192 offset:4224
	v_mul_f32_e32 v193, v193, v225
	ds_write_b32 v5, v193 offset:4488
	v_mul_f32_e32 v194, v194, v226
	ds_write_b32 v5, v194 offset:4752
	v_mul_f32_e32 v195, v195, v227
	ds_write_b32 v5, v195 offset:5016
	v_mul_f32_e32 v196, v196, v228
	ds_write_b32 v5, v196 offset:5280
	v_mul_f32_e32 v197, v197, v229
	ds_write_b32 v5, v197 offset:5544
	v_mul_f32_e32 v198, v198, v230
	ds_write_b32 v5, v198 offset:5808
	v_mul_f32_e32 v199, v199, v231
	ds_write_b32 v5, v199 offset:6072
	v_mul_f32_e32 v200, v200, v232
	ds_write_b32 v5, v200 offset:6336
	v_mul_f32_e32 v201, v201, v233
	ds_write_b32 v5, v201 offset:6600
	v_mul_f32_e32 v202, v202, v234
	ds_write_b32 v5, v202 offset:6864
	v_mul_f32_e32 v203, v203, v235
	ds_write_b32 v5, v203 offset:7128
	v_mul_f32_e32 v204, v204, v236
	ds_write_b32 v5, v204 offset:7392
	v_mul_f32_e32 v205, v205, v237
	ds_write_b32 v5, v205 offset:7656
	v_mul_f32_e32 v206, v206, v238
	ds_write_b32 v5, v206 offset:7920
	v_mul_f32_e32 v207, v207, v239
	ds_write_b32 v5, v207 offset:8184
	s_waitcnt lgkmcnt(0)
	ds_read2_b32 v[0:1], v120 offset1:33
	s_waitcnt lgkmcnt(0)
	v_cvt_pk_bf16_f32 v0, v0, v1
	ds_read2_b32 v[2:3], v120 offset0:66 offset1:99
	s_lshl_b32 s20, s25, 1
	v_or_b32_e32 v10, s24, v119
	s_waitcnt lgkmcnt(0)
	v_cvt_pk_bf16_f32 v1, v2, v3
	ds_read2_b32 v[2:3], v120 offset0:132 offset1:165
	v_lshl_add_u64 v[6:7], v[28:29], 0, s[20:21]
	v_lshlrev_b32_e32 v10, 11, v10
	s_waitcnt lgkmcnt(0)
	v_cvt_pk_bf16_f32 v2, v2, v3
	ds_read2_b32 v[4:5], v120 offset0:198 offset1:231
	s_waitcnt lgkmcnt(0)
	v_cvt_pk_bf16_f32 v3, v4, v5
	v_lshl_add_u64 v[50:51], v[6:7], 0, v[10:11]
	ds_read2_b32 v[4:5], v120 offset0:8 offset1:41
	global_store_dwordx4 v[50:51], v[0:3], off
	v_or_b32_e32 v10, s24, v121
	v_lshlrev_b32_e32 v10, 11, v10
	s_waitcnt lgkmcnt(0)
	v_cvt_pk_bf16_f32 v0, v4, v5
	ds_read2_b32 v[2:3], v120 offset0:74 offset1:107
	s_waitcnt lgkmcnt(0)
	v_cvt_pk_bf16_f32 v1, v2, v3
	ds_read2_b32 v[2:3], v120 offset0:140 offset1:173
	s_waitcnt lgkmcnt(0)
	v_cvt_pk_bf16_f32 v2, v2, v3
	ds_read2_b32 v[4:5], v120 offset0:206 offset1:239
	s_waitcnt lgkmcnt(0)
	v_cvt_pk_bf16_f32 v3, v4, v5
	v_lshl_add_u64 v[50:51], v[6:7], 0, v[10:11]
	ds_read2_b32 v[4:5], v120 offset0:16 offset1:49
	global_store_dwordx4 v[50:51], v[0:3], off
	v_or_b32_e32 v10, s24, v122
	v_lshlrev_b32_e32 v10, 11, v10
	s_waitcnt lgkmcnt(0)
	v_cvt_pk_bf16_f32 v0, v4, v5
	ds_read2_b32 v[2:3], v120 offset0:82 offset1:115
	s_waitcnt lgkmcnt(0)
	v_cvt_pk_bf16_f32 v1, v2, v3
	ds_read2_b32 v[2:3], v120 offset0:148 offset1:181
	s_waitcnt lgkmcnt(0)
	v_cvt_pk_bf16_f32 v2, v2, v3
	ds_read2_b32 v[4:5], v120 offset0:214 offset1:247
	s_waitcnt lgkmcnt(0)
	v_cvt_pk_bf16_f32 v3, v4, v5
	v_lshl_add_u64 v[50:51], v[6:7], 0, v[10:11]
	ds_read2_b32 v[4:5], v120 offset0:24 offset1:57
	global_store_dwordx4 v[50:51], v[0:3], off
	s_waitcnt lgkmcnt(0)
	s_nop 0
	v_cvt_pk_bf16_f32 v0, v4, v5
	ds_read2_b32 v[2:3], v120 offset0:90 offset1:123
	s_waitcnt lgkmcnt(0)
	v_cvt_pk_bf16_f32 v1, v2, v3
	ds_read2_b32 v[2:3], v120 offset0:156 offset1:189
	s_waitcnt lgkmcnt(0)
	v_cvt_pk_bf16_f32 v2, v2, v3
	v_or_b32_e32 v3, s24, v123
	ds_read2_b32 v[4:5], v120 offset0:222 offset1:255
	v_lshlrev_b32_e32 v10, 11, v3
	s_waitcnt lgkmcnt(0)
	v_cvt_pk_bf16_f32 v3, v4, v5
	v_lshl_add_u64 v[4:5], v[6:7], 0, v[10:11]
	global_store_dwordx4 v[4:5], v[0:3], off
	s_waitcnt lgkmcnt(0)

.LBB0_266:
	s_andn2_b64 vcc, exec, s[12:13]
	s_cbranch_vccnz .LBB0_268
	s_lshl_b32 s12, s40, 2
	s_and_b32 s13, s12, 0x3c0
	s_lshl_b32 s12, s40, 5
	s_and_b32 s12, s12, 0x1e0
	s_lshl_b32 s20, s12, 2
	v_or_b32_e32 v2, s13, v61
	v_lshl_add_u64 v[0:1], v[30:31], 0, s[20:21]
	v_lshlrev_b32_e32 v10, 11, v2
	v_or_b32_e32 v4, s13, v64
	v_lshl_add_u64 v[2:3], v[0:1], 0, v[10:11]
	v_lshlrev_b32_e32 v10, 11, v4
	v_or_b32_e32 v6, s13, v66
	v_lshl_add_u64 v[4:5], v[0:1], 0, v[10:11]
	v_lshlrev_b32_e32 v10, 11, v6
	v_lshl_add_u64 v[6:7], v[0:1], 0, v[10:11]
	v_or_b32_e32 v10, s13, v68
	v_lshlrev_b32_e32 v10, 11, v10
	v_lshl_add_u64 v[50:51], v[0:1], 0, v[10:11]
	v_or_b32_e32 v10, s13, v70
	v_lshlrev_b32_e32 v10, 11, v10
	v_lshl_add_u64 v[52:53], v[0:1], 0, v[10:11]
	v_or_b32_e32 v10, s13, v72
	v_lshlrev_b32_e32 v10, 11, v10
	v_lshl_add_u64 v[54:55], v[0:1], 0, v[10:11]
	v_or_b32_e32 v10, s13, v74
	v_lshlrev_b32_e32 v10, 11, v10
	v_lshl_add_u64 v[56:57], v[0:1], 0, v[10:11]
	v_or_b32_e32 v10, s13, v76
	v_lshlrev_b32_e32 v10, 11, v10
	v_lshl_add_u64 v[138:139], v[0:1], 0, v[10:11]
	global_load_dword v47, v[2:3], off nt
	global_load_dword v137, v[4:5], off nt
	global_load_dword v140, v[6:7], off nt
	global_load_dword v141, v[50:51], off nt
	global_load_dword v142, v[52:53], off nt
	global_load_dword v143, v[54:55], off nt
	global_load_dword v150, v[56:57], off nt
	global_load_dword v151, v[138:139], off nt
	v_or_b32_e32 v2, s13, v78
	v_lshlrev_b32_e32 v10, 11, v2
	v_or_b32_e32 v4, s13, v80
	v_lshl_add_u64 v[2:3], v[0:1], 0, v[10:11]
	v_lshlrev_b32_e32 v10, 11, v4
	v_or_b32_e32 v6, s13, v82
	v_lshl_add_u64 v[4:5], v[0:1], 0, v[10:11]
	v_lshlrev_b32_e32 v10, 11, v6
	v_lshl_add_u64 v[6:7], v[0:1], 0, v[10:11]
	v_or_b32_e32 v10, s13, v84
	v_lshlrev_b32_e32 v10, 11, v10
	v_lshl_add_u64 v[50:51], v[0:1], 0, v[10:11]
	v_or_b32_e32 v10, s13, v86
	v_lshlrev_b32_e32 v10, 11, v10
	v_lshl_add_u64 v[52:53], v[0:1], 0, v[10:11]
	v_or_b32_e32 v10, s13, v88
	v_lshlrev_b32_e32 v10, 11, v10
	v_lshl_add_u64 v[54:55], v[0:1], 0, v[10:11]
	v_or_b32_e32 v10, s13, v90
	v_lshlrev_b32_e32 v10, 11, v10
	v_lshl_add_u64 v[56:57], v[0:1], 0, v[10:11]
	v_or_b32_e32 v10, s13, v92
	v_lshlrev_b32_e32 v10, 11, v10
	v_lshl_add_u64 v[138:139], v[0:1], 0, v[10:11]
	global_load_dword v152, v[2:3], off nt
	global_load_dword v153, v[4:5], off nt
	global_load_dword v154, v[6:7], off nt
	global_load_dword v155, v[50:51], off nt
	global_load_dword v156, v[52:53], off nt
	global_load_dword v157, v[54:55], off nt
	global_load_dword v158, v[56:57], off nt
	global_load_dword v159, v[138:139], off nt
	v_or_b32_e32 v2, s13, v94
	v_lshlrev_b32_e32 v10, 11, v2
	v_or_b32_e32 v4, s13, v96
	v_lshl_add_u64 v[2:3], v[0:1], 0, v[10:11]
	v_lshlrev_b32_e32 v10, 11, v4
	v_or_b32_e32 v6, s13, v98
	v_lshl_add_u64 v[4:5], v[0:1], 0, v[10:11]
	v_lshlrev_b32_e32 v10, 11, v6
	v_lshl_add_u64 v[6:7], v[0:1], 0, v[10:11]
	v_or_b32_e32 v10, s13, v100
	v_lshlrev_b32_e32 v10, 11, v10
	v_lshl_add_u64 v[50:51], v[0:1], 0, v[10:11]
	v_or_b32_e32 v10, s13, v102
	v_lshlrev_b32_e32 v10, 11, v10
	v_lshl_add_u64 v[52:53], v[0:1], 0, v[10:11]
	v_or_b32_e32 v10, s13, v104
	v_lshlrev_b32_e32 v10, 11, v10
	v_lshl_add_u64 v[54:55], v[0:1], 0, v[10:11]
	v_or_b32_e32 v10, s13, v106
	v_lshlrev_b32_e32 v10, 11, v10
	v_lshl_add_u64 v[56:57], v[0:1], 0, v[10:11]
	v_or_b32_e32 v10, s13, v108
	v_lshlrev_b32_e32 v10, 11, v10
	v_lshl_add_u64 v[138:139], v[0:1], 0, v[10:11]
	global_load_dword v160, v[2:3], off nt
	global_load_dword v161, v[4:5], off nt
	global_load_dword v162, v[6:7], off nt
	global_load_dword v163, v[50:51], off nt
	global_load_dword v164, v[52:53], off nt
	global_load_dword v165, v[54:55], off nt
	global_load_dword v166, v[56:57], off nt
	s_nop 0
	global_load_dword v138, v[138:139], off nt
	v_or_b32_e32 v2, s13, v110
	v_lshlrev_b32_e32 v10, 11, v2
	v_or_b32_e32 v4, s13, v112
	v_lshl_add_u64 v[2:3], v[0:1], 0, v[10:11]
	v_lshlrev_b32_e32 v10, 11, v4
	v_or_b32_e32 v6, s13, v113
	v_lshl_add_u64 v[4:5], v[0:1], 0, v[10:11]
	v_lshlrev_b32_e32 v10, 11, v6
	v_lshl_add_u64 v[6:7], v[0:1], 0, v[10:11]
	v_or_b32_e32 v10, s13, v114
	v_lshlrev_b32_e32 v10, 11, v10
	v_lshl_add_u64 v[50:51], v[0:1], 0, v[10:11]
	v_or_b32_e32 v10, s13, v115
	v_lshlrev_b32_e32 v10, 11, v10
	v_lshl_add_u64 v[52:53], v[0:1], 0, v[10:11]
	v_or_b32_e32 v10, s13, v116
	v_lshlrev_b32_e32 v10, 11, v10
	v_lshl_add_u64 v[54:55], v[0:1], 0, v[10:11]
	v_or_b32_e32 v10, s13, v117
	v_lshlrev_b32_e32 v10, 11, v10
	v_lshl_add_u64 v[56:57], v[0:1], 0, v[10:11]
	v_or_b32_e32 v10, s13, v118
	v_lshlrev_b32_e32 v10, 11, v10
	v_lshl_add_u64 v[0:1], v[0:1], 0, v[10:11]
	global_load_dword v2, v[2:3], off nt
	s_nop 0
	global_load_dword v3, v[4:5], off nt
	s_nop 0
	global_load_dword v4, v[6:7], off nt
	global_load_dword v5, v[50:51], off nt
	s_nop 0
	global_load_dword v6, v[52:53], off nt
	global_load_dword v7, v[54:55], off nt
	global_load_dword v10, v[56:57], off nt
	s_nop 0
	global_load_dword v0, v[0:1], off nt
	v_add_u32_e32 v1, v62, v63
	s_waitcnt vmcnt(30)
	ds_write2_b32 v1, v47, v137 offset1:66
	s_waitcnt vmcnt(28)
	ds_write2_b32 v1, v140, v141 offset0:132 offset1:198
	v_add_u32_e32 v1, 0x400, v1
	s_waitcnt vmcnt(26)
	ds_write2_b32 v1, v142, v143 offset0:8 offset1:74
	v_add_u32_e32 v1, v62, v75
	s_waitcnt vmcnt(24)
	ds_write2_b32 v1, v150, v151 offset1:66
	s_waitcnt vmcnt(22)
	ds_write2_b32 v1, v152, v153 offset0:132 offset1:198
	v_add_u32_e32 v1, 0x400, v1
	s_waitcnt vmcnt(20)
	ds_write2_b32 v1, v154, v155 offset0:8 offset1:74
	v_add_u32_e32 v1, v62, v87
	s_waitcnt vmcnt(18)
	ds_write2_b32 v1, v156, v157 offset1:66
	s_waitcnt vmcnt(16)
	ds_write2_b32 v1, v158, v159 offset0:132 offset1:198
	v_add_u32_e32 v1, 0x400, v1
	s_lshl_b32 s20, s13, 1
	s_waitcnt vmcnt(14)
	ds_write2_b32 v1, v160, v161 offset0:8 offset1:74
	v_add_u32_e32 v1, v62, v99
	s_waitcnt vmcnt(12)
	ds_write2_b32 v1, v162, v163 offset1:66
	s_waitcnt vmcnt(10)
	ds_write2_b32 v1, v164, v165 offset0:132 offset1:198
	v_add_u32_e32 v1, 0x400, v1
	s_waitcnt vmcnt(8)
	ds_write2_b32 v1, v166, v138 offset0:8 offset1:74
	v_add_u32_e32 v1, v62, v111
	s_waitcnt vmcnt(6)
	ds_write2_b32 v1, v2, v3 offset1:66
	s_waitcnt vmcnt(4)
	ds_write2_b32 v1, v4, v5 offset0:132 offset1:198
	v_add_u32_e32 v1, 0x400, v1
	s_waitcnt vmcnt(2)
	ds_write2_b32 v1, v6, v7 offset0:8 offset1:74
	s_waitcnt vmcnt(0)
	ds_write2_b32 v1, v10, v0 offset0:140 offset1:206
	s_waitcnt lgkmcnt(0)
	ds_read2_b32 v[0:1], v120 offset1:33
	s_waitcnt lgkmcnt(0)
	v_cvt_pk_bf16_f32 v0, v0, v1
	ds_read2_b32 v[2:3], v120 offset0:66 offset1:99
	v_or_b32_e32 v10, s12, v119
	s_waitcnt lgkmcnt(0)
	v_cvt_pk_bf16_f32 v1, v2, v3
	ds_read2_b32 v[2:3], v120 offset0:132 offset1:165
	v_lshl_add_u64 v[6:7], v[32:33], 0, s[20:21]
	v_lshlrev_b32_e32 v10, 10, v10
	s_waitcnt lgkmcnt(0)
	v_cvt_pk_bf16_f32 v2, v2, v3
	ds_read2_b32 v[4:5], v120 offset0:198 offset1:231
	s_waitcnt lgkmcnt(0)
	v_cvt_pk_bf16_f32 v3, v4, v5
	v_lshl_add_u64 v[50:51], v[6:7], 0, v[10:11]
	ds_read2_b32 v[4:5], v120 offset0:8 offset1:41
	global_store_dwordx4 v[50:51], v[0:3], off
	v_or_b32_e32 v10, s12, v121
	v_lshlrev_b32_e32 v10, 10, v10
	s_waitcnt lgkmcnt(0)
	v_cvt_pk_bf16_f32 v0, v4, v5
	ds_read2_b32 v[2:3], v120 offset0:74 offset1:107
	s_waitcnt lgkmcnt(0)
	v_cvt_pk_bf16_f32 v1, v2, v3
	ds_read2_b32 v[2:3], v120 offset0:140 offset1:173
	s_waitcnt lgkmcnt(0)
	v_cvt_pk_bf16_f32 v2, v2, v3
	ds_read2_b32 v[4:5], v120 offset0:206 offset1:239
	s_waitcnt lgkmcnt(0)
	v_cvt_pk_bf16_f32 v3, v4, v5
	v_lshl_add_u64 v[50:51], v[6:7], 0, v[10:11]
	ds_read2_b32 v[4:5], v120 offset0:16 offset1:49
	global_store_dwordx4 v[50:51], v[0:3], off
	v_or_b32_e32 v10, s12, v122
	v_lshlrev_b32_e32 v10, 10, v10
	s_waitcnt lgkmcnt(0)
	v_cvt_pk_bf16_f32 v0, v4, v5
	ds_read2_b32 v[2:3], v120 offset0:82 offset1:115
	s_waitcnt lgkmcnt(0)
	v_cvt_pk_bf16_f32 v1, v2, v3
	ds_read2_b32 v[2:3], v120 offset0:148 offset1:181
	s_waitcnt lgkmcnt(0)
	v_cvt_pk_bf16_f32 v2, v2, v3
	ds_read2_b32 v[4:5], v120 offset0:214 offset1:247
	s_waitcnt lgkmcnt(0)
	v_cvt_pk_bf16_f32 v3, v4, v5
	v_lshl_add_u64 v[50:51], v[6:7], 0, v[10:11]
	ds_read2_b32 v[4:5], v120 offset0:24 offset1:57
	global_store_dwordx4 v[50:51], v[0:3], off
	s_waitcnt lgkmcnt(0)
	s_nop 0
	v_cvt_pk_bf16_f32 v0, v4, v5
	ds_read2_b32 v[2:3], v120 offset0:90 offset1:123
	s_waitcnt lgkmcnt(0)
	v_cvt_pk_bf16_f32 v1, v2, v3
	ds_read2_b32 v[2:3], v120 offset0:156 offset1:189
	s_waitcnt lgkmcnt(0)
	v_cvt_pk_bf16_f32 v2, v2, v3
	ds_read2_b32 v[4:5], v120 offset0:222 offset1:255
	s_waitcnt lgkmcnt(0)
	v_cvt_pk_bf16_f32 v3, v4, v5
	v_or_b32_e32 v4, s12, v123
	v_lshlrev_b32_e32 v10, 10, v4
	v_lshl_add_u64 v[4:5], v[6:7], 0, v[10:11]
	global_store_dwordx4 v[4:5], v[0:3], off
	s_waitcnt lgkmcnt(0)

.LBB0_269:
	s_ashr_i32 s12, s40, 31
	s_lshr_b32 s12, s12, 26
	s_add_i32 s12, s40, s12
	s_andn2_b32 s12, s12, 63
	s_sub_i32 s13, s40, s12
	s_lshl_b32 s16, s13, 5
	s_lshl_b32 s17, s13, 7
	s_add_i32 s14, s13, -16
	s_and_b32 s15, s16, 0x700
	s_and_b32 s17, s17, 0x80
	s_lshl_b32 s13, s13, 4
	s_or_b32 s15, s15, s17
	s_and_b32 s13, s13, 0x60
	s_or_b32 s13, s15, s13
	s_cmp_lt_u32 s14, 32
	s_cselect_b32 s14, s13, s16
	s_ashr_i32 s17, s16, 31
	v_lshl_add_u64 v[0:1], s[16:17], 2, v[34:35]
	v_or_b32_e32 v10, s12, v68
	v_mad_i64_i32 v[50:51], s[16:17], v10, s76, v[0:1]
	v_or_b32_e32 v10, s12, v70
	v_mad_i64_i32 v[52:53], s[16:17], v10, s76, v[0:1]
	v_or_b32_e32 v10, s12, v72
	v_or_b32_e32 v2, s12, v61
	v_mad_i64_i32 v[54:55], s[16:17], v10, s76, v[0:1]
	v_or_b32_e32 v10, s12, v74
	v_mad_i64_i32 v[2:3], s[16:17], v2, s76, v[0:1]
	v_or_b32_e32 v4, s12, v64
	v_or_b32_e32 v6, s12, v66
	v_mad_i64_i32 v[56:57], s[16:17], v10, s76, v[0:1]
	v_or_b32_e32 v10, s12, v76
	v_mad_i64_i32 v[4:5], s[16:17], v4, s76, v[0:1]
	v_mad_i64_i32 v[6:7], s[16:17], v6, s76, v[0:1]
	v_mad_i64_i32 v[138:139], s[16:17], v10, s76, v[0:1]
	global_load_dword v10, v[2:3], off nt
	global_load_dword v47, v[4:5], off nt
	global_load_dword v137, v[6:7], off nt
	global_load_dword v140, v[50:51], off nt
	global_load_dword v141, v[52:53], off nt
	global_load_dword v142, v[54:55], off nt
	global_load_dword v143, v[56:57], off nt
	global_load_dword v150, v[138:139], off nt
	v_or_b32_e32 v2, s12, v78
	v_mad_i64_i32 v[2:3], s[16:17], v2, s76, v[0:1]
	v_or_b32_e32 v4, s12, v80
	v_or_b32_e32 v6, s12, v82
	v_or_b32_e32 v50, s12, v84
	v_or_b32_e32 v52, s12, v86
	v_or_b32_e32 v54, s12, v88
	v_or_b32_e32 v56, s12, v90
	v_or_b32_e32 v138, s12, v92
	v_mad_i64_i32 v[4:5], s[16:17], v4, s76, v[0:1]
	v_mad_i64_i32 v[6:7], s[16:17], v6, s76, v[0:1]
	v_mad_i64_i32 v[50:51], s[16:17], v50, s76, v[0:1]
	v_mad_i64_i32 v[52:53], s[16:17], v52, s76, v[0:1]
	v_mad_i64_i32 v[54:55], s[16:17], v54, s76, v[0:1]
	v_mad_i64_i32 v[56:57], s[16:17], v56, s76, v[0:1]
	v_mad_i64_i32 v[138:139], s[16:17], v138, s76, v[0:1]
	global_load_dword v151, v[2:3], off nt
	global_load_dword v152, v[4:5], off nt
	global_load_dword v153, v[6:7], off nt
	global_load_dword v154, v[50:51], off nt
	global_load_dword v155, v[52:53], off nt
	global_load_dword v156, v[54:55], off nt
	global_load_dword v157, v[56:57], off nt
	global_load_dword v158, v[138:139], off nt
	v_or_b32_e32 v2, s12, v94
	v_or_b32_e32 v4, s12, v96
	v_or_b32_e32 v6, s12, v98
	v_or_b32_e32 v50, s12, v100
	v_or_b32_e32 v52, s12, v102
	v_or_b32_e32 v54, s12, v104
	v_or_b32_e32 v56, s12, v106
	v_or_b32_e32 v138, s12, v108
	v_mad_i64_i32 v[2:3], s[16:17], v2, s76, v[0:1]
	v_mad_i64_i32 v[4:5], s[16:17], v4, s76, v[0:1]
	v_mad_i64_i32 v[6:7], s[16:17], v6, s76, v[0:1]
	v_mad_i64_i32 v[50:51], s[16:17], v50, s76, v[0:1]
	v_mad_i64_i32 v[52:53], s[16:17], v52, s76, v[0:1]
	v_mad_i64_i32 v[54:55], s[16:17], v54, s76, v[0:1]
	v_mad_i64_i32 v[56:57], s[16:17], v56, s76, v[0:1]
	v_mad_i64_i32 v[138:139], s[16:17], v138, s76, v[0:1]
	global_load_dword v159, v[2:3], off nt
	global_load_dword v160, v[4:5], off nt
	global_load_dword v161, v[6:7], off nt
	global_load_dword v162, v[50:51], off nt
	global_load_dword v163, v[52:53], off nt
	global_load_dword v164, v[54:55], off nt
	global_load_dword v165, v[56:57], off nt
	s_nop 0
	global_load_dword v138, v[138:139], off nt
	v_or_b32_e32 v2, s12, v110
	v_or_b32_e32 v4, s12, v112
	v_or_b32_e32 v6, s12, v113
	v_or_b32_e32 v50, s12, v114
	v_or_b32_e32 v52, s12, v115
	v_or_b32_e32 v54, s12, v116
	v_or_b32_e32 v56, s12, v117
	v_or_b32_e32 v139, s12, v118
	v_mad_i64_i32 v[2:3], s[16:17], v2, s76, v[0:1]
	v_mad_i64_i32 v[4:5], s[16:17], v4, s76, v[0:1]
	v_mad_i64_i32 v[6:7], s[16:17], v6, s76, v[0:1]
	v_mad_i64_i32 v[50:51], s[16:17], v50, s76, v[0:1]
	v_mad_i64_i32 v[52:53], s[16:17], v52, s76, v[0:1]
	v_mad_i64_i32 v[54:55], s[16:17], v54, s76, v[0:1]
	v_mad_i64_i32 v[56:57], s[16:17], v56, s76, v[0:1]
	v_mad_i64_i32 v[0:1], s[16:17], v139, s76, v[0:1]
	global_load_dword v2, v[2:3], off nt
	s_nop 0
	global_load_dword v3, v[4:5], off nt
	s_nop 0
	global_load_dword v4, v[6:7], off nt
	global_load_dword v5, v[50:51], off nt
	s_nop 0
	global_load_dword v6, v[52:53], off nt
	global_load_dword v7, v[54:55], off nt
	global_load_dword v50, v[56:57], off nt
	s_nop 0
	global_load_dword v0, v[0:1], off nt
	v_add_u32_e32 v1, v62, v63
	s_waitcnt vmcnt(30)
	ds_write2_b32 v1, v10, v47 offset1:66
	s_waitcnt vmcnt(28)
	ds_write2_b32 v1, v137, v140 offset0:132 offset1:198
	v_add_u32_e32 v1, 0x400, v1
	s_waitcnt vmcnt(26)
	ds_write2_b32 v1, v141, v142 offset0:8 offset1:74
	v_add_u32_e32 v1, v62, v75
	s_waitcnt vmcnt(24)
	ds_write2_b32 v1, v143, v150 offset1:66
	s_waitcnt vmcnt(22)
	ds_write2_b32 v1, v151, v152 offset0:132 offset1:198
	v_add_u32_e32 v1, 0x400, v1
	s_waitcnt vmcnt(20)
	ds_write2_b32 v1, v153, v154 offset0:8 offset1:74
	v_add_u32_e32 v1, v62, v87
	s_waitcnt vmcnt(18)
	ds_write2_b32 v1, v155, v156 offset1:66
	s_waitcnt vmcnt(16)
	ds_write2_b32 v1, v157, v158 offset0:132 offset1:198
	v_add_u32_e32 v1, 0x400, v1
	s_ashr_i32 s13, s12, 31
	s_waitcnt vmcnt(14)
	ds_write2_b32 v1, v159, v160 offset0:8 offset1:74
	v_add_u32_e32 v1, v62, v99
	s_waitcnt vmcnt(12)
	ds_write2_b32 v1, v161, v162 offset1:66
	s_waitcnt vmcnt(10)
	ds_write2_b32 v1, v163, v164 offset0:132 offset1:198
	v_add_u32_e32 v1, 0x400, v1
	s_waitcnt vmcnt(8)
	ds_write2_b32 v1, v165, v138 offset0:8 offset1:74
	v_add_u32_e32 v1, v62, v111
	s_waitcnt vmcnt(6)
	ds_write2_b32 v1, v2, v3 offset1:66
	s_waitcnt vmcnt(4)
	ds_write2_b32 v1, v4, v5 offset0:132 offset1:198
	v_add_u32_e32 v1, 0x400, v1
	s_waitcnt vmcnt(2)
	ds_write2_b32 v1, v6, v7 offset0:8 offset1:74
	s_waitcnt vmcnt(0)
	ds_write2_b32 v1, v50, v0 offset0:140 offset1:206
	s_waitcnt lgkmcnt(0)
	ds_read2_b32 v[0:1], v120 offset1:33
	s_waitcnt lgkmcnt(0)
	v_cvt_pk_bf16_f32 v0, v0, v1
	ds_read2_b32 v[2:3], v120 offset0:66 offset1:99
	s_waitcnt lgkmcnt(0)
	v_cvt_pk_bf16_f32 v1, v2, v3
	ds_read2_b32 v[2:3], v120 offset0:132 offset1:165
	s_waitcnt lgkmcnt(0)
	v_cvt_pk_bf16_f32 v2, v2, v3
	ds_read2_b32 v[4:5], v120 offset0:198 offset1:231
	s_waitcnt lgkmcnt(0)
	v_cvt_pk_bf16_f32 v3, v4, v5
	v_or_b32_e32 v4, s14, v119
	v_ashrrev_i32_e32 v5, 31, v4
	v_lshl_add_u64 v[6:7], s[12:13], 1, v[36:37]
	v_lshlrev_b64 v[4:5], 11, v[4:5]
	v_lshl_add_u64 v[4:5], v[6:7], 0, v[4:5]
	ds_read2_b32 v[50:51], v120 offset0:8 offset1:41
	global_store_dwordx4 v[4:5], v[0:3], off
	s_waitcnt lgkmcnt(0)
	s_nop 0
	v_cvt_pk_bf16_f32 v0, v50, v51
	ds_read2_b32 v[2:3], v120 offset0:74 offset1:107
	s_waitcnt lgkmcnt(0)
	v_cvt_pk_bf16_f32 v1, v2, v3
	ds_read2_b32 v[2:3], v120 offset0:140 offset1:173
	s_waitcnt lgkmcnt(0)
	v_cvt_pk_bf16_f32 v2, v2, v3
	ds_read2_b32 v[4:5], v120 offset0:206 offset1:239
	s_waitcnt lgkmcnt(0)
	v_cvt_pk_bf16_f32 v3, v4, v5
	v_or_b32_e32 v4, s14, v121
	v_ashrrev_i32_e32 v5, 31, v4
	v_lshlrev_b64 v[4:5], 11, v[4:5]
	v_lshl_add_u64 v[4:5], v[6:7], 0, v[4:5]
	ds_read2_b32 v[50:51], v120 offset0:16 offset1:49
	global_store_dwordx4 v[4:5], v[0:3], off
	s_waitcnt lgkmcnt(0)
	s_nop 0
	v_cvt_pk_bf16_f32 v0, v50, v51
	ds_read2_b32 v[2:3], v120 offset0:82 offset1:115
	s_waitcnt lgkmcnt(0)
	v_cvt_pk_bf16_f32 v1, v2, v3
	ds_read2_b32 v[2:3], v120 offset0:148 offset1:181
	s_waitcnt lgkmcnt(0)
	v_cvt_pk_bf16_f32 v2, v2, v3
	ds_read2_b32 v[4:5], v120 offset0:214 offset1:247
	s_waitcnt lgkmcnt(0)
	v_cvt_pk_bf16_f32 v3, v4, v5
	v_or_b32_e32 v4, s14, v122
	v_ashrrev_i32_e32 v5, 31, v4
	v_lshlrev_b64 v[4:5], 11, v[4:5]
	v_lshl_add_u64 v[4:5], v[6:7], 0, v[4:5]
	ds_read2_b32 v[50:51], v120 offset0:24 offset1:57
	global_store_dwordx4 v[4:5], v[0:3], off
	s_waitcnt lgkmcnt(0)
	s_nop 0
	v_cvt_pk_bf16_f32 v0, v50, v51
	ds_read2_b32 v[2:3], v120 offset0:90 offset1:123
	s_waitcnt lgkmcnt(0)
	v_cvt_pk_bf16_f32 v1, v2, v3
	ds_read2_b32 v[2:3], v120 offset0:156 offset1:189
	s_waitcnt lgkmcnt(0)
	v_cvt_pk_bf16_f32 v2, v2, v3
	ds_read2_b32 v[4:5], v120 offset0:222 offset1:255
	s_waitcnt lgkmcnt(0)
	v_cvt_pk_bf16_f32 v3, v4, v5
	v_or_b32_e32 v4, s14, v123
	v_ashrrev_i32_e32 v5, 31, v4
	v_lshlrev_b64 v[4:5], 11, v[4:5]
	v_lshl_add_u64 v[4:5], v[6:7], 0, v[4:5]
	global_store_dwordx4 v[4:5], v[0:3], off
	s_waitcnt lgkmcnt(0)
	s_branch .LBB0_22

.LBB0_286:
	s_or_b64 exec, exec, s[4:5]
	s_cmp_lt_i32 s0, 0x8000
	s_waitcnt lgkmcnt(0)
	s_barrier
	s_cbranch_scc0 .LBB0_295
	v_mbcnt_lo_u32_b32 v1, -1, 0
	v_mbcnt_hi_u32_b32 v1, -1, v1
	v_readlane_b32 s10, v255, 2
	v_readlane_b32 s11, v255, 3
	v_readlane_b32 s8, v255, 4
	v_readlane_b32 s9, v255, 5
	v_readlane_b32 s4, v255, 8
	v_readlane_b32 s5, v255, 9
	v_lshlrev_b32_e32 v2, 3, v1
	v_bfe_u32 v6, v1, 5, 1
	v_bfe_u32 v7, v1, 2, 1
	v_bfe_u32 v8, v1, 3, 1
	v_lshlrev_b32_e32 v6, 2, v6
	v_lshl_or_b32 v6, v7, 1, v6
	v_or_b32_e32 v6, v6, v8
	v_lshlrev_b32_e32 v4, 2, v6
	v_lshlrev_b32_e32 v1, 4, v1
	v_mov_b32_e32 v0, 0
	v_mov_b32_e32 v153, 0x358637bd
	s_lshl_b32 s53, s96, 11
	s_lshl_b32 s54, s96, 2
	s_lshl_b32 s55, s96, 5
	s_lshl_b32 s59, s96, 1
	s_movk_i32 s61, 0x7fff
	s_mov_b32 s57, 0x3fb8aa3b
	s_mov_b32 s62, 0x00001111
	s_mov_b32 s63, 0x00001111
	s_mov_b32 s64, 0xff00ff00
	s_mov_b32 s65, 0xff00ff00
	s_mov_b32 s66, 0xf0f0f0f0
	s_mov_b32 s67, 0xf0f0f0f0
	global_load_dwordx4 v[64:67], v1, s[8:9]
	global_load_dwordx4 v[68:71], v1, s[8:9] offset:1024
	global_load_dwordx4 v[72:75], v1, s[8:9] offset:2048
	global_load_dwordx4 v[76:79], v1, s[8:9] offset:3072
	global_load_dword v156, v4, s[4:5]
	s_lshl_b32 s1, s0, 11
	s_add_u32 s12, s30, s1
	s_addc_u32 s13, s31, 0
	s_add_u32 s12, s12, 0x2400000
	s_addc_u32 s13, s13, 0
	s_lshl_b32 s1, s0, 2
	s_add_u32 s14, s30, s1
	s_addc_u32 s15, s31, 0
	s_add_u32 s14, s14, 0x4d0000
	s_addc_u32 s15, s15, 0
	s_lshl_b32 s1, s0, 5
	s_add_u32 s26, s30, s1
	s_addc_u32 s27, s31, 0
	s_add_u32 s26, s26, 0x2200000
	s_addc_u32 s27, s27, 0
	s_lshl_b32 s4, s0, 12
	s_add_u32 s4, s10, s4
	s_addc_u32 s5, s11, 0
	global_load_dwordx4 v[16:19], v1, s[4:5] nt
	global_load_dwordx4 v[20:23], v1, s[4:5] offset:1024 nt
	global_load_dwordx4 v[24:27], v1, s[4:5] offset:2048 nt
	global_load_dwordx4 v[28:31], v1, s[4:5] offset:3072 nt
	s_add_i32 s1, s0, s96
	s_min_i32 s1, s1, s61
	s_lshl_b32 s4, s1, 12
	s_add_u32 s4, s10, s4
	s_addc_u32 s5, s11, 0
	global_load_dwordx4 v[32:35], v1, s[4:5] nt
	global_load_dwordx4 v[36:39], v1, s[4:5] offset:1024 nt
	global_load_dwordx4 v[40:43], v1, s[4:5] offset:2048 nt
	global_load_dwordx4 v[44:47], v1, s[4:5] offset:3072 nt
	ds_read_b128 v[80:83], v1
	ds_read_b128 v[84:87], v1 offset:1024
	ds_read_b128 v[88:91], v1 offset:2048
	ds_read_b128 v[92:95], v1 offset:3072
	ds_read_b128 v[96:99], v1 offset:4096
	ds_read_b128 v[100:103], v1 offset:5120
	ds_read_b128 v[104:107], v1 offset:6144
	ds_read_b128 v[108:111], v1 offset:7168
	ds_read_b128 v[112:115], v1 offset:8192
	ds_read_b128 v[116:119], v1 offset:9216
	ds_read_b128 v[120:123], v1 offset:10240
	ds_read_b128 v[124:127], v1 offset:11264
	ds_read_b128 v[128:131], v1 offset:12288
	ds_read_b128 v[132:135], v1 offset:13312
	ds_read_b128 v[136:139], v1 offset:14336
	ds_read_b128 v[140:143], v1 offset:15360
	ds_read_b128 v[176:179], v1 offset:16384
	ds_read_b128 v[180:183], v1 offset:17408
	ds_read_b128 v[184:187], v1 offset:18432
	ds_read_b128 v[188:191], v1 offset:19456
	ds_read_b128 v[192:195], v1 offset:20480
	ds_read_b128 v[196:199], v1 offset:21504
	ds_read_b128 v[200:203], v1 offset:22528
	ds_read_b128 v[204:207], v1 offset:23552
	ds_read_b128 v[208:211], v1 offset:24576
	ds_read_b128 v[212:215], v1 offset:25600
	ds_read_b128 v[216:219], v1 offset:26624
	ds_read_b128 v[220:223], v1 offset:27648
	ds_read_b128 v[224:227], v1 offset:28672
	ds_read_b128 v[228:231], v1 offset:29696
	ds_read_b128 v[232:235], v1 offset:30720
	ds_read_b128 v[236:239], v1 offset:31744
	s_waitcnt vmcnt(0) lgkmcnt(0)
.Lrow_loop:
	s_add_i32 s1, s0, s59
	s_min_i32 s1, s1, s61
	s_lshl_b32 s4, s1, 12
	s_add_u32 s4, s10, s4
	s_addc_u32 s5, s11, 0
	global_load_dwordx4 v[48:51], v1, s[4:5] nt
	global_load_dwordx4 v[52:55], v1, s[4:5] offset:1024 nt
	global_load_dwordx4 v[56:59], v1, s[4:5] offset:2048 nt
	global_load_dwordx4 v[60:63], v1, s[4:5] offset:3072 nt
	s_waitcnt vmcnt(20)
	v_pk_mul_f32 v[150:151], v[16:17], v[16:17]
	v_pk_fma_f32 v[150:151], v[18:19], v[18:19], v[150:151]
	v_pk_fma_f32 v[150:151], v[20:21], v[20:21], v[150:151]
	v_pk_fma_f32 v[150:151], v[22:23], v[22:23], v[150:151]
	v_pk_fma_f32 v[150:151], v[24:25], v[24:25], v[150:151]
	v_pk_fma_f32 v[150:151], v[26:27], v[26:27], v[150:151]
	v_pk_fma_f32 v[150:151], v[28:29], v[28:29], v[150:151]
	v_pk_fma_f32 v[150:151], v[30:31], v[30:31], v[150:151]
	v_add_f32_e32 v150, v150, v151
	s_nop 1
	v_add_f32_dpp v150, v150, v150 quad_perm:[1,0,3,2] row_mask:0xf bank_mask:0xf bound_ctrl:1
	s_nop 1
	v_add_f32_dpp v150, v150, v150 quad_perm:[2,3,0,1] row_mask:0xf bank_mask:0xf bound_ctrl:1
	s_nop 1
	v_add_f32_dpp v150, v150, v150 row_half_mirror row_mask:0xf bank_mask:0xf bound_ctrl:1
	s_nop 1
	v_add_f32_dpp v150, v150, v150 row_mirror row_mask:0xf bank_mask:0xf bound_ctrl:1
	s_nop 1
	v_readlane_b32 s7, v150, 0
	v_readlane_b32 s8, v150, 16
	v_readlane_b32 s9, v150, 32
	v_readlane_b32 s18, v150, 48
	s_nop 1
	v_mov_b32_e32 v150, s7
	v_add_f32_e32 v150, s8, v150
	v_add_f32_e32 v150, s9, v150
	v_add_f32_e32 v150, s18, v150
	v_fmamk_f32 v150, v150, 0x3a800000, v153
	v_sqrt_f32_e32 v152, v150
	s_nop 0
	v_rcp_f32_e32 v154, v152
	s_mov_b64 exec, 1
	global_store_dword v0, v152, s[14:15]
	s_mov_b64 exec, -1
	v_pk_mul_f32 v[16:17], v[16:17], v[154:155] op_sel_hi:[1,0]
	v_pk_mul_f32 v[18:19], v[18:19], v[154:155] op_sel_hi:[1,0]
	v_pk_mul_f32 v[20:21], v[20:21], v[154:155] op_sel_hi:[1,0]
	v_pk_mul_f32 v[22:23], v[22:23], v[154:155] op_sel_hi:[1,0]
	v_pk_mul_f32 v[24:25], v[24:25], v[154:155] op_sel_hi:[1,0]
	v_pk_mul_f32 v[26:27], v[26:27], v[154:155] op_sel_hi:[1,0]
	v_pk_mul_f32 v[28:29], v[28:29], v[154:155] op_sel_hi:[1,0]
	v_pk_mul_f32 v[30:31], v[30:31], v[154:155] op_sel_hi:[1,0]
	v_pk_mul_f32 v[16:17], v[16:17], v[64:65]
	v_pk_mul_f32 v[18:19], v[18:19], v[66:67]
	v_pk_mul_f32 v[20:21], v[20:21], v[68:69]
	v_pk_mul_f32 v[22:23], v[22:23], v[70:71]
	v_pk_mul_f32 v[24:25], v[24:25], v[72:73]
	v_pk_mul_f32 v[26:27], v[26:27], v[74:75]
	v_pk_mul_f32 v[28:29], v[28:29], v[76:77]
	v_pk_mul_f32 v[30:31], v[30:31], v[78:79]
	v_cvt_pk_bf16_f32 v240, v16, v17
	v_cvt_pk_bf16_f32 v241, v18, v19
	v_cvt_pk_bf16_f32 v242, v20, v21
	v_cvt_pk_bf16_f32 v243, v22, v23
	v_cvt_pk_bf16_f32 v244, v24, v25
	v_cvt_pk_bf16_f32 v245, v26, v27
	v_cvt_pk_bf16_f32 v246, v28, v29
	v_cvt_pk_bf16_f32 v247, v30, v31
	global_store_dwordx2 v2, v[240:241], s[12:13]
	global_store_dwordx2 v2, v[242:243], s[12:13] offset:512
	global_store_dwordx2 v2, v[244:245], s[12:13] offset:1024
	global_store_dwordx2 v2, v[246:247], s[12:13] offset:1536
	v_pk_mul_f32 v[6:7], v[16:17], v[80:81]
	v_pk_mul_f32 v[8:9], v[16:17], v[96:97]
	v_pk_mul_f32 v[10:11], v[16:17], v[112:113]
	v_pk_mul_f32 v[12:13], v[16:17], v[128:129]
	v_pk_mul_f32 v[14:15], v[16:17], v[176:177]
	v_pk_mul_f32 v[144:145], v[16:17], v[192:193]
	v_pk_mul_f32 v[146:147], v[16:17], v[208:209]
	v_pk_mul_f32 v[148:149], v[16:17], v[224:225]
	v_pk_fma_f32 v[6:7], v[18:19], v[82:83], v[6:7]
	v_pk_fma_f32 v[8:9], v[18:19], v[98:99], v[8:9]
	v_pk_fma_f32 v[10:11], v[18:19], v[114:115], v[10:11]
	v_pk_fma_f32 v[12:13], v[18:19], v[130:131], v[12:13]
	v_pk_fma_f32 v[14:15], v[18:19], v[178:179], v[14:15]
	v_pk_fma_f32 v[144:145], v[18:19], v[194:195], v[144:145]
	v_pk_fma_f32 v[146:147], v[18:19], v[210:211], v[146:147]
	v_pk_fma_f32 v[148:149], v[18:19], v[226:227], v[148:149]
	v_pk_fma_f32 v[6:7], v[20:21], v[84:85], v[6:7]
	v_pk_fma_f32 v[8:9], v[20:21], v[100:101], v[8:9]
	v_pk_fma_f32 v[10:11], v[20:21], v[116:117], v[10:11]
	v_pk_fma_f32 v[12:13], v[20:21], v[132:133], v[12:13]
	v_pk_fma_f32 v[14:15], v[20:21], v[180:181], v[14:15]
	v_pk_fma_f32 v[144:145], v[20:21], v[196:197], v[144:145]
	v_pk_fma_f32 v[146:147], v[20:21], v[212:213], v[146:147]
	v_pk_fma_f32 v[148:149], v[20:21], v[228:229], v[148:149]
	v_pk_fma_f32 v[6:7], v[22:23], v[86:87], v[6:7]
	v_pk_fma_f32 v[8:9], v[22:23], v[102:103], v[8:9]
	v_pk_fma_f32 v[10:11], v[22:23], v[118:119], v[10:11]
	v_pk_fma_f32 v[12:13], v[22:23], v[134:135], v[12:13]
	v_pk_fma_f32 v[14:15], v[22:23], v[182:183], v[14:15]
	v_pk_fma_f32 v[144:145], v[22:23], v[198:199], v[144:145]
	v_pk_fma_f32 v[146:147], v[22:23], v[214:215], v[146:147]
	v_pk_fma_f32 v[148:149], v[22:23], v[230:231], v[148:149]
	v_pk_fma_f32 v[6:7], v[24:25], v[88:89], v[6:7]
	v_pk_fma_f32 v[8:9], v[24:25], v[104:105], v[8:9]
	v_pk_fma_f32 v[10:11], v[24:25], v[120:121], v[10:11]
	v_pk_fma_f32 v[12:13], v[24:25], v[136:137], v[12:13]
	v_pk_fma_f32 v[14:15], v[24:25], v[184:185], v[14:15]
	v_pk_fma_f32 v[144:145], v[24:25], v[200:201], v[144:145]
	v_pk_fma_f32 v[146:147], v[24:25], v[216:217], v[146:147]
	v_pk_fma_f32 v[148:149], v[24:25], v[232:233], v[148:149]
	v_pk_fma_f32 v[6:7], v[26:27], v[90:91], v[6:7]
	v_pk_fma_f32 v[8:9], v[26:27], v[106:107], v[8:9]
	v_pk_fma_f32 v[10:11], v[26:27], v[122:123], v[10:11]
	v_pk_fma_f32 v[12:13], v[26:27], v[138:139], v[12:13]
	v_pk_fma_f32 v[14:15], v[26:27], v[186:187], v[14:15]
	v_pk_fma_f32 v[144:145], v[26:27], v[202:203], v[144:145]
	v_pk_fma_f32 v[146:147], v[26:27], v[218:219], v[146:147]
	v_pk_fma_f32 v[148:149], v[26:27], v[234:235], v[148:149]
	v_pk_fma_f32 v[6:7], v[28:29], v[92:93], v[6:7]
	v_pk_fma_f32 v[8:9], v[28:29], v[108:109], v[8:9]
	v_pk_fma_f32 v[10:11], v[28:29], v[124:125], v[10:11]
	v_pk_fma_f32 v[12:13], v[28:29], v[140:141], v[12:13]
	v_pk_fma_f32 v[14:15], v[28:29], v[188:189], v[14:15]
	v_pk_fma_f32 v[144:145], v[28:29], v[204:205], v[144:145]
	v_pk_fma_f32 v[146:147], v[28:29], v[220:221], v[146:147]
	v_pk_fma_f32 v[148:149], v[28:29], v[236:237], v[148:149]
	v_pk_fma_f32 v[6:7], v[30:31], v[94:95], v[6:7]
	v_pk_fma_f32 v[8:9], v[30:31], v[110:111], v[8:9]
	v_pk_fma_f32 v[10:11], v[30:31], v[126:127], v[10:11]
	v_pk_fma_f32 v[12:13], v[30:31], v[142:143], v[12:13]
	v_pk_fma_f32 v[14:15], v[30:31], v[190:191], v[14:15]
	v_pk_fma_f32 v[144:145], v[30:31], v[206:207], v[144:145]
	v_pk_fma_f32 v[146:147], v[30:31], v[222:223], v[146:147]
	v_pk_fma_f32 v[148:149], v[30:31], v[238:239], v[148:149]
	v_add_f32_e32 v6, v6, v7
	v_add_f32_e32 v8, v8, v9
	v_add_f32_e32 v10, v10, v11
	v_add_f32_e32 v12, v12, v13
	v_add_f32_e32 v14, v14, v15
	v_add_f32_e32 v144, v144, v145
	v_add_f32_e32 v146, v146, v147
	v_add_f32_e32 v148, v148, v149
	s_nop 1
	v_permlane32_swap_b32_e32 v6, v14
	v_permlane32_swap_b32_e32 v8, v144
	v_permlane32_swap_b32_e32 v10, v146
	v_permlane32_swap_b32_e32 v12, v148
	v_add_f32_e32 v6, v6, v14
	v_add_f32_e32 v8, v8, v144
	v_add_f32_e32 v10, v10, v146
	v_add_f32_e32 v12, v12, v148
	s_nop 1
	v_add_f32_dpp v14, v6, v6 row_ror:8 row_mask:0xf bank_mask:0xf bound_ctrl:1
	v_add_f32_dpp v144, v8, v8 row_ror:8 row_mask:0xf bank_mask:0xf bound_ctrl:1
	v_add_f32_dpp v146, v10, v10 row_ror:8 row_mask:0xf bank_mask:0xf bound_ctrl:1
	v_add_f32_dpp v148, v12, v12 row_ror:8 row_mask:0xf bank_mask:0xf bound_ctrl:1
	v_cndmask_b32_e64 v6, v14, v144, s[64:65]
	v_cndmask_b32_e64 v8, v146, v148, s[64:65]
	s_nop 1
	v_add_f32_dpp v10, v6, v6 row_half_mirror row_mask:0xf bank_mask:0xf bound_ctrl:1
	v_add_f32_dpp v12, v8, v8 row_half_mirror row_mask:0xf bank_mask:0xf bound_ctrl:1
	v_cndmask_b32_e64 v6, v10, v12, s[66:67]
	s_nop 1
	v_add_f32_dpp v6, v6, v6 quad_perm:[1,0,3,2] row_mask:0xf bank_mask:0xf bound_ctrl:1
	s_nop 1
	v_add_f32_dpp v6, v6, v6 quad_perm:[2,3,0,1] row_mask:0xf bank_mask:0xf bound_ctrl:1
	s_nop 0
	ds_swizzle_b32 v254, v6 offset:0x401f
	s_waitcnt lgkmcnt(0)
	v_add_f32_e32 v248, v6, v254
	v_add_f32_e32 v248, v248, v156
	v_mul_f32_e64 v249, -|v248|, s57
	v_exp_f32_e32 v249, v249
	v_min_f32_e32 v253, 0, v248
	v_add_f32_e32 v250, 1.0, v249
	v_log_f32_e32 v251, v250
	v_add_f32_e32 v252, -1.0, v250
	v_rcp_f32_e32 v250, v252
	v_cmp_eq_f32_e32 vcc, 0, v252
	v_mul_f32_e32 v251, 0x3f317218, v251
	v_mul_f32_e32 v251, v251, v249
	v_mul_f32_e32 v251, v251, v250
	v_cndmask_b32_e32 v251, v251, v249, vcc
	v_sub_f32_e32 v253, v253, v251
	s_mov_b64 exec, s[62:63]
	global_store_dword v4, v253, s[26:27]
	s_mov_b64 exec, -1
	s_add_u32 s12, s12, s53
	s_addc_u32 s13, s13, 0
	s_add_u32 s14, s14, s54
	s_addc_u32 s15, s15, 0
	s_add_u32 s26, s26, s55
	s_addc_u32 s27, s27, 0
	s_add_i32 s0, s0, s96
	s_cmp_lt_i32 s0, 0x8000
	s_cbranch_scc0 .Lrow_done
	s_add_i32 s1, s0, s59
	s_min_i32 s1, s1, s61
	s_lshl_b32 s4, s1, 12
	s_add_u32 s4, s10, s4
	s_addc_u32 s5, s11, 0
	global_load_dwordx4 v[16:19], v1, s[4:5] nt
	global_load_dwordx4 v[20:23], v1, s[4:5] offset:1024 nt
	global_load_dwordx4 v[24:27], v1, s[4:5] offset:2048 nt
	global_load_dwordx4 v[28:31], v1, s[4:5] offset:3072 nt
	s_waitcnt vmcnt(20)
	v_pk_mul_f32 v[150:151], v[32:33], v[32:33]
	v_pk_fma_f32 v[150:151], v[34:35], v[34:35], v[150:151]
	v_pk_fma_f32 v[150:151], v[36:37], v[36:37], v[150:151]
	v_pk_fma_f32 v[150:151], v[38:39], v[38:39], v[150:151]
	v_pk_fma_f32 v[150:151], v[40:41], v[40:41], v[150:151]
	v_pk_fma_f32 v[150:151], v[42:43], v[42:43], v[150:151]
	v_pk_fma_f32 v[150:151], v[44:45], v[44:45], v[150:151]
	v_pk_fma_f32 v[150:151], v[46:47], v[46:47], v[150:151]
	v_add_f32_e32 v150, v150, v151
	s_nop 1
	v_add_f32_dpp v150, v150, v150 quad_perm:[1,0,3,2] row_mask:0xf bank_mask:0xf bound_ctrl:1
	s_nop 1
	v_add_f32_dpp v150, v150, v150 quad_perm:[2,3,0,1] row_mask:0xf bank_mask:0xf bound_ctrl:1
	s_nop 1
	v_add_f32_dpp v150, v150, v150 row_half_mirror row_mask:0xf bank_mask:0xf bound_ctrl:1
	s_nop 1
	v_add_f32_dpp v150, v150, v150 row_mirror row_mask:0xf bank_mask:0xf bound_ctrl:1
	s_nop 1
	v_readlane_b32 s7, v150, 0
	v_readlane_b32 s8, v150, 16
	v_readlane_b32 s9, v150, 32
	v_readlane_b32 s18, v150, 48
	s_nop 1
	v_mov_b32_e32 v150, s7
	v_add_f32_e32 v150, s8, v150
	v_add_f32_e32 v150, s9, v150
	v_add_f32_e32 v150, s18, v150
	v_fmamk_f32 v150, v150, 0x3a800000, v153
	v_sqrt_f32_e32 v152, v150
	s_nop 0
	v_rcp_f32_e32 v154, v152
	s_mov_b64 exec, 1
	global_store_dword v0, v152, s[14:15]
	s_mov_b64 exec, -1
	v_pk_mul_f32 v[32:33], v[32:33], v[154:155] op_sel_hi:[1,0]
	v_pk_mul_f32 v[34:35], v[34:35], v[154:155] op_sel_hi:[1,0]
	v_pk_mul_f32 v[36:37], v[36:37], v[154:155] op_sel_hi:[1,0]
	v_pk_mul_f32 v[38:39], v[38:39], v[154:155] op_sel_hi:[1,0]
	v_pk_mul_f32 v[40:41], v[40:41], v[154:155] op_sel_hi:[1,0]
	v_pk_mul_f32 v[42:43], v[42:43], v[154:155] op_sel_hi:[1,0]
	v_pk_mul_f32 v[44:45], v[44:45], v[154:155] op_sel_hi:[1,0]
	v_pk_mul_f32 v[46:47], v[46:47], v[154:155] op_sel_hi:[1,0]
	v_pk_mul_f32 v[32:33], v[32:33], v[64:65]
	v_pk_mul_f32 v[34:35], v[34:35], v[66:67]
	v_pk_mul_f32 v[36:37], v[36:37], v[68:69]
	v_pk_mul_f32 v[38:39], v[38:39], v[70:71]
	v_pk_mul_f32 v[40:41], v[40:41], v[72:73]
	v_pk_mul_f32 v[42:43], v[42:43], v[74:75]
	v_pk_mul_f32 v[44:45], v[44:45], v[76:77]
	v_pk_mul_f32 v[46:47], v[46:47], v[78:79]
	v_cvt_pk_bf16_f32 v240, v32, v33
	v_cvt_pk_bf16_f32 v241, v34, v35
	v_cvt_pk_bf16_f32 v242, v36, v37
	v_cvt_pk_bf16_f32 v243, v38, v39
	v_cvt_pk_bf16_f32 v244, v40, v41
	v_cvt_pk_bf16_f32 v245, v42, v43
	v_cvt_pk_bf16_f32 v246, v44, v45
	v_cvt_pk_bf16_f32 v247, v46, v47
	global_store_dwordx2 v2, v[240:241], s[12:13]
	global_store_dwordx2 v2, v[242:243], s[12:13] offset:512
	global_store_dwordx2 v2, v[244:245], s[12:13] offset:1024
	global_store_dwordx2 v2, v[246:247], s[12:13] offset:1536
	v_pk_mul_f32 v[6:7], v[32:33], v[80:81]
	v_pk_mul_f32 v[8:9], v[32:33], v[96:97]
	v_pk_mul_f32 v[10:11], v[32:33], v[112:113]
	v_pk_mul_f32 v[12:13], v[32:33], v[128:129]
	v_pk_mul_f32 v[14:15], v[32:33], v[176:177]
	v_pk_mul_f32 v[144:145], v[32:33], v[192:193]
	v_pk_mul_f32 v[146:147], v[32:33], v[208:209]
	v_pk_mul_f32 v[148:149], v[32:33], v[224:225]
	v_pk_fma_f32 v[6:7], v[34:35], v[82:83], v[6:7]
	v_pk_fma_f32 v[8:9], v[34:35], v[98:99], v[8:9]
	v_pk_fma_f32 v[10:11], v[34:35], v[114:115], v[10:11]
	v_pk_fma_f32 v[12:13], v[34:35], v[130:131], v[12:13]
	v_pk_fma_f32 v[14:15], v[34:35], v[178:179], v[14:15]
	v_pk_fma_f32 v[144:145], v[34:35], v[194:195], v[144:145]
	v_pk_fma_f32 v[146:147], v[34:35], v[210:211], v[146:147]
	v_pk_fma_f32 v[148:149], v[34:35], v[226:227], v[148:149]
	v_pk_fma_f32 v[6:7], v[36:37], v[84:85], v[6:7]
	v_pk_fma_f32 v[8:9], v[36:37], v[100:101], v[8:9]
	v_pk_fma_f32 v[10:11], v[36:37], v[116:117], v[10:11]
	v_pk_fma_f32 v[12:13], v[36:37], v[132:133], v[12:13]
	v_pk_fma_f32 v[14:15], v[36:37], v[180:181], v[14:15]
	v_pk_fma_f32 v[144:145], v[36:37], v[196:197], v[144:145]
	v_pk_fma_f32 v[146:147], v[36:37], v[212:213], v[146:147]
	v_pk_fma_f32 v[148:149], v[36:37], v[228:229], v[148:149]
	v_pk_fma_f32 v[6:7], v[38:39], v[86:87], v[6:7]
	v_pk_fma_f32 v[8:9], v[38:39], v[102:103], v[8:9]
	v_pk_fma_f32 v[10:11], v[38:39], v[118:119], v[10:11]
	v_pk_fma_f32 v[12:13], v[38:39], v[134:135], v[12:13]
	v_pk_fma_f32 v[14:15], v[38:39], v[182:183], v[14:15]
	v_pk_fma_f32 v[144:145], v[38:39], v[198:199], v[144:145]
	v_pk_fma_f32 v[146:147], v[38:39], v[214:215], v[146:147]
	v_pk_fma_f32 v[148:149], v[38:39], v[230:231], v[148:149]
	v_pk_fma_f32 v[6:7], v[40:41], v[88:89], v[6:7]
	v_pk_fma_f32 v[8:9], v[40:41], v[104:105], v[8:9]
	v_pk_fma_f32 v[10:11], v[40:41], v[120:121], v[10:11]
	v_pk_fma_f32 v[12:13], v[40:41], v[136:137], v[12:13]
	v_pk_fma_f32 v[14:15], v[40:41], v[184:185], v[14:15]
	v_pk_fma_f32 v[144:145], v[40:41], v[200:201], v[144:145]
	v_pk_fma_f32 v[146:147], v[40:41], v[216:217], v[146:147]
	v_pk_fma_f32 v[148:149], v[40:41], v[232:233], v[148:149]
	v_pk_fma_f32 v[6:7], v[42:43], v[90:91], v[6:7]
	v_pk_fma_f32 v[8:9], v[42:43], v[106:107], v[8:9]
	v_pk_fma_f32 v[10:11], v[42:43], v[122:123], v[10:11]
	v_pk_fma_f32 v[12:13], v[42:43], v[138:139], v[12:13]
	v_pk_fma_f32 v[14:15], v[42:43], v[186:187], v[14:15]
	v_pk_fma_f32 v[144:145], v[42:43], v[202:203], v[144:145]
	v_pk_fma_f32 v[146:147], v[42:43], v[218:219], v[146:147]
	v_pk_fma_f32 v[148:149], v[42:43], v[234:235], v[148:149]
	v_pk_fma_f32 v[6:7], v[44:45], v[92:93], v[6:7]
	v_pk_fma_f32 v[8:9], v[44:45], v[108:109], v[8:9]
	v_pk_fma_f32 v[10:11], v[44:45], v[124:125], v[10:11]
	v_pk_fma_f32 v[12:13], v[44:45], v[140:141], v[12:13]
	v_pk_fma_f32 v[14:15], v[44:45], v[188:189], v[14:15]
	v_pk_fma_f32 v[144:145], v[44:45], v[204:205], v[144:145]
	v_pk_fma_f32 v[146:147], v[44:45], v[220:221], v[146:147]
	v_pk_fma_f32 v[148:149], v[44:45], v[236:237], v[148:149]
	v_pk_fma_f32 v[6:7], v[46:47], v[94:95], v[6:7]
	v_pk_fma_f32 v[8:9], v[46:47], v[110:111], v[8:9]
	v_pk_fma_f32 v[10:11], v[46:47], v[126:127], v[10:11]
	v_pk_fma_f32 v[12:13], v[46:47], v[142:143], v[12:13]
	v_pk_fma_f32 v[14:15], v[46:47], v[190:191], v[14:15]
	v_pk_fma_f32 v[144:145], v[46:47], v[206:207], v[144:145]
	v_pk_fma_f32 v[146:147], v[46:47], v[222:223], v[146:147]
	v_pk_fma_f32 v[148:149], v[46:47], v[238:239], v[148:149]
	v_add_f32_e32 v6, v6, v7
	v_add_f32_e32 v8, v8, v9
	v_add_f32_e32 v10, v10, v11
	v_add_f32_e32 v12, v12, v13
	v_add_f32_e32 v14, v14, v15
	v_add_f32_e32 v144, v144, v145
	v_add_f32_e32 v146, v146, v147
	v_add_f32_e32 v148, v148, v149
	s_nop 1
	v_permlane32_swap_b32_e32 v6, v14
	v_permlane32_swap_b32_e32 v8, v144
	v_permlane32_swap_b32_e32 v10, v146
	v_permlane32_swap_b32_e32 v12, v148
	v_add_f32_e32 v6, v6, v14
	v_add_f32_e32 v8, v8, v144
	v_add_f32_e32 v10, v10, v146
	v_add_f32_e32 v12, v12, v148
	s_nop 1
	v_add_f32_dpp v14, v6, v6 row_ror:8 row_mask:0xf bank_mask:0xf bound_ctrl:1
	v_add_f32_dpp v144, v8, v8 row_ror:8 row_mask:0xf bank_mask:0xf bound_ctrl:1
	v_add_f32_dpp v146, v10, v10 row_ror:8 row_mask:0xf bank_mask:0xf bound_ctrl:1
	v_add_f32_dpp v148, v12, v12 row_ror:8 row_mask:0xf bank_mask:0xf bound_ctrl:1
	v_cndmask_b32_e64 v6, v14, v144, s[64:65]
	v_cndmask_b32_e64 v8, v146, v148, s[64:65]
	s_nop 1
	v_add_f32_dpp v10, v6, v6 row_half_mirror row_mask:0xf bank_mask:0xf bound_ctrl:1
	v_add_f32_dpp v12, v8, v8 row_half_mirror row_mask:0xf bank_mask:0xf bound_ctrl:1
	v_cndmask_b32_e64 v6, v10, v12, s[66:67]
	s_nop 1
	v_add_f32_dpp v6, v6, v6 quad_perm:[1,0,3,2] row_mask:0xf bank_mask:0xf bound_ctrl:1
	s_nop 1
	v_add_f32_dpp v6, v6, v6 quad_perm:[2,3,0,1] row_mask:0xf bank_mask:0xf bound_ctrl:1
	s_nop 0
	ds_swizzle_b32 v254, v6 offset:0x401f
	s_waitcnt lgkmcnt(0)
	v_add_f32_e32 v248, v6, v254
	v_add_f32_e32 v248, v248, v156
	v_mul_f32_e64 v249, -|v248|, s57
	v_exp_f32_e32 v249, v249
	v_min_f32_e32 v253, 0, v248
	v_add_f32_e32 v250, 1.0, v249
	v_log_f32_e32 v251, v250
	v_add_f32_e32 v252, -1.0, v250
	v_rcp_f32_e32 v250, v252
	v_cmp_eq_f32_e32 vcc, 0, v252
	v_mul_f32_e32 v251, 0x3f317218, v251
	v_mul_f32_e32 v251, v251, v249
	v_mul_f32_e32 v251, v251, v250
	v_cndmask_b32_e32 v251, v251, v249, vcc
	v_sub_f32_e32 v253, v253, v251
	s_mov_b64 exec, s[62:63]
	global_store_dword v4, v253, s[26:27]
	s_mov_b64 exec, -1
	s_add_u32 s12, s12, s53
	s_addc_u32 s13, s13, 0
	s_add_u32 s14, s14, s54
	s_addc_u32 s15, s15, 0
	s_add_u32 s26, s26, s55
	s_addc_u32 s27, s27, 0
	s_add_i32 s0, s0, s96
	s_cmp_lt_i32 s0, 0x8000
	s_cbranch_scc0 .Lrow_done
	s_add_i32 s1, s0, s59
	s_min_i32 s1, s1, s61
	s_lshl_b32 s4, s1, 12
	s_add_u32 s4, s10, s4
	s_addc_u32 s5, s11, 0
	global_load_dwordx4 v[32:35], v1, s[4:5] nt
	global_load_dwordx4 v[36:39], v1, s[4:5] offset:1024 nt
	global_load_dwordx4 v[40:43], v1, s[4:5] offset:2048 nt
	global_load_dwordx4 v[44:47], v1, s[4:5] offset:3072 nt
	s_waitcnt vmcnt(20)
	v_pk_mul_f32 v[150:151], v[48:49], v[48:49]
	v_pk_fma_f32 v[150:151], v[50:51], v[50:51], v[150:151]
	v_pk_fma_f32 v[150:151], v[52:53], v[52:53], v[150:151]
	v_pk_fma_f32 v[150:151], v[54:55], v[54:55], v[150:151]
	v_pk_fma_f32 v[150:151], v[56:57], v[56:57], v[150:151]
	v_pk_fma_f32 v[150:151], v[58:59], v[58:59], v[150:151]
	v_pk_fma_f32 v[150:151], v[60:61], v[60:61], v[150:151]
	v_pk_fma_f32 v[150:151], v[62:63], v[62:63], v[150:151]
	v_add_f32_e32 v150, v150, v151
	s_nop 1
	v_add_f32_dpp v150, v150, v150 quad_perm:[1,0,3,2] row_mask:0xf bank_mask:0xf bound_ctrl:1
	s_nop 1
	v_add_f32_dpp v150, v150, v150 quad_perm:[2,3,0,1] row_mask:0xf bank_mask:0xf bound_ctrl:1
	s_nop 1
	v_add_f32_dpp v150, v150, v150 row_half_mirror row_mask:0xf bank_mask:0xf bound_ctrl:1
	s_nop 1
	v_add_f32_dpp v150, v150, v150 row_mirror row_mask:0xf bank_mask:0xf bound_ctrl:1
	s_nop 1
	v_readlane_b32 s7, v150, 0
	v_readlane_b32 s8, v150, 16
	v_readlane_b32 s9, v150, 32
	v_readlane_b32 s18, v150, 48
	s_nop 1
	v_mov_b32_e32 v150, s7
	v_add_f32_e32 v150, s8, v150
	v_add_f32_e32 v150, s9, v150
	v_add_f32_e32 v150, s18, v150
	v_fmamk_f32 v150, v150, 0x3a800000, v153
	v_sqrt_f32_e32 v152, v150
	s_nop 0
	v_rcp_f32_e32 v154, v152
	s_mov_b64 exec, 1
	global_store_dword v0, v152, s[14:15]
	s_mov_b64 exec, -1
	v_pk_mul_f32 v[48:49], v[48:49], v[154:155] op_sel_hi:[1,0]
	v_pk_mul_f32 v[50:51], v[50:51], v[154:155] op_sel_hi:[1,0]
	v_pk_mul_f32 v[52:53], v[52:53], v[154:155] op_sel_hi:[1,0]
	v_pk_mul_f32 v[54:55], v[54:55], v[154:155] op_sel_hi:[1,0]
	v_pk_mul_f32 v[56:57], v[56:57], v[154:155] op_sel_hi:[1,0]
	v_pk_mul_f32 v[58:59], v[58:59], v[154:155] op_sel_hi:[1,0]
	v_pk_mul_f32 v[60:61], v[60:61], v[154:155] op_sel_hi:[1,0]
	v_pk_mul_f32 v[62:63], v[62:63], v[154:155] op_sel_hi:[1,0]
	v_pk_mul_f32 v[48:49], v[48:49], v[64:65]
	v_pk_mul_f32 v[50:51], v[50:51], v[66:67]
	v_pk_mul_f32 v[52:53], v[52:53], v[68:69]
	v_pk_mul_f32 v[54:55], v[54:55], v[70:71]
	v_pk_mul_f32 v[56:57], v[56:57], v[72:73]
	v_pk_mul_f32 v[58:59], v[58:59], v[74:75]
	v_pk_mul_f32 v[60:61], v[60:61], v[76:77]
	v_pk_mul_f32 v[62:63], v[62:63], v[78:79]
	v_cvt_pk_bf16_f32 v240, v48, v49
	v_cvt_pk_bf16_f32 v241, v50, v51
	v_cvt_pk_bf16_f32 v242, v52, v53
	v_cvt_pk_bf16_f32 v243, v54, v55
	v_cvt_pk_bf16_f32 v244, v56, v57
	v_cvt_pk_bf16_f32 v245, v58, v59
	v_cvt_pk_bf16_f32 v246, v60, v61
	v_cvt_pk_bf16_f32 v247, v62, v63
	global_store_dwordx2 v2, v[240:241], s[12:13]
	global_store_dwordx2 v2, v[242:243], s[12:13] offset:512
	global_store_dwordx2 v2, v[244:245], s[12:13] offset:1024
	global_store_dwordx2 v2, v[246:247], s[12:13] offset:1536
	v_pk_mul_f32 v[6:7], v[48:49], v[80:81]
	v_pk_mul_f32 v[8:9], v[48:49], v[96:97]
	v_pk_mul_f32 v[10:11], v[48:49], v[112:113]
	v_pk_mul_f32 v[12:13], v[48:49], v[128:129]
	v_pk_mul_f32 v[14:15], v[48:49], v[176:177]
	v_pk_mul_f32 v[144:145], v[48:49], v[192:193]
	v_pk_mul_f32 v[146:147], v[48:49], v[208:209]
	v_pk_mul_f32 v[148:149], v[48:49], v[224:225]
	v_pk_fma_f32 v[6:7], v[50:51], v[82:83], v[6:7]
	v_pk_fma_f32 v[8:9], v[50:51], v[98:99], v[8:9]
	v_pk_fma_f32 v[10:11], v[50:51], v[114:115], v[10:11]
	v_pk_fma_f32 v[12:13], v[50:51], v[130:131], v[12:13]
	v_pk_fma_f32 v[14:15], v[50:51], v[178:179], v[14:15]
	v_pk_fma_f32 v[144:145], v[50:51], v[194:195], v[144:145]
	v_pk_fma_f32 v[146:147], v[50:51], v[210:211], v[146:147]
	v_pk_fma_f32 v[148:149], v[50:51], v[226:227], v[148:149]
	v_pk_fma_f32 v[6:7], v[52:53], v[84:85], v[6:7]
	v_pk_fma_f32 v[8:9], v[52:53], v[100:101], v[8:9]
	v_pk_fma_f32 v[10:11], v[52:53], v[116:117], v[10:11]
	v_pk_fma_f32 v[12:13], v[52:53], v[132:133], v[12:13]
	v_pk_fma_f32 v[14:15], v[52:53], v[180:181], v[14:15]
	v_pk_fma_f32 v[144:145], v[52:53], v[196:197], v[144:145]
	v_pk_fma_f32 v[146:147], v[52:53], v[212:213], v[146:147]
	v_pk_fma_f32 v[148:149], v[52:53], v[228:229], v[148:149]
	v_pk_fma_f32 v[6:7], v[54:55], v[86:87], v[6:7]
	v_pk_fma_f32 v[8:9], v[54:55], v[102:103], v[8:9]
	v_pk_fma_f32 v[10:11], v[54:55], v[118:119], v[10:11]
	v_pk_fma_f32 v[12:13], v[54:55], v[134:135], v[12:13]
	v_pk_fma_f32 v[14:15], v[54:55], v[182:183], v[14:15]
	v_pk_fma_f32 v[144:145], v[54:55], v[198:199], v[144:145]
	v_pk_fma_f32 v[146:147], v[54:55], v[214:215], v[146:147]
	v_pk_fma_f32 v[148:149], v[54:55], v[230:231], v[148:149]
	v_pk_fma_f32 v[6:7], v[56:57], v[88:89], v[6:7]
	v_pk_fma_f32 v[8:9], v[56:57], v[104:105], v[8:9]
	v_pk_fma_f32 v[10:11], v[56:57], v[120:121], v[10:11]
	v_pk_fma_f32 v[12:13], v[56:57], v[136:137], v[12:13]
	v_pk_fma_f32 v[14:15], v[56:57], v[184:185], v[14:15]
	v_pk_fma_f32 v[144:145], v[56:57], v[200:201], v[144:145]
	v_pk_fma_f32 v[146:147], v[56:57], v[216:217], v[146:147]
	v_pk_fma_f32 v[148:149], v[56:57], v[232:233], v[148:149]
	v_pk_fma_f32 v[6:7], v[58:59], v[90:91], v[6:7]
	v_pk_fma_f32 v[8:9], v[58:59], v[106:107], v[8:9]
	v_pk_fma_f32 v[10:11], v[58:59], v[122:123], v[10:11]
	v_pk_fma_f32 v[12:13], v[58:59], v[138:139], v[12:13]
	v_pk_fma_f32 v[14:15], v[58:59], v[186:187], v[14:15]
	v_pk_fma_f32 v[144:145], v[58:59], v[202:203], v[144:145]
	v_pk_fma_f32 v[146:147], v[58:59], v[218:219], v[146:147]
	v_pk_fma_f32 v[148:149], v[58:59], v[234:235], v[148:149]
	v_pk_fma_f32 v[6:7], v[60:61], v[92:93], v[6:7]
	v_pk_fma_f32 v[8:9], v[60:61], v[108:109], v[8:9]
	v_pk_fma_f32 v[10:11], v[60:61], v[124:125], v[10:11]
	v_pk_fma_f32 v[12:13], v[60:61], v[140:141], v[12:13]
	v_pk_fma_f32 v[14:15], v[60:61], v[188:189], v[14:15]
	v_pk_fma_f32 v[144:145], v[60:61], v[204:205], v[144:145]
	v_pk_fma_f32 v[146:147], v[60:61], v[220:221], v[146:147]
	v_pk_fma_f32 v[148:149], v[60:61], v[236:237], v[148:149]
	v_pk_fma_f32 v[6:7], v[62:63], v[94:95], v[6:7]
	v_pk_fma_f32 v[8:9], v[62:63], v[110:111], v[8:9]
	v_pk_fma_f32 v[10:11], v[62:63], v[126:127], v[10:11]
	v_pk_fma_f32 v[12:13], v[62:63], v[142:143], v[12:13]
	v_pk_fma_f32 v[14:15], v[62:63], v[190:191], v[14:15]
	v_pk_fma_f32 v[144:145], v[62:63], v[206:207], v[144:145]
	v_pk_fma_f32 v[146:147], v[62:63], v[222:223], v[146:147]
	v_pk_fma_f32 v[148:149], v[62:63], v[238:239], v[148:149]
	v_add_f32_e32 v6, v6, v7
	v_add_f32_e32 v8, v8, v9
	v_add_f32_e32 v10, v10, v11
	v_add_f32_e32 v12, v12, v13
	v_add_f32_e32 v14, v14, v15
	v_add_f32_e32 v144, v144, v145
	v_add_f32_e32 v146, v146, v147
	v_add_f32_e32 v148, v148, v149
	s_nop 1
	v_permlane32_swap_b32_e32 v6, v14
	v_permlane32_swap_b32_e32 v8, v144
	v_permlane32_swap_b32_e32 v10, v146
	v_permlane32_swap_b32_e32 v12, v148
	v_add_f32_e32 v6, v6, v14
	v_add_f32_e32 v8, v8, v144
	v_add_f32_e32 v10, v10, v146
	v_add_f32_e32 v12, v12, v148
	s_nop 1
	v_add_f32_dpp v14, v6, v6 row_ror:8 row_mask:0xf bank_mask:0xf bound_ctrl:1
	v_add_f32_dpp v144, v8, v8 row_ror:8 row_mask:0xf bank_mask:0xf bound_ctrl:1
	v_add_f32_dpp v146, v10, v10 row_ror:8 row_mask:0xf bank_mask:0xf bound_ctrl:1
	v_add_f32_dpp v148, v12, v12 row_ror:8 row_mask:0xf bank_mask:0xf bound_ctrl:1
	v_cndmask_b32_e64 v6, v14, v144, s[64:65]
	v_cndmask_b32_e64 v8, v146, v148, s[64:65]
	s_nop 1
	v_add_f32_dpp v10, v6, v6 row_half_mirror row_mask:0xf bank_mask:0xf bound_ctrl:1
	v_add_f32_dpp v12, v8, v8 row_half_mirror row_mask:0xf bank_mask:0xf bound_ctrl:1
	v_cndmask_b32_e64 v6, v10, v12, s[66:67]
	s_nop 1
	v_add_f32_dpp v6, v6, v6 quad_perm:[1,0,3,2] row_mask:0xf bank_mask:0xf bound_ctrl:1
	s_nop 1
	v_add_f32_dpp v6, v6, v6 quad_perm:[2,3,0,1] row_mask:0xf bank_mask:0xf bound_ctrl:1
	s_nop 0
	ds_swizzle_b32 v254, v6 offset:0x401f
	s_waitcnt lgkmcnt(0)
	v_add_f32_e32 v248, v6, v254
	v_add_f32_e32 v248, v248, v156
	v_mul_f32_e64 v249, -|v248|, s57
	v_exp_f32_e32 v249, v249
	v_min_f32_e32 v253, 0, v248
	v_add_f32_e32 v250, 1.0, v249
	v_log_f32_e32 v251, v250
	v_add_f32_e32 v252, -1.0, v250
	v_rcp_f32_e32 v250, v252
	v_cmp_eq_f32_e32 vcc, 0, v252
	v_mul_f32_e32 v251, 0x3f317218, v251
	v_mul_f32_e32 v251, v251, v249
	v_mul_f32_e32 v251, v251, v250
	v_cndmask_b32_e32 v251, v251, v249, vcc
	v_sub_f32_e32 v253, v253, v251
	s_mov_b64 exec, s[62:63]
	global_store_dword v4, v253, s[26:27]
	s_mov_b64 exec, -1
	s_add_u32 s12, s12, s53
	s_addc_u32 s13, s13, 0
	s_add_u32 s14, s14, s54
	s_addc_u32 s15, s15, 0
	s_add_u32 s26, s26, s55
	s_addc_u32 s27, s27, 0
	s_add_i32 s0, s0, s96
	s_cmp_lt_i32 s0, 0x8000
	s_cbranch_scc1 .Lrow_loop

.LBB0_493:
	s_or_b64 exec, exec, s[0:1]
	s_add_u32 s8, s30, 0x2200000
	s_addc_u32 s9, s31, 0
	s_add_u32 s18, s30, 0x2300000
	s_addc_u32 s19, s31, 0
	s_add_u32 s16, s30, 0x11400000
	s_addc_u32 s17, s31, 0
	s_cmpk_lt_i32 s2, 0x200
	s_cselect_b64 s[10:11], -1, 0
	s_and_b64 vcc, exec, s[10:11]
	v_mbcnt_lo_u32_b32 v224, -1, 0
	s_waitcnt lgkmcnt(0)
	s_barrier
	s_cbranch_vccz .LBB0_503
	s_add_u32 s5, s30, 0x1c00000
	s_addc_u32 s24, s31, 0
	s_ashr_i32 s0, s2, 5
	s_ashr_i32 s1, s0, 31
	s_lshl_b64 s[0:1], s[0:1], 16
	s_add_u32 s0, s14, s0
	s_addc_u32 s1, s15, s1
	s_lshl_b32 s4, s2, 20
	v_mbcnt_lo_u32_b32 v0, -1, 0
	v_mbcnt_hi_u32_b32 v0, -1, v0
	s_and_b32 s4, s4, 0x1f00000
	v_add_u32_e32 v0, s33, v0
	s_add_u32 s0, s0, s4
	s_addc_u32 s1, s1, 0
	v_ashrrev_i32_e32 v1, 31, v0
	v_lshl_add_u64 v[24:25], v[0:1], 4, s[0:1]
	s_movk_i32 s25, 0x2000
	v_add_co_u32_e32 v4, vcc, s25, v24
	s_movk_i32 s36, 0x4000
	s_nop 0
	v_addc_co_u32_e32 v5, vcc, 0, v25, vcc
	v_add_co_u32_e32 v8, vcc, s36, v24
	s_movk_i32 s37, 0x6000
	s_nop 0
	v_addc_co_u32_e32 v9, vcc, 0, v25, vcc
	v_add_co_u32_e32 v12, vcc, s37, v24
	s_mov_b32 s38, 0x8000
	s_nop 0
	v_addc_co_u32_e32 v13, vcc, 0, v25, vcc
	v_add_co_u32_e32 v16, vcc, s38, v24
	s_mov_b32 s39, 0xa000
	s_nop 0
	v_addc_co_u32_e32 v17, vcc, 0, v25, vcc
	v_add_co_u32_e32 v20, vcc, s39, v24
	s_mov_b32 s40, 0xc000
	s_nop 0
	v_addc_co_u32_e32 v21, vcc, 0, v25, vcc
	v_add_co_u32_e32 v26, vcc, s40, v24
	s_mov_b32 s41, 0xe000
	s_nop 0
	v_addc_co_u32_e32 v27, vcc, 0, v25, vcc
	v_add_co_u32_e32 v28, vcc, s41, v24
	global_load_dwordx4 v[0:3], v[24:25], off nt
	s_nop 0
	global_load_dwordx4 v[4:7], v[4:5], off nt
	v_addc_co_u32_e32 v29, vcc, 0, v25, vcc
	global_load_dwordx4 v[8:11], v[8:9], off nt
	s_nop 0
	global_load_dwordx4 v[12:15], v[12:13], off nt
	s_nop 0
	global_load_dwordx4 v[16:19], v[16:17], off nt
	s_nop 0
	global_load_dwordx4 v[20:23], v[20:21], off nt
	s_nop 0
	global_load_dwordx4 v[24:27], v[26:27], off nt
	s_nop 0
	global_load_dwordx4 v[28:31], v[28:29], off nt
	s_mov_b32 s1, 0
	v_mov_b32_e32 v185, 0
	s_movk_i32 s42, 0x300
	s_mov_b32 s4, 0xbfb8aa3b
	v_mbcnt_hi_u32_b32 v188, -1, v224
	s_mov_b32 s43, 0
	s_mov_b32 s51, s2
	s_branch .LBB0_496

.LBB0_496:
	s_add_i32 s44, s51, s84
	s_cmpk_gt_i32 s44, 0x1ff
	v_mbcnt_lo_u32_b32 v157, -1, 0
	v_mbcnt_hi_u32_b32 v157, -1, v157
	s_cselect_b64 s[6:7], -1, 0
	v_add_u32_e32 v186, s33, v157
	s_and_b32 s45, s51, 31
	s_ashr_i32 s0, s44, 5
	s_cmpk_lt_i32 s44, 0x200
	v_readfirstlane_b32 s23, v186
	s_cselect_b32 s0, s0, -1
	s_ashr_i32 s22, s23, 6
	v_and_b32_e32 v182, 15, v157
	s_lshl_b32 s26, s45, 17
	v_lshl_or_b32 v32, s22, 4, v182
	s_add_u32 s26, s92, s26
	v_ashrrev_i32_e32 v33, 31, v32
	s_addc_u32 s27, s93, 0
	v_lshlrev_b64 v[32:33], 9, v[32:33]
	v_lshl_add_u64 v[32:33], s[26:27], 0, v[32:33]
	v_and_b32_e32 v184, 48, v157
	v_lshl_add_u64 v[32:33], v[32:33], 0, v[184:185]
	global_load_dwordx4 v[48:51], v[32:33], off
	global_load_dwordx4 v[52:55], v[32:33], off offset:64
	global_load_dwordx4 v[56:59], v[32:33], off offset:128
	global_load_dwordx4 v[60:63], v[32:33], off offset:192
	global_load_dwordx4 v[44:47], v[32:33], off offset:256
	global_load_dwordx4 v[40:43], v[32:33], off offset:320
	global_load_dwordx4 v[36:39], v[32:33], off offset:384
	s_nop 0
	global_load_dwordx4 v[32:35], v[32:33], off offset:448
	v_and_b32_e32 v64, 31, v157
	v_ashrrev_i32_e32 v65, 5, v186
	v_lshlrev_b32_e32 v66, 9, v65
	v_bitop3_b32 v65, v65, v64, 15 bitop3:0x6c
	v_lshlrev_b32_e32 v65, 4, v65
	v_add3_u32 v65, 0, v66, v65
	v_add_u32_e32 v189, 0x200, v186
	s_waitcnt vmcnt(15)
	ds_write_b128 v65, v[0:3]
	v_ashrrev_i32_e32 v65, 5, v189
	v_lshlrev_b32_e32 v66, 9, v65
	v_bitop3_b32 v65, v65, v64, 15 bitop3:0x6c
	v_lshlrev_b32_e32 v65, 4, v65
	v_add3_u32 v65, 0, v66, v65
	v_add_u32_e32 v190, 0x400, v186
	s_waitcnt vmcnt(14)
	ds_write_b128 v65, v[4:7]
	v_ashrrev_i32_e32 v65, 5, v190
	v_lshlrev_b32_e32 v66, 9, v65
	v_bitop3_b32 v65, v65, v64, 15 bitop3:0x6c
	v_lshlrev_b32_e32 v65, 4, v65
	v_add3_u32 v65, 0, v66, v65
	v_add_u32_e32 v191, 0x600, v186
	s_waitcnt vmcnt(13)
	ds_write_b128 v65, v[8:11]
	v_ashrrev_i32_e32 v65, 5, v191
	v_lshlrev_b32_e32 v66, 9, v65
	v_bitop3_b32 v65, v65, v64, 15 bitop3:0x6c
	v_lshlrev_b32_e32 v65, 4, v65
	v_add3_u32 v65, 0, v66, v65
	v_add_u32_e32 v192, 0x800, v186
	s_waitcnt vmcnt(12)
	ds_write_b128 v65, v[12:15]
	v_ashrrev_i32_e32 v65, 5, v192
	v_lshlrev_b32_e32 v66, 9, v65
	v_bitop3_b32 v65, v65, v64, 15 bitop3:0x6c
	v_lshlrev_b32_e32 v65, 4, v65
	v_add3_u32 v65, 0, v66, v65
	v_add_u32_e32 v193, 0xa00, v186
	s_waitcnt vmcnt(11)
	ds_write_b128 v65, v[16:19]
	v_ashrrev_i32_e32 v65, 5, v193
	v_lshlrev_b32_e32 v66, 9, v65
	v_bitop3_b32 v65, v65, v64, 15 bitop3:0x6c
	v_lshlrev_b32_e32 v65, 4, v65
	v_add3_u32 v65, 0, v66, v65
	v_add_u32_e32 v194, 0xc00, v186
	s_waitcnt vmcnt(10)
	ds_write_b128 v65, v[20:23]
	v_ashrrev_i32_e32 v65, 5, v194
	v_lshlrev_b32_e32 v66, 9, v65
	v_bitop3_b32 v65, v65, v64, 15 bitop3:0x6c
	v_lshlrev_b32_e32 v65, 4, v65
	v_add3_u32 v65, 0, v66, v65
	v_add_u32_e32 v195, 0xe00, v186
	s_waitcnt vmcnt(9)
	ds_write_b128 v65, v[24:27]
	v_ashrrev_i32_e32 v65, 5, v195
	v_bitop3_b32 v64, v65, v64, 15 bitop3:0x6c
	v_lshlrev_b32_e32 v66, 9, v65
	v_lshlrev_b32_e32 v64, 4, v64
	v_bfe_u32 v156, v157, 4, 2
	v_add3_u32 v64, 0, v66, v64
	s_waitcnt vmcnt(8)
	ds_write_b128 v64, v[28:31]
	v_lshlrev_b32_e32 v196, 9, v182
	v_bitop3_b32 v64, v156, v157, 15 bitop3:0x78
	v_add_u32_e32 v100, 0, v196
	v_lshlrev_b32_e32 v64, 4, v64
	v_add_u32_e32 v197, v100, v64
	s_waitcnt lgkmcnt(0)
	s_barrier
	ds_read_b128 v[64:67], v197
	ds_read_b128 v[68:71], v197 offset:8192
	v_bitop3_b32 v72, v156, v182, 4 bitop3:0x36
	v_lshlrev_b32_e32 v72, 4, v72
	v_add_u32_e32 v198, v100, v72
	s_waitcnt vmcnt(7) lgkmcnt(1)
	v_mfma_f32_16x16x32_bf16 v[64:67], v[64:67], v[48:51], 0
	ds_read_b128 v[72:75], v198
	ds_read_b128 v[76:79], v198 offset:8192
	s_and_b32 s50, s23, 0xffffffc0
	s_add_i32 s26, s50, 0
	s_waitcnt vmcnt(6) lgkmcnt(1)
	v_mfma_f32_16x16x32_bf16 v[64:67], v[72:75], v[52:55], v[64:67]
	v_bitop3_b32 v72, v156, v182, 8 bitop3:0x36
	v_lshlrev_b32_e32 v72, 4, v72
	v_add_u32_e32 v199, v100, v72
	ds_read_b128 v[72:75], v199
	ds_read_b128 v[80:83], v199 offset:8192
	s_waitcnt vmcnt(5) lgkmcnt(1)
	v_mfma_f32_16x16x32_bf16 v[64:67], v[72:75], v[56:59], v[64:67]
	v_bitop3_b32 v72, v156, v182, 12 bitop3:0x36
	v_lshlrev_b32_e32 v72, 4, v72
	v_add_u32_e32 v200, v100, v72
	ds_read_b128 v[72:75], v200
	ds_read_b128 v[84:87], v200 offset:8192
	s_waitcnt vmcnt(4) lgkmcnt(1)
	v_mfma_f32_16x16x32_bf16 v[64:67], v[72:75], v[60:63], v[64:67]
	v_bitop3_b32 v72, v156, v182, 16 bitop3:0x36
	v_lshlrev_b32_e32 v72, 4, v72
	v_add_u32_e32 v201, v100, v72
	ds_read_b128 v[72:75], v201
	ds_read_b128 v[88:91], v201 offset:8192
	s_waitcnt vmcnt(3) lgkmcnt(1)
	v_mfma_f32_16x16x32_bf16 v[64:67], v[72:75], v[44:47], v[64:67]
	v_bitop3_b32 v72, v156, v182, 20 bitop3:0x36
	v_lshlrev_b32_e32 v72, 4, v72
	v_add_u32_e32 v202, v100, v72
	ds_read_b128 v[72:75], v202
	ds_read_b128 v[92:95], v202 offset:8192
	s_waitcnt vmcnt(2) lgkmcnt(1)
	v_mfma_f32_16x16x32_bf16 v[64:67], v[72:75], v[40:43], v[64:67]
	v_bitop3_b32 v72, v156, v182, 24 bitop3:0x36
	v_lshlrev_b32_e32 v72, 4, v72
	v_add_u32_e32 v203, v100, v72
	ds_read_b128 v[72:75], v203
	ds_read_b128 v[96:99], v203 offset:8192
	s_waitcnt vmcnt(1) lgkmcnt(1)
	v_mfma_f32_16x16x32_bf16 v[64:67], v[72:75], v[36:39], v[64:67]
	v_bitop3_b32 v72, v156, v182, 28 bitop3:0x36
	v_lshlrev_b32_e32 v72, 4, v72
	v_add_u32_e32 v204, v100, v72
	ds_read_b128 v[72:75], v204
	ds_read_b128 v[100:103], v204 offset:8192
	s_waitcnt vmcnt(0) lgkmcnt(1)
	v_mfma_f32_16x16x32_bf16 v[158:161], v[72:75], v[32:35], v[64:67]
	s_add_i32 s52, s26, 0x10000
	s_mul_i32 s26, s45, 0x30000
	s_add_u32 s26, s5, s26
	v_mfma_f32_16x16x32_bf16 v[64:67], v[68:71], v[48:51], 0
	s_addc_u32 s27, s24, 0
	s_cmp_lt_i32 s0, 0
	v_ashrrev_i32_e32 v187, 31, v186
	v_mfma_f32_16x16x32_bf16 v[64:67], v[76:79], v[52:55], v[64:67]
	v_mfma_f32_16x16x32_bf16 v[64:67], v[80:83], v[56:59], v[64:67]
	v_mfma_f32_16x16x32_bf16 v[64:67], v[84:87], v[60:63], v[64:67]
	v_mfma_f32_16x16x32_bf16 v[64:67], v[88:91], v[44:47], v[64:67]
	v_mfma_f32_16x16x32_bf16 v[64:67], v[92:95], v[40:43], v[64:67]
	v_mfma_f32_16x16x32_bf16 v[64:67], v[96:99], v[36:39], v[64:67]
	s_waitcnt lgkmcnt(0)
	v_mfma_f32_16x16x32_bf16 v[162:165], v[100:103], v[32:35], v[64:67]
	s_nop 5
	ds_read_b128 v[64:67], v197 offset:16384
	ds_read_b128 v[68:71], v197 offset:24576
	ds_read_b128 v[72:75], v198 offset:16384
	ds_read_b128 v[76:79], v198 offset:24576
	s_waitcnt lgkmcnt(3)
	v_mfma_f32_16x16x32_bf16 v[64:67], v[64:67], v[48:51], 0
	s_waitcnt lgkmcnt(1)
	v_mfma_f32_16x16x32_bf16 v[64:67], v[72:75], v[52:55], v[64:67]
	ds_read_b128 v[72:75], v199 offset:16384
	ds_read_b128 v[80:83], v199 offset:24576
	s_waitcnt lgkmcnt(1)
	v_mfma_f32_16x16x32_bf16 v[64:67], v[72:75], v[56:59], v[64:67]
	ds_read_b128 v[72:75], v200 offset:16384
	ds_read_b128 v[84:87], v200 offset:24576
	s_waitcnt lgkmcnt(1)
	v_mfma_f32_16x16x32_bf16 v[64:67], v[72:75], v[60:63], v[64:67]
	ds_read_b128 v[72:75], v201 offset:16384
	ds_read_b128 v[88:91], v201 offset:24576
	s_waitcnt lgkmcnt(1)
	v_mfma_f32_16x16x32_bf16 v[64:67], v[72:75], v[44:47], v[64:67]
	ds_read_b128 v[72:75], v202 offset:16384
	ds_read_b128 v[92:95], v202 offset:24576
	s_waitcnt lgkmcnt(1)
	v_mfma_f32_16x16x32_bf16 v[64:67], v[72:75], v[40:43], v[64:67]
	ds_read_b128 v[72:75], v203 offset:16384
	ds_read_b128 v[96:99], v203 offset:24576
	s_waitcnt lgkmcnt(1)
	v_mfma_f32_16x16x32_bf16 v[64:67], v[72:75], v[36:39], v[64:67]
	ds_read_b128 v[72:75], v204 offset:16384
	ds_read_b128 v[100:103], v204 offset:24576
	s_waitcnt lgkmcnt(1)
	v_mfma_f32_16x16x32_bf16 v[166:169], v[72:75], v[32:35], v[64:67]
	v_mfma_f32_16x16x32_bf16 v[64:67], v[68:71], v[48:51], 0
	v_mfma_f32_16x16x32_bf16 v[64:67], v[76:79], v[52:55], v[64:67]
	v_mfma_f32_16x16x32_bf16 v[64:67], v[80:83], v[56:59], v[64:67]
	v_mfma_f32_16x16x32_bf16 v[64:67], v[84:87], v[60:63], v[64:67]
	v_mfma_f32_16x16x32_bf16 v[64:67], v[88:91], v[44:47], v[64:67]
	v_mfma_f32_16x16x32_bf16 v[64:67], v[92:95], v[40:43], v[64:67]
	v_mfma_f32_16x16x32_bf16 v[64:67], v[96:99], v[36:39], v[64:67]
	s_waitcnt lgkmcnt(0)
	v_mfma_f32_16x16x32_bf16 v[170:173], v[100:103], v[32:35], v[64:67]
	s_nop 5
	ds_read_b128 v[64:67], v197 offset:32768
	ds_read_b128 v[68:71], v197 offset:40960
	ds_read_b128 v[72:75], v198 offset:32768
	ds_read_b128 v[76:79], v198 offset:40960
	s_waitcnt lgkmcnt(3)
	v_mfma_f32_16x16x32_bf16 v[64:67], v[64:67], v[48:51], 0
	s_waitcnt lgkmcnt(1)
	v_mfma_f32_16x16x32_bf16 v[64:67], v[72:75], v[52:55], v[64:67]
	ds_read_b128 v[72:75], v199 offset:32768
	ds_read_b128 v[80:83], v199 offset:40960
	s_waitcnt lgkmcnt(1)
	v_mfma_f32_16x16x32_bf16 v[64:67], v[72:75], v[56:59], v[64:67]
	ds_read_b128 v[72:75], v200 offset:32768
	ds_read_b128 v[84:87], v200 offset:40960
	s_waitcnt lgkmcnt(1)
	v_mfma_f32_16x16x32_bf16 v[64:67], v[72:75], v[60:63], v[64:67]
	ds_read_b128 v[72:75], v201 offset:32768
	ds_read_b128 v[88:91], v201 offset:40960
	s_waitcnt lgkmcnt(1)
	v_mfma_f32_16x16x32_bf16 v[64:67], v[72:75], v[44:47], v[64:67]
	ds_read_b128 v[72:75], v202 offset:32768
	ds_read_b128 v[92:95], v202 offset:40960
	s_waitcnt lgkmcnt(1)
	v_mfma_f32_16x16x32_bf16 v[64:67], v[72:75], v[40:43], v[64:67]
	ds_read_b128 v[72:75], v203 offset:32768
	ds_read_b128 v[96:99], v203 offset:40960
	s_waitcnt lgkmcnt(1)
	v_mfma_f32_16x16x32_bf16 v[64:67], v[72:75], v[36:39], v[64:67]
	ds_read_b128 v[72:75], v204 offset:32768
	ds_read_b128 v[100:103], v204 offset:40960
	s_waitcnt lgkmcnt(1)
	v_mfma_f32_16x16x32_bf16 v[174:177], v[72:75], v[32:35], v[64:67]
	v_mfma_f32_16x16x32_bf16 v[64:67], v[68:71], v[48:51], 0
	v_mfma_f32_16x16x32_bf16 v[64:67], v[76:79], v[52:55], v[64:67]
	v_mfma_f32_16x16x32_bf16 v[64:67], v[80:83], v[56:59], v[64:67]
	v_mfma_f32_16x16x32_bf16 v[64:67], v[84:87], v[60:63], v[64:67]
	v_mfma_f32_16x16x32_bf16 v[64:67], v[88:91], v[44:47], v[64:67]
	v_mfma_f32_16x16x32_bf16 v[64:67], v[92:95], v[40:43], v[64:67]
	v_mfma_f32_16x16x32_bf16 v[64:67], v[96:99], v[36:39], v[64:67]
	s_waitcnt lgkmcnt(0)
	v_mfma_f32_16x16x32_bf16 v[178:181], v[100:103], v[32:35], v[64:67]
	s_nop 5
	ds_read_b128 v[64:67], v197 offset:49152
	ds_read_b128 v[68:71], v197 offset:57344
	ds_read_b128 v[72:75], v198 offset:49152
	ds_read_b128 v[76:79], v198 offset:57344
	s_waitcnt lgkmcnt(3)
	v_mfma_f32_16x16x32_bf16 v[64:67], v[64:67], v[48:51], 0
	s_waitcnt lgkmcnt(2)
	v_mfma_f32_16x16x32_bf16 v[48:51], v[68:71], v[48:51], 0
	s_waitcnt lgkmcnt(1)
	v_mfma_f32_16x16x32_bf16 v[64:67], v[72:75], v[52:55], v[64:67]
	ds_read_b128 v[72:75], v199 offset:49152
	ds_read_b128 v[80:83], v199 offset:57344
	s_waitcnt lgkmcnt(2)
	v_mfma_f32_16x16x32_bf16 v[48:51], v[76:79], v[52:55], v[48:51]
	s_waitcnt lgkmcnt(1)
	v_mfma_f32_16x16x32_bf16 v[64:67], v[72:75], v[56:59], v[64:67]
	ds_read_b128 v[72:75], v200 offset:49152
	ds_read_b128 v[84:87], v200 offset:57344
	s_waitcnt lgkmcnt(2)
	v_mfma_f32_16x16x32_bf16 v[48:51], v[80:83], v[56:59], v[48:51]
	s_waitcnt lgkmcnt(1)
	v_mfma_f32_16x16x32_bf16 v[64:67], v[72:75], v[60:63], v[64:67]
	ds_read_b128 v[72:75], v201 offset:49152
	ds_read_b128 v[88:91], v201 offset:57344
	s_waitcnt lgkmcnt(2)
	v_mfma_f32_16x16x32_bf16 v[48:51], v[84:87], v[60:63], v[48:51]
	s_waitcnt lgkmcnt(1)
	v_mfma_f32_16x16x32_bf16 v[64:67], v[72:75], v[44:47], v[64:67]
	ds_read_b128 v[72:75], v202 offset:49152
	ds_read_b128 v[92:95], v202 offset:57344
	s_waitcnt lgkmcnt(2)
	v_mfma_f32_16x16x32_bf16 v[44:47], v[88:91], v[44:47], v[48:51]
	s_waitcnt lgkmcnt(1)
	v_mfma_f32_16x16x32_bf16 v[64:67], v[72:75], v[40:43], v[64:67]
	ds_read_b128 v[72:75], v203 offset:49152
	ds_read_b128 v[96:99], v203 offset:57344
	s_waitcnt lgkmcnt(2)
	v_mfma_f32_16x16x32_bf16 v[40:43], v[92:95], v[40:43], v[44:47]
	s_waitcnt lgkmcnt(1)
	v_mfma_f32_16x16x32_bf16 v[64:67], v[72:75], v[36:39], v[64:67]
	ds_read_b128 v[72:75], v204 offset:49152
	ds_read_b128 v[206:209], v204 offset:57344
	v_lshl_or_b32 v46, s22, 5, v182
	v_lshl_add_u64 v[44:45], s[26:27], 0, v[184:185]
	s_waitcnt lgkmcnt(2)
	v_mfma_f32_16x16x32_bf16 v[36:39], v[96:99], v[36:39], v[40:43]
	s_nop 2
	v_mad_i64_i32 v[40:41], s[26:27], v46, s42, v[44:45]
	v_or_b32_e32 v46, 16, v46
	v_mad_i64_i32 v[44:45], s[26:27], v46, s42, v[44:45]
	s_waitcnt lgkmcnt(1)
	v_mfma_f32_16x16x32_bf16 v[210:213], v[72:75], v[32:35], v[64:67]
	global_load_dwordx4 v[136:139], v[40:41], off
	global_load_dwordx4 v[120:123], v[40:41], off offset:64
	global_load_dwordx4 v[108:111], v[40:41], off offset:128
	global_load_dwordx4 v[100:103], v[40:41], off offset:192
	global_load_dwordx4 v[92:95], v[40:41], off offset:256
	global_load_dwordx4 v[84:87], v[40:41], off offset:320
	global_load_dwordx4 v[80:83], v[40:41], off offset:384
	global_load_dwordx4 v[76:79], v[40:41], off offset:448
	global_load_dwordx4 v[72:75], v[40:41], off offset:512
	global_load_dwordx4 v[68:71], v[40:41], off offset:576
	global_load_dwordx4 v[64:67], v[40:41], off offset:640
	s_nop 0
	global_load_dwordx4 v[40:43], v[40:41], off offset:704
	s_nop 0
	global_load_dwordx4 v[152:155], v[44:45], off
	global_load_dwordx4 v[148:151], v[44:45], off offset:64
	global_load_dwordx4 v[144:147], v[44:45], off offset:128
	global_load_dwordx4 v[140:143], v[44:45], off offset:192
	global_load_dwordx4 v[132:135], v[44:45], off offset:256
	global_load_dwordx4 v[128:131], v[44:45], off offset:320
	global_load_dwordx4 v[124:127], v[44:45], off offset:384
	global_load_dwordx4 v[116:119], v[44:45], off offset:448
	global_load_dwordx4 v[112:115], v[44:45], off offset:512
	global_load_dwordx4 v[104:107], v[44:45], off offset:576
	global_load_dwordx4 v[96:99], v[44:45], off offset:640
	global_load_dwordx4 v[88:91], v[44:45], off offset:704
	s_waitcnt lgkmcnt(0)
	v_mfma_f32_16x16x32_bf16 v[32:35], v[206:209], v[32:35], v[36:39]
	s_nop 2
	v_lshlrev_b32_e32 v36, 11, v156
	v_lshlrev_b32_e32 v37, 2, v182
	v_add3_u32 v36, s52, v37, v36
	ds_write2st64_b32 v36, v158, v159 offset1:2
	ds_write2st64_b32 v36, v160, v161 offset0:4 offset1:6
	ds_write2st64_b32 v36, v162, v163 offset0:32 offset1:34
	ds_write2st64_b32 v36, v164, v165 offset0:36 offset1:38
	ds_write2st64_b32 v36, v166, v167 offset0:64 offset1:66
	ds_write2st64_b32 v36, v168, v169 offset0:68 offset1:70
	ds_write2st64_b32 v36, v170, v171 offset0:96 offset1:98
	ds_write2st64_b32 v36, v172, v173 offset0:100 offset1:102
	ds_write2st64_b32 v36, v174, v175 offset0:128 offset1:130
	ds_write2st64_b32 v36, v176, v177 offset0:132 offset1:134
	ds_write2st64_b32 v36, v178, v179 offset0:160 offset1:162
	ds_write2st64_b32 v36, v180, v181 offset0:164 offset1:166
	ds_write2st64_b32 v36, v210, v211 offset0:192 offset1:194
	ds_write2st64_b32 v36, v212, v213 offset0:196 offset1:198
	ds_write2st64_b32 v36, v32, v33 offset0:224 offset1:226
	ds_write2st64_b32 v36, v34, v35 offset0:228 offset1:230
	s_cbranch_scc1 .LBB0_498
	s_lshl_b64 s[26:27], s[0:1], 16
	s_add_u32 s0, s14, s26
	s_addc_u32 s27, s15, s27
	s_lshl_b32 s26, s44, 20
	s_and_b32 s26, s26, 0x1f00000
	s_add_u32 s26, s0, s26
	s_addc_u32 s27, s27, 0
	v_lshl_add_u64 v[24:25], v[186:187], 4, s[26:27]
	v_add_co_u32_e32 v4, vcc, s25, v24
	s_nop 1
	v_addc_co_u32_e32 v5, vcc, 0, v25, vcc
	v_add_co_u32_e32 v8, vcc, s36, v24
	global_load_dwordx4 v[0:3], v[24:25], off nt
	s_nop 0
	global_load_dwordx4 v[4:7], v[4:5], off nt
	v_addc_co_u32_e32 v9, vcc, 0, v25, vcc
	v_add_co_u32_e32 v12, vcc, s37, v24
	s_nop 1
	v_addc_co_u32_e32 v13, vcc, 0, v25, vcc
	v_add_co_u32_e32 v16, vcc, s38, v24
	global_load_dwordx4 v[8:11], v[8:9], off nt
	s_nop 0
	global_load_dwordx4 v[12:15], v[12:13], off nt
	v_addc_co_u32_e32 v17, vcc, 0, v25, vcc
	v_add_co_u32_e32 v20, vcc, s39, v24
	s_nop 1
	v_addc_co_u32_e32 v21, vcc, 0, v25, vcc
	v_add_co_u32_e32 v26, vcc, s40, v24
	global_load_dwordx4 v[16:19], v[16:17], off nt
	s_nop 0
	global_load_dwordx4 v[20:23], v[20:21], off nt
	v_addc_co_u32_e32 v27, vcc, 0, v25, vcc
	v_add_co_u32_e32 v28, vcc, s41, v24
	s_nop 1
	v_addc_co_u32_e32 v29, vcc, 0, v25, vcc
	global_load_dwordx4 v[24:27], v[26:27], off nt
	s_nop 0
	global_load_dwordx4 v[28:31], v[28:29], off nt

.LBB0_508:
	s_or_b64 exec, exec, s[42:43]
	s_ashr_i32 s0, s4, 31
	s_lshr_b32 s0, s0, 29
	s_add_i32 s0, s4, s0
	s_ashr_i32 s26, s0, 3
	s_and_b32 s0, s0, -8
	s_ashr_i32 s45, s68, 6
	s_ashr_i32 s27, s26, 31
	s_sub_i32 s44, s4, s0
	s_lshl_b64 s[4:5], s[26:27], 11
	s_lshl_b32 s57, s45, 5
	s_or_b32 s0, s4, s52
	s_ashr_i32 s4, s57, 31
	s_add_u32 s42, s0, s57
	s_addc_u32 s43, s5, s4
	s_lshl_b64 s[4:5], s[42:43], 10
	s_add_u32 s0, s3, s4
	s_addc_u32 s54, s66, s5
	s_lshl_b32 s4, s44, 6
	s_ashr_i32 s5, s4, 31
	s_lshl_b64 s[50:51], s[4:5], 1
	s_add_u32 s4, s0, s50
	s_addc_u32 s5, s54, s51
	s_lshl_b64 s[26:27], s[26:27], 21
	s_add_u32 s0, s62, s26
	s_addc_u32 s55, s63, s27
	s_add_u32 s54, s0, s50
	s_addc_u32 s55, s55, s51
	s_add_u32 s0, s20, s26
	v_and_b32_e32 v253, 63, v252
	s_addc_u32 s27, s21, s27
	s_add_u32 s26, s0, s50
	v_lshlrev_b32_e32 v222, 10, v253
	s_addc_u32 s27, s27, s51
	v_lshl_add_u64 v[0:1], s[54:55], 0, v[222:223]
	s_lshl_b32 s54, s45, 3
	s_ashr_i32 s55, s54, 31
	v_lshl_add_u64 v[224:225], s[54:55], 1, v[0:1]
	s_lshl_b32 s0, s45, 4
	v_bfe_u32 v0, v252, 2, 4
	v_and_or_b32 v0, s0, 48, v0
	v_lshlrev_b32_e32 v222, 10, v0
	s_ashr_i32 s0, s68, 3
	v_lshl_add_u64 v[0:1], s[26:27], 0, v[222:223]
	s_and_b32 s26, s0, 0xffffffe0
	s_ashr_i32 s27, s26, 31
	s_lshl_b32 s56, s45, 10
	v_lshlrev_b32_e32 v2, 3, v252
	s_cmp_lg_u32 0, -1
	v_and_b32_e32 v240, 24, v2
	s_cselect_b32 s0, 0, 0
	v_lshl_add_u64 v[0:1], s[26:27], 1, v[0:1]
	v_lshlrev_b32_e32 v222, 1, v240
	s_add_i32 s69, s56, s0
	s_mov_b32 s0, m0
	s_mov_b32 m0, s69
	s_nop 0
	global_load_lds_dwordx4 v[224:225], off
	s_mov_b32 m0, s0
	v_and_b32_e32 v254, 31, v252
	v_lshl_add_u64 v[48:49], v[0:1], 0, v[222:223]
	s_add_i32 s70, s69, 0x6000
	s_mov_b32 s0, m0
	s_mov_b32 m0, s70
	s_nop 0
	global_load_lds_dwordx4 v[48:49], off
	s_mov_b32 m0, s0
	v_lshl_add_u64 v[0:1], v[224:225], 0, s[6:7]
	v_bfe_u32 v232, v252, 5, 1
	s_add_i32 s0, s69, 0x2000
	s_mov_b32 s26, m0
	s_mov_b32 m0, s0
	s_nop 0
	global_load_lds_dwordx4 v[0:1], off
	s_mov_b32 m0, s26
	v_lshlrev_b32_e32 v0, 10, v254
	v_lshl_or_b32 v2, v232, 4, v0
	global_load_dwordx4 v[140:143], v2, s[4:5] nt
	global_load_dwordx4 v[136:139], v2, s[4:5] offset:32 nt
	global_load_dwordx4 v[132:135], v2, s[4:5] offset:64 nt
	global_load_dwordx4 v[128:131], v2, s[4:5] offset:96 nt
	s_lshl_b32 s0, s52, 2
	s_add_i32 s67, s0, 0
	v_or_b32_e32 v239, s57, v254
	v_lshl_add_u64 v[0:1], v[224:225], 0, s[22:23]
	s_add_i32 s0, s69, 0x4000
	s_add_i32 s67, s67, 0x14800
	s_mov_b32 s4, m0
	s_mov_b32 m0, s0
	s_nop 0
	global_load_lds_dwordx4 v[0:1], off
	s_mov_b32 m0, s4
	v_lshl_add_u32 v3, v239, 2, s67
	s_waitcnt vmcnt(3) lgkmcnt(0)
	s_barrier
	ds_read_b32 v0, v3
	v_lshlrev_b32_e32 v1, 10, v232
	v_lshlrev_b32_e32 v2, 4, v254
	v_add3_u32 v241, 0, v1, v2
	s_cmp_lg_u32 s52, 0
	s_waitcnt lgkmcnt(0)
	v_add_f32_e32 v0, 0x41800000, v0
	v_xor_b32_e32 v32, 0x80000000, v0
	v_mov_b32_e32 v33, v32
	v_mov_b32_e32 v34, v32
	v_mov_b32_e32 v35, v32
	v_mov_b32_e32 v36, v32
	v_mov_b32_e32 v37, v32
	v_mov_b32_e32 v38, v32
	v_mov_b32_e32 v39, v32
	v_mov_b32_e32 v40, v32
	v_mov_b32_e32 v41, v32
	v_mov_b32_e32 v42, v32
	v_mov_b32_e32 v43, v32
	v_mov_b32_e32 v44, v32
	v_mov_b32_e32 v45, v32
	v_mov_b32_e32 v46, v32
	v_mov_b32_e32 v47, v32
	ds_read_b128 v[0:3], v241
	ds_read_b128 v[50:53], v241 offset:512
	s_cselect_b64 s[4:5], -1, 0
	v_lshlrev_b32_e32 v222, 2, v232
	s_and_b64 vcc, exec, s[4:5]
	s_waitcnt vmcnt(3) lgkmcnt(1)
	v_mfma_f32_32x32x16_bf16 v[16:31], v[0:3], v[140:143], v[32:47]
	s_waitcnt lgkmcnt(0)
	v_mfma_f32_32x32x16_bf16 v[0:15], v[50:53], v[140:143], v[32:47]
	ds_read_b128 v[50:53], v241 offset:2048
	s_waitcnt vmcnt(2) lgkmcnt(0)
	v_mfma_f32_32x32x16_bf16 v[16:31], v[50:53], v[136:139], v[16:31]
	ds_read_b128 v[50:53], v241 offset:2560
	s_waitcnt lgkmcnt(0)
	v_mfma_f32_32x32x16_bf16 v[0:15], v[50:53], v[136:139], v[0:15]
	ds_read_b128 v[50:53], v241 offset:4096
	s_waitcnt vmcnt(1) lgkmcnt(0)
	v_mfma_f32_32x32x16_bf16 v[16:31], v[50:53], v[132:135], v[16:31]
	ds_read_b128 v[50:53], v241 offset:4608
	s_waitcnt lgkmcnt(0)
	v_mfma_f32_32x32x16_bf16 v[0:15], v[50:53], v[132:135], v[0:15]
	ds_read_b128 v[50:53], v241 offset:6144
	s_waitcnt vmcnt(0) lgkmcnt(0)
	v_mfma_f32_32x32x16_bf16 v[16:31], v[50:53], v[128:131], v[16:31]
	ds_read_b128 v[50:53], v241 offset:6656
	s_waitcnt lgkmcnt(0)
	v_mfma_f32_32x32x16_bf16 v[0:15], v[50:53], v[128:131], v[0:15]
	s_nop 15
	s_nop 7
	s_cbranch_vccnz .LBB0_510
	v_or_b32_e32 v50, 32, v222
	v_cmp_le_i32_e32 vcc, v50, v239
	v_or_b32_e32 v50, 33, v222
	s_nop 7
	v_cndmask_b32_e32 v0, v233, v0, vcc
	v_cmp_lt_i32_e32 vcc, v222, v239
	s_nop 1
	v_cndmask_b32_e32 v17, v233, v17, vcc
	v_cmp_le_i32_e32 vcc, v222, v239
	s_nop 1
	v_cndmask_b32_e32 v16, v233, v16, vcc
	v_cmp_le_i32_e32 vcc, v50, v239
	v_or_b32_e32 v50, 2, v222
	s_nop 0
	v_cndmask_b32_e32 v1, v233, v1, vcc
	v_cmp_le_i32_e32 vcc, v50, v239
	v_or_b32_e32 v50, 34, v222
	s_nop 0
	v_cndmask_b32_e32 v18, v233, v18, vcc
	v_cmp_le_i32_e32 vcc, v50, v239
	v_or_b32_e32 v50, 3, v222
	s_nop 0
	v_cndmask_b32_e32 v2, v233, v2, vcc
	v_cmp_le_i32_e32 vcc, v50, v239
	v_or_b32_e32 v50, 35, v222
	s_nop 0
	v_cndmask_b32_e32 v19, v233, v19, vcc
	v_cmp_le_i32_e32 vcc, v50, v239
	v_or_b32_e32 v50, 8, v222
	s_nop 0
	v_cndmask_b32_e32 v3, v233, v3, vcc
	v_cmp_le_i32_e32 vcc, v50, v239
	v_or_b32_e32 v50, 40, v222
	s_nop 0
	v_cndmask_b32_e32 v20, v233, v20, vcc
	v_cmp_le_i32_e32 vcc, v50, v239
	v_or_b32_e32 v50, 9, v222
	s_nop 0
	v_cndmask_b32_e32 v4, v233, v4, vcc
	v_cmp_le_i32_e32 vcc, v50, v239
	v_or_b32_e32 v50, 41, v222
	s_nop 0
	v_cndmask_b32_e32 v21, v233, v21, vcc
	v_cmp_le_i32_e32 vcc, v50, v239
	v_or_b32_e32 v50, 10, v222
	s_nop 0
	v_cndmask_b32_e32 v5, v233, v5, vcc
	v_cmp_le_i32_e32 vcc, v50, v239
	v_or_b32_e32 v50, 42, v222
	s_nop 0
	v_cndmask_b32_e32 v22, v233, v22, vcc
	v_cmp_le_i32_e32 vcc, v50, v239
	v_or_b32_e32 v50, 11, v222
	s_nop 0
	v_cndmask_b32_e32 v6, v233, v6, vcc
	v_cmp_le_i32_e32 vcc, v50, v239
	v_or_b32_e32 v50, 43, v222
	s_nop 0
	v_cndmask_b32_e32 v23, v233, v23, vcc
	v_cmp_le_i32_e32 vcc, v50, v239
	v_or_b32_e32 v50, 16, v222
	s_nop 0
	v_cndmask_b32_e32 v7, v233, v7, vcc
	v_cmp_le_i32_e32 vcc, v50, v239
	v_or_b32_e32 v50, 48, v222
	s_nop 0
	v_cndmask_b32_e32 v24, v233, v24, vcc
	v_cmp_le_i32_e32 vcc, v50, v239
	v_or_b32_e32 v50, 17, v222
	s_nop 0
	v_cndmask_b32_e32 v8, v233, v8, vcc
	v_cmp_le_i32_e32 vcc, v50, v239
	v_or_b32_e32 v50, 49, v222
	s_nop 0
	v_cndmask_b32_e32 v25, v233, v25, vcc
	v_cmp_le_i32_e32 vcc, v50, v239
	v_or_b32_e32 v50, 18, v222
	s_nop 0
	v_cndmask_b32_e32 v9, v233, v9, vcc
	v_cmp_le_i32_e32 vcc, v50, v239
	v_or_b32_e32 v50, 50, v222
	s_nop 0
	v_cndmask_b32_e32 v26, v233, v26, vcc
	v_cmp_le_i32_e32 vcc, v50, v239
	v_or_b32_e32 v50, 19, v222
	s_nop 0
	v_cndmask_b32_e32 v10, v233, v10, vcc
	v_cmp_le_i32_e32 vcc, v50, v239
	v_or_b32_e32 v50, 51, v222
	s_nop 0
	v_cndmask_b32_e32 v27, v233, v27, vcc
	v_cmp_le_i32_e32 vcc, v50, v239
	v_or_b32_e32 v50, 24, v222
	s_nop 0
	v_cndmask_b32_e32 v11, v233, v11, vcc
	v_cmp_le_i32_e32 vcc, v50, v239
	v_or_b32_e32 v50, 56, v222
	s_nop 0
	v_cndmask_b32_e32 v28, v233, v28, vcc
	v_cmp_le_i32_e32 vcc, v50, v239
	v_or_b32_e32 v50, 25, v222
	s_nop 0
	v_cndmask_b32_e32 v12, v233, v12, vcc
	v_cmp_le_i32_e32 vcc, v50, v239
	v_or_b32_e32 v50, 57, v222
	s_nop 0
	v_cndmask_b32_e32 v29, v233, v29, vcc
	v_cmp_le_i32_e32 vcc, v50, v239
	v_or_b32_e32 v50, 26, v222
	s_nop 0
	v_cndmask_b32_e32 v13, v233, v13, vcc
	v_cmp_le_i32_e32 vcc, v50, v239
	v_or_b32_e32 v50, 58, v222
	s_nop 0
	v_cndmask_b32_e32 v30, v233, v30, vcc
	v_cmp_le_i32_e32 vcc, v50, v239
	v_or_b32_e32 v50, 27, v222
	s_nop 0
	v_cndmask_b32_e32 v14, v233, v14, vcc
	v_cmp_le_i32_e32 vcc, v50, v239
	v_or_b32_e32 v50, 59, v222
	s_nop 0
	v_cndmask_b32_e32 v31, v233, v31, vcc
	v_cmp_le_i32_e32 vcc, v50, v239
	s_nop 1
	v_cndmask_b32_e32 v15, v233, v15, vcc

.LBB0_638:
	v_lshl_or_b32 v164, s20, 8, v175
	v_ashrrev_i32_e32 v165, 31, v164
	v_lshl_add_u64 v[60:61], v[164:165], 2, s[78:79]
	global_load_dwordx4 v[68:71], v[60:61], off
	global_load_dwordx4 v[64:67], v[60:61], off offset:16
	v_ashrrev_i32_e32 v56, 4, v164
	v_lshl_add_u32 v166, s50, 8, v155
	v_ashrrev_i32_e32 v57, 31, v56
	v_ashrrev_i32_e32 v167, 31, v166
	v_lshlrev_b64 v[56:57], 20, v[56:57]
	v_lshlrev_b64 v[172:173], 5, v[166:167]
	v_lshl_add_u64 v[168:169], s[16:17], 0, v[56:57]
	v_lshlrev_b32_e32 v152, 1, v154
	v_lshl_add_u64 v[56:57], v[168:169], 0, v[172:173]
	v_lshl_add_u64 v[56:57], v[56:57], 0, v[152:153]
	global_load_dwordx4 v[180:183], v[56:57], off nt
	v_or_b32_e32 v56, 0x80, v164
	v_ashrrev_i32_e32 v184, 4, v56
	global_load_dwordx4 v[56:59], v[60:61], off offset:528
	s_nop 0
	global_load_dwordx4 v[60:63], v[60:61], off offset:512
	v_lshlrev_b64 v[170:171], 11, v[166:167]
	v_lshl_add_u64 v[170:171], s[0:1], 0, v[170:171]
	v_ashrrev_i32_e32 v185, 31, v184
	v_lshl_add_u64 v[186:187], v[164:165], 1, v[170:171]
	v_lshlrev_b64 v[170:171], 20, v[184:185]
	v_lshl_add_u64 v[170:171], s[16:17], 0, v[170:171]
	v_lshl_add_u64 v[184:185], v[170:171], 0, v[172:173]
	v_lshl_add_u64 v[184:185], v[184:185], 0, v[152:153]
	s_lshl_b32 s50, s20, 2
	s_ashr_i32 s51, s50, 31
	s_waitcnt vmcnt(0)
	v_pk_add_f32 v[142:143], v[142:143], v[70:71]
	v_pk_add_f32 v[140:141], v[140:141], v[68:69]
	v_pk_add_f32 v[138:139], v[138:139], v[66:67]
	v_pk_add_f32 v[136:137], v[136:137], v[64:65]
	v_mul_f32_e32 v140, 0xbfb8aa3b, v140
	v_mul_f32_e32 v141, 0xbfb8aa3b, v141
	v_mul_f32_e32 v142, 0xbfb8aa3b, v142
	v_mul_f32_e32 v143, 0xbfb8aa3b, v143
	v_mul_f32_e32 v136, 0xbfb8aa3b, v136
	v_mul_f32_e32 v137, 0xbfb8aa3b, v137
	v_mul_f32_e32 v138, 0xbfb8aa3b, v138
	v_mul_f32_e32 v139, 0xbfb8aa3b, v139
	v_exp_f32_e32 v140, v140
	v_exp_f32_e32 v141, v141
	v_exp_f32_e32 v142, v142
	v_exp_f32_e32 v143, v143
	v_exp_f32_e32 v136, v136
	v_exp_f32_e32 v137, v137
	v_exp_f32_e32 v138, v138
	v_exp_f32_e32 v139, v139
	v_add_f32_e32 v140, 1.0, v140
	v_add_f32_e32 v141, 1.0, v141
	v_add_f32_e32 v142, 1.0, v142
	v_add_f32_e32 v143, 1.0, v143
	v_add_f32_e32 v136, 1.0, v136
	v_add_f32_e32 v137, 1.0, v137
	v_add_f32_e32 v138, 1.0, v138
	v_add_f32_e32 v139, 1.0, v139
	v_rcp_f32_e32 v140, v140
	v_rcp_f32_e32 v141, v141
	v_rcp_f32_e32 v142, v142
	v_rcp_f32_e32 v143, v143
	v_rcp_f32_e32 v136, v136
	v_rcp_f32_e32 v137, v137
	v_rcp_f32_e32 v138, v138
	v_rcp_f32_e32 v139, v139
	v_lshlrev_b32_e32 v167, 16, v180
	v_and_b32_e32 v180, 0xffff0000, v180
	v_lshlrev_b32_e32 v188, 16, v181
	v_and_b32_e32 v181, 0xffff0000, v181
	v_lshlrev_b32_e32 v189, 16, v182
	v_and_b32_e32 v182, 0xffff0000, v182
	v_lshlrev_b32_e32 v190, 16, v183
	v_and_b32_e32 v183, 0xffff0000, v183
	v_mul_f32_e32 v167, v140, v167
	v_mul_f32_e32 v180, v141, v180
	v_mul_f32_e32 v142, v142, v188
	v_mul_f32_e32 v143, v143, v181
	v_mul_f32_e32 v181, v136, v189
	v_mul_f32_e32 v182, v137, v182
	v_mul_f32_e32 v188, v138, v190
	v_mul_f32_e32 v183, v139, v183
	v_cvt_pk_bf16_f32 v136, v167, v180
	v_cvt_pk_bf16_f32 v137, v142, v143
	v_cvt_pk_bf16_f32 v138, v181, v182
	v_cvt_pk_bf16_f32 v139, v188, v183
	global_store_dwordx4 v[186:187], v[136:139], off
	global_load_dwordx4 v[138:141], v[184:185], off nt
	v_pk_add_f32 v[134:135], v[134:135], v[62:63]
	v_pk_add_f32 v[132:133], v[132:133], v[60:61]
	v_pk_add_f32 v[130:131], v[130:131], v[58:59]
	v_pk_add_f32 v[128:129], v[128:129], v[56:57]
	v_mul_f32_e32 v133, 0xbfb8aa3b, v133
	v_mul_f32_e32 v135, 0xbfb8aa3b, v135
	v_mul_f32_e32 v129, 0xbfb8aa3b, v129
	v_mul_f32_e32 v131, 0xbfb8aa3b, v131
	v_mul_f32_e32 v132, 0xbfb8aa3b, v132
	v_mul_f32_e32 v134, 0xbfb8aa3b, v134
	v_mul_f32_e32 v128, 0xbfb8aa3b, v128
	v_mul_f32_e32 v130, 0xbfb8aa3b, v130
	v_exp_f32_e32 v133, v133
	v_exp_f32_e32 v135, v135
	v_exp_f32_e32 v129, v129
	v_exp_f32_e32 v131, v131
	v_exp_f32_e32 v132, v132
	v_exp_f32_e32 v134, v134
	v_exp_f32_e32 v128, v128
	v_exp_f32_e32 v130, v130
	v_add_f32_e32 v133, 1.0, v133
	v_add_f32_e32 v135, 1.0, v135
	v_add_f32_e32 v129, 1.0, v129
	v_add_f32_e32 v131, 1.0, v131
	v_add_f32_e32 v132, 1.0, v132
	v_add_f32_e32 v134, 1.0, v134
	v_add_f32_e32 v128, 1.0, v128
	v_add_f32_e32 v130, 1.0, v130
	v_rcp_f32_e32 v133, v133
	v_rcp_f32_e32 v135, v135
	v_rcp_f32_e32 v129, v129
	v_rcp_f32_e32 v131, v131
	v_mul_f32_e32 v180, v180, v180
	v_mul_f32_e32 v143, v143, v143
	v_mul_f32_e32 v182, v182, v182
	v_mul_f32_e32 v183, v183, v183
	v_rcp_f32_e32 v132, v132
	v_rcp_f32_e32 v134, v134
	v_rcp_f32_e32 v128, v128
	v_rcp_f32_e32 v130, v130
	v_fmac_f32_e32 v180, v167, v167
	v_fmac_f32_e32 v143, v142, v142
	v_fmac_f32_e32 v182, v181, v181
	v_fmac_f32_e32 v183, v188, v188
	v_add_f32_e32 v142, v180, v143
	v_add_f32_e32 v143, v182, v183
	v_add_f32_e32 v142, v142, v143
	v_and_b32_e32 v137, 64, v179
	v_xor_b32_e32 v136, 16, v179
	v_add_u32_e32 v137, 64, v137
	v_cmp_lt_i32_e32 vcc, v136, v137
	v_xor_b32_e32 v184, 32, v179
	s_waitcnt vmcnt(0)
	v_lshlrev_b32_e32 v143, 16, v138
	v_and_b32_e32 v138, 0xffff0000, v138
	v_lshlrev_b32_e32 v167, 16, v139
	v_and_b32_e32 v139, 0xffff0000, v139
	v_lshlrev_b32_e32 v180, 16, v140
	v_and_b32_e32 v140, 0xffff0000, v140
	v_lshlrev_b32_e32 v181, 16, v141
	v_and_b32_e32 v141, 0xffff0000, v141
	v_mul_f32_e32 v133, v133, v138
	v_mul_f32_e32 v135, v135, v139
	v_mul_f32_e32 v139, v129, v140
	v_mul_f32_e32 v131, v131, v141
	v_mul_f32_e32 v132, v132, v143
	v_mul_f32_e32 v134, v134, v167
	v_mul_f32_e32 v138, v128, v180
	v_mul_f32_e32 v140, v130, v181
	v_mul_f32_e32 v128, v133, v133
	v_mul_f32_e32 v129, v135, v135
	v_mul_f32_e32 v130, v139, v139
	v_mul_f32_e32 v141, v131, v131
	v_fmac_f32_e32 v128, v132, v132
	v_fmac_f32_e32 v129, v134, v134
	v_fmac_f32_e32 v130, v138, v138
	v_fmac_f32_e32 v141, v140, v140
	v_add_f32_e32 v128, v128, v129
	v_add_f32_e32 v129, v130, v141
	v_cndmask_b32_e32 v136, v179, v136, vcc
	v_add_f32_e32 v128, v128, v129
	v_lshlrev_b32_e32 v136, 2, v136
	v_add_f32_e32 v128, v142, v128
	ds_bpermute_b32 v129, v136, v128
	v_cmp_lt_i32_e32 vcc, v184, v137
	v_cvt_pk_bf16_f32 v132, v132, v133
	v_cvt_pk_bf16_f32 v133, v134, v135
	v_cvt_pk_bf16_f32 v134, v138, v139
	s_waitcnt lgkmcnt(0)
	v_add_f32_e32 v128, v128, v129
	v_cvt_pk_bf16_f32 v135, v140, v131
	v_cndmask_b32_e32 v130, v179, v184, vcc
	v_lshlrev_b32_e32 v130, 2, v130
	ds_bpermute_b32 v129, v130, v128
	global_store_dwordx4 v[186:187], v[132:135], off offset:256
	s_and_saveexec_b64 s[52:53], s[4:5]
	s_cbranch_execz .LBB0_640
	v_lshl_add_u64 v[132:133], s[18:19], 0, v[172:173]
	v_lshl_add_u64 v[132:133], s[50:51], 2, v[132:133]
	s_lshl_b32 s20, s66, 2
	v_lshl_add_u64 v[132:133], v[132:133], 0, s[20:21]
	s_waitcnt lgkmcnt(0)
	v_add_f32_e32 v128, v128, v129
	global_store_dword v[132:133], v128, off
.LBB0_640:
	s_or_b64 exec, exec, s[52:53]
	v_or_b32_e32 v138, 16, v166
	v_ashrrev_i32_e32 v139, 31, v138
	s_waitcnt lgkmcnt(0)
	v_lshlrev_b64 v[128:129], 5, v[138:139]
	v_lshl_add_u64 v[132:133], v[168:169], 0, v[128:129]
	v_lshl_add_u64 v[132:133], v[132:133], 0, v[152:153]
	global_load_dwordx4 v[132:135], v[132:133], off nt
	v_pk_add_f32 v[126:127], v[126:127], v[70:71]
	v_pk_add_f32 v[124:125], v[124:125], v[68:69]
	v_pk_add_f32 v[122:123], v[122:123], v[66:67]
	v_pk_add_f32 v[120:121], v[120:121], v[64:65]
	v_mul_f32_e32 v124, 0xbfb8aa3b, v124
	v_mul_f32_e32 v125, 0xbfb8aa3b, v125
	v_mul_f32_e32 v126, 0xbfb8aa3b, v126
	v_mul_f32_e32 v127, 0xbfb8aa3b, v127
	v_mul_f32_e32 v131, 0xbfb8aa3b, v120
	v_mul_f32_e32 v137, 0xbfb8aa3b, v121
	v_mul_f32_e32 v122, 0xbfb8aa3b, v122
	v_mul_f32_e32 v123, 0xbfb8aa3b, v123
	v_lshlrev_b64 v[120:121], 11, v[138:139]
	v_exp_f32_e32 v138, v124
	v_exp_f32_e32 v139, v125
	v_exp_f32_e32 v140, v126
	v_exp_f32_e32 v141, v127
	v_exp_f32_e32 v131, v131
	v_exp_f32_e32 v137, v137
	v_exp_f32_e32 v142, v122
	v_exp_f32_e32 v143, v123
	v_lshl_add_u64 v[120:121], s[0:1], 0, v[120:121]
	v_lshl_add_u64 v[122:123], v[170:171], 0, v[128:129]
	v_lshl_add_u64 v[124:125], v[164:165], 1, v[120:121]
	v_lshl_add_u64 v[126:127], v[122:123], 0, v[152:153]
	v_add_f32_e32 v120, 1.0, v138
	v_add_f32_e32 v121, 1.0, v139
	v_add_f32_e32 v122, 1.0, v140
	v_add_f32_e32 v123, 1.0, v141
	v_add_f32_e32 v131, 1.0, v131
	v_add_f32_e32 v137, 1.0, v137
	v_add_f32_e32 v138, 1.0, v142
	v_add_f32_e32 v139, 1.0, v143
	v_rcp_f32_e32 v120, v120
	v_rcp_f32_e32 v121, v121
	v_rcp_f32_e32 v122, v122
	v_rcp_f32_e32 v123, v123
	v_rcp_f32_e32 v131, v131
	v_rcp_f32_e32 v137, v137
	v_rcp_f32_e32 v138, v138
	v_rcp_f32_e32 v139, v139
	v_pk_add_f32 v[118:119], v[118:119], v[62:63]
	v_pk_add_f32 v[116:117], v[116:117], v[60:61]
	v_pk_add_f32 v[114:115], v[114:115], v[58:59]
	v_pk_add_f32 v[112:113], v[112:113], v[56:57]
	v_mul_f32_e32 v117, 0xbfb8aa3b, v117
	v_mul_f32_e32 v119, 0xbfb8aa3b, v119
	v_mul_f32_e32 v113, 0xbfb8aa3b, v113
	v_mul_f32_e32 v115, 0xbfb8aa3b, v115
	v_mul_f32_e32 v116, 0xbfb8aa3b, v116
	v_mul_f32_e32 v118, 0xbfb8aa3b, v118
	v_mul_f32_e32 v112, 0xbfb8aa3b, v112
	v_mul_f32_e32 v114, 0xbfb8aa3b, v114
	v_exp_f32_e32 v117, v117
	v_exp_f32_e32 v119, v119
	v_exp_f32_e32 v113, v113
	v_exp_f32_e32 v115, v115
	v_exp_f32_e32 v116, v116
	v_exp_f32_e32 v118, v118
	v_exp_f32_e32 v112, v112
	v_exp_f32_e32 v114, v114
	v_add_f32_e32 v117, 1.0, v117
	v_add_f32_e32 v119, 1.0, v119
	v_add_f32_e32 v113, 1.0, v113
	v_add_f32_e32 v115, 1.0, v115
	v_add_f32_e32 v116, 1.0, v116
	v_add_f32_e32 v118, 1.0, v118
	v_add_f32_e32 v112, 1.0, v112
	v_add_f32_e32 v114, 1.0, v114
	v_rcp_f32_e32 v117, v117
	v_rcp_f32_e32 v119, v119
	v_rcp_f32_e32 v113, v113
	v_rcp_f32_e32 v115, v115
	v_rcp_f32_e32 v116, v116
	v_rcp_f32_e32 v118, v118
	v_rcp_f32_e32 v112, v112
	v_rcp_f32_e32 v114, v114
	s_waitcnt vmcnt(0)
	v_lshlrev_b32_e32 v140, 16, v132
	v_and_b32_e32 v132, 0xffff0000, v132
	v_lshlrev_b32_e32 v141, 16, v133
	v_and_b32_e32 v133, 0xffff0000, v133
	v_lshlrev_b32_e32 v142, 16, v134
	v_and_b32_e32 v134, 0xffff0000, v134
	v_lshlrev_b32_e32 v143, 16, v135
	v_and_b32_e32 v135, 0xffff0000, v135
	v_mul_f32_e32 v140, v120, v140
	v_mul_f32_e32 v132, v121, v132
	v_mul_f32_e32 v141, v122, v141
	v_mul_f32_e32 v133, v123, v133
	v_mul_f32_e32 v131, v131, v142
	v_mul_f32_e32 v134, v137, v134
	v_mul_f32_e32 v137, v138, v143
	v_mul_f32_e32 v135, v139, v135
	v_cvt_pk_bf16_f32 v120, v140, v132
	v_cvt_pk_bf16_f32 v121, v141, v133
	v_cvt_pk_bf16_f32 v122, v131, v134
	v_cvt_pk_bf16_f32 v123, v137, v135
	global_store_dwordx4 v[124:125], v[120:123], off
	global_load_dwordx4 v[120:123], v[126:127], off nt
	v_mul_f32_e32 v126, v132, v132
	v_mul_f32_e32 v127, v133, v133
	v_mul_f32_e32 v132, v134, v134
	v_mul_f32_e32 v133, v135, v135
	v_fmac_f32_e32 v126, v140, v140
	v_fmac_f32_e32 v127, v141, v141
	v_fmac_f32_e32 v132, v131, v131
	v_fmac_f32_e32 v133, v137, v137
	v_add_f32_e32 v126, v126, v127
	v_add_f32_e32 v127, v132, v133
	v_add_f32_e32 v126, v126, v127
	s_waitcnt vmcnt(0)
	v_lshlrev_b32_e32 v127, 16, v120
	v_and_b32_e32 v120, 0xffff0000, v120
	v_lshlrev_b32_e32 v131, 16, v121
	v_and_b32_e32 v121, 0xffff0000, v121
	v_lshlrev_b32_e32 v132, 16, v122
	v_and_b32_e32 v122, 0xffff0000, v122
	v_lshlrev_b32_e32 v133, 16, v123
	v_and_b32_e32 v123, 0xffff0000, v123
	v_mul_f32_e32 v117, v117, v120
	v_mul_f32_e32 v119, v119, v121
	v_mul_f32_e32 v121, v113, v122
	v_mul_f32_e32 v123, v115, v123
	v_mul_f32_e32 v116, v116, v127
	v_mul_f32_e32 v118, v118, v131
	v_mul_f32_e32 v120, v112, v132
	v_mul_f32_e32 v122, v114, v133
	v_mul_f32_e32 v112, v117, v117
	v_mul_f32_e32 v113, v119, v119
	v_mul_f32_e32 v114, v121, v121
	v_mul_f32_e32 v115, v123, v123
	v_fmac_f32_e32 v112, v116, v116
	v_fmac_f32_e32 v113, v118, v118
	v_fmac_f32_e32 v114, v120, v120
	v_fmac_f32_e32 v115, v122, v122
	v_add_f32_e32 v112, v112, v113
	v_add_f32_e32 v113, v114, v115
	v_add_f32_e32 v112, v112, v113
	v_add_f32_e32 v112, v126, v112
	ds_bpermute_b32 v113, v136, v112
	v_cvt_pk_bf16_f32 v114, v116, v117
	v_cvt_pk_bf16_f32 v115, v118, v119
	v_cvt_pk_bf16_f32 v116, v120, v121
	v_cvt_pk_bf16_f32 v117, v122, v123
	s_waitcnt lgkmcnt(0)
	v_add_f32_e32 v112, v112, v113
	ds_bpermute_b32 v113, v130, v112
	global_store_dwordx4 v[124:125], v[114:117], off offset:256
	s_and_saveexec_b64 s[52:53], s[4:5]
	s_cbranch_execz .LBB0_642
	v_lshl_add_u64 v[114:115], s[18:19], 0, v[128:129]
	v_lshl_add_u64 v[114:115], s[50:51], 2, v[114:115]
	s_lshl_b32 s20, s66, 2
	v_lshl_add_u64 v[114:115], v[114:115], 0, s[20:21]
	s_waitcnt lgkmcnt(0)
	v_add_f32_e32 v112, v112, v113
	global_store_dword v[114:115], v112, off
.LBB0_642:
	s_or_b64 exec, exec, s[52:53]
	v_or_b32_e32 v118, 32, v166
	v_ashrrev_i32_e32 v119, 31, v118
	s_waitcnt lgkmcnt(0)
	v_lshlrev_b64 v[112:113], 5, v[118:119]
	v_lshl_add_u64 v[114:115], v[168:169], 0, v[112:113]
	v_lshl_add_u64 v[114:115], v[114:115], 0, v[152:153]
	global_load_dwordx4 v[114:117], v[114:115], off nt
	v_pk_add_f32 v[110:111], v[110:111], v[70:71]
	v_pk_add_f32 v[108:109], v[108:109], v[68:69]
	v_pk_add_f32 v[106:107], v[106:107], v[66:67]
	v_pk_add_f32 v[104:105], v[104:105], v[64:65]
	v_mul_f32_e32 v108, 0xbfb8aa3b, v108
	v_mul_f32_e32 v109, 0xbfb8aa3b, v109
	v_mul_f32_e32 v110, 0xbfb8aa3b, v110
	v_mul_f32_e32 v111, 0xbfb8aa3b, v111
	v_mul_f32_e32 v120, 0xbfb8aa3b, v104
	v_mul_f32_e32 v121, 0xbfb8aa3b, v105
	v_mul_f32_e32 v106, 0xbfb8aa3b, v106
	v_mul_f32_e32 v107, 0xbfb8aa3b, v107
	v_lshlrev_b64 v[104:105], 11, v[118:119]
	v_exp_f32_e32 v118, v108
	v_exp_f32_e32 v119, v109
	v_exp_f32_e32 v122, v110
	v_exp_f32_e32 v123, v111
	v_exp_f32_e32 v120, v120
	v_exp_f32_e32 v121, v121
	v_exp_f32_e32 v124, v106
	v_exp_f32_e32 v125, v107
	v_lshl_add_u64 v[104:105], s[0:1], 0, v[104:105]
	v_lshl_add_u64 v[106:107], v[170:171], 0, v[112:113]
	v_lshl_add_u64 v[108:109], v[164:165], 1, v[104:105]
	v_lshl_add_u64 v[110:111], v[106:107], 0, v[152:153]
	v_add_f32_e32 v104, 1.0, v118
	v_add_f32_e32 v105, 1.0, v119
	v_add_f32_e32 v106, 1.0, v122
	v_add_f32_e32 v107, 1.0, v123
	v_add_f32_e32 v118, 1.0, v120
	v_add_f32_e32 v119, 1.0, v121
	v_add_f32_e32 v120, 1.0, v124
	v_add_f32_e32 v121, 1.0, v125
	v_rcp_f32_e32 v104, v104
	v_rcp_f32_e32 v105, v105
	v_rcp_f32_e32 v106, v106
	v_rcp_f32_e32 v107, v107
	v_rcp_f32_e32 v118, v118
	v_rcp_f32_e32 v119, v119
	v_rcp_f32_e32 v120, v120
	v_rcp_f32_e32 v121, v121
	v_pk_add_f32 v[102:103], v[102:103], v[62:63]
	v_pk_add_f32 v[100:101], v[100:101], v[60:61]
	v_pk_add_f32 v[98:99], v[98:99], v[58:59]
	v_pk_add_f32 v[96:97], v[96:97], v[56:57]
	v_mul_f32_e32 v101, 0xbfb8aa3b, v101
	v_mul_f32_e32 v103, 0xbfb8aa3b, v103
	v_mul_f32_e32 v97, 0xbfb8aa3b, v97
	v_mul_f32_e32 v99, 0xbfb8aa3b, v99
	v_mul_f32_e32 v100, 0xbfb8aa3b, v100
	v_mul_f32_e32 v102, 0xbfb8aa3b, v102
	v_mul_f32_e32 v96, 0xbfb8aa3b, v96
	v_mul_f32_e32 v98, 0xbfb8aa3b, v98
	v_exp_f32_e32 v101, v101
	v_exp_f32_e32 v103, v103
	v_exp_f32_e32 v97, v97
	v_exp_f32_e32 v99, v99
	v_exp_f32_e32 v100, v100
	v_exp_f32_e32 v102, v102
	v_exp_f32_e32 v96, v96
	v_exp_f32_e32 v98, v98
	v_add_f32_e32 v101, 1.0, v101
	v_add_f32_e32 v103, 1.0, v103
	v_add_f32_e32 v97, 1.0, v97
	v_add_f32_e32 v99, 1.0, v99
	v_add_f32_e32 v100, 1.0, v100
	v_add_f32_e32 v102, 1.0, v102
	v_add_f32_e32 v96, 1.0, v96
	v_add_f32_e32 v98, 1.0, v98
	v_rcp_f32_e32 v101, v101
	v_rcp_f32_e32 v103, v103
	v_rcp_f32_e32 v97, v97
	v_rcp_f32_e32 v99, v99
	v_rcp_f32_e32 v100, v100
	v_rcp_f32_e32 v102, v102
	v_rcp_f32_e32 v96, v96
	v_rcp_f32_e32 v98, v98
	s_waitcnt vmcnt(0)
	v_lshlrev_b32_e32 v122, 16, v114
	v_and_b32_e32 v114, 0xffff0000, v114
	v_lshlrev_b32_e32 v123, 16, v115
	v_and_b32_e32 v115, 0xffff0000, v115
	v_lshlrev_b32_e32 v124, 16, v116
	v_and_b32_e32 v116, 0xffff0000, v116
	v_lshlrev_b32_e32 v125, 16, v117
	v_and_b32_e32 v117, 0xffff0000, v117
	v_mul_f32_e32 v122, v104, v122
	v_mul_f32_e32 v114, v105, v114
	v_mul_f32_e32 v123, v106, v123
	v_mul_f32_e32 v115, v107, v115
	v_mul_f32_e32 v118, v118, v124
	v_mul_f32_e32 v116, v119, v116
	v_mul_f32_e32 v119, v120, v125
	v_mul_f32_e32 v117, v121, v117
	v_cvt_pk_bf16_f32 v104, v122, v114
	v_cvt_pk_bf16_f32 v105, v123, v115
	v_cvt_pk_bf16_f32 v106, v118, v116
	v_cvt_pk_bf16_f32 v107, v119, v117
	global_store_dwordx4 v[108:109], v[104:107], off
	global_load_dwordx4 v[104:107], v[110:111], off nt
	v_mul_f32_e32 v110, v114, v114
	v_mul_f32_e32 v111, v115, v115
	v_mul_f32_e32 v114, v116, v116
	v_mul_f32_e32 v115, v117, v117
	v_fmac_f32_e32 v110, v122, v122
	v_fmac_f32_e32 v111, v123, v123
	v_fmac_f32_e32 v114, v118, v118
	v_fmac_f32_e32 v115, v119, v119
	v_add_f32_e32 v110, v110, v111
	v_add_f32_e32 v111, v114, v115
	v_add_f32_e32 v110, v110, v111
	s_waitcnt vmcnt(0)
	v_lshlrev_b32_e32 v111, 16, v104
	v_and_b32_e32 v104, 0xffff0000, v104
	v_lshlrev_b32_e32 v114, 16, v105
	v_and_b32_e32 v105, 0xffff0000, v105
	v_lshlrev_b32_e32 v115, 16, v106
	v_and_b32_e32 v106, 0xffff0000, v106
	v_lshlrev_b32_e32 v116, 16, v107
	v_and_b32_e32 v107, 0xffff0000, v107
	v_mul_f32_e32 v101, v101, v104
	v_mul_f32_e32 v103, v103, v105
	v_mul_f32_e32 v105, v97, v106
	v_mul_f32_e32 v107, v99, v107
	v_mul_f32_e32 v100, v100, v111
	v_mul_f32_e32 v102, v102, v114
	v_mul_f32_e32 v104, v96, v115
	v_mul_f32_e32 v106, v98, v116
	v_mul_f32_e32 v96, v101, v101
	v_mul_f32_e32 v97, v103, v103
	v_mul_f32_e32 v98, v105, v105
	v_mul_f32_e32 v99, v107, v107
	v_fmac_f32_e32 v96, v100, v100
	v_fmac_f32_e32 v97, v102, v102
	v_fmac_f32_e32 v98, v104, v104
	v_fmac_f32_e32 v99, v106, v106
	v_add_f32_e32 v96, v96, v97
	v_add_f32_e32 v97, v98, v99
	v_add_f32_e32 v96, v96, v97
	v_add_f32_e32 v96, v110, v96
	ds_bpermute_b32 v97, v136, v96
	v_cvt_pk_bf16_f32 v98, v100, v101
	v_cvt_pk_bf16_f32 v99, v102, v103
	v_cvt_pk_bf16_f32 v100, v104, v105
	v_cvt_pk_bf16_f32 v101, v106, v107
	s_waitcnt lgkmcnt(0)
	v_add_f32_e32 v96, v96, v97
	ds_bpermute_b32 v97, v130, v96
	global_store_dwordx4 v[108:109], v[98:101], off offset:256
	s_and_saveexec_b64 s[52:53], s[4:5]
	s_cbranch_execz .LBB0_644
	v_lshl_add_u64 v[98:99], s[18:19], 0, v[112:113]
	v_lshl_add_u64 v[98:99], s[50:51], 2, v[98:99]
	s_lshl_b32 s20, s66, 2
	v_lshl_add_u64 v[98:99], v[98:99], 0, s[20:21]
	s_waitcnt lgkmcnt(0)
	v_add_f32_e32 v96, v96, v97
	global_store_dword v[98:99], v96, off
.LBB0_644:
	s_or_b64 exec, exec, s[52:53]
	v_or_b32_e32 v102, 48, v166
	v_ashrrev_i32_e32 v103, 31, v102
	s_waitcnt lgkmcnt(0)
	v_lshlrev_b64 v[96:97], 5, v[102:103]
	v_lshl_add_u64 v[98:99], v[168:169], 0, v[96:97]
	v_lshl_add_u64 v[98:99], v[98:99], 0, v[152:153]
	global_load_dwordx4 v[98:101], v[98:99], off nt
	v_pk_add_f32 v[94:95], v[94:95], v[70:71]
	v_pk_add_f32 v[92:93], v[92:93], v[68:69]
	v_pk_add_f32 v[90:91], v[90:91], v[66:67]
	v_pk_add_f32 v[88:89], v[88:89], v[64:65]
	v_mul_f32_e32 v92, 0xbfb8aa3b, v92
	v_mul_f32_e32 v93, 0xbfb8aa3b, v93
	v_mul_f32_e32 v94, 0xbfb8aa3b, v94
	v_mul_f32_e32 v95, 0xbfb8aa3b, v95
	v_mul_f32_e32 v104, 0xbfb8aa3b, v88
	v_mul_f32_e32 v105, 0xbfb8aa3b, v89
	v_mul_f32_e32 v90, 0xbfb8aa3b, v90
	v_mul_f32_e32 v91, 0xbfb8aa3b, v91
	v_lshlrev_b64 v[88:89], 11, v[102:103]
	v_exp_f32_e32 v102, v92
	v_exp_f32_e32 v103, v93
	v_exp_f32_e32 v106, v94
	v_exp_f32_e32 v107, v95
	v_exp_f32_e32 v104, v104
	v_exp_f32_e32 v105, v105
	v_exp_f32_e32 v108, v90
	v_exp_f32_e32 v109, v91
	v_lshl_add_u64 v[88:89], s[0:1], 0, v[88:89]
	v_lshl_add_u64 v[90:91], v[170:171], 0, v[96:97]
	v_lshl_add_u64 v[92:93], v[164:165], 1, v[88:89]
	v_lshl_add_u64 v[94:95], v[90:91], 0, v[152:153]
	v_add_f32_e32 v88, 1.0, v102
	v_add_f32_e32 v89, 1.0, v103
	v_add_f32_e32 v90, 1.0, v106
	v_add_f32_e32 v91, 1.0, v107
	v_add_f32_e32 v102, 1.0, v104
	v_add_f32_e32 v103, 1.0, v105
	v_add_f32_e32 v104, 1.0, v108
	v_add_f32_e32 v105, 1.0, v109
	v_rcp_f32_e32 v88, v88
	v_rcp_f32_e32 v89, v89
	v_rcp_f32_e32 v90, v90
	v_rcp_f32_e32 v91, v91
	v_rcp_f32_e32 v102, v102
	v_rcp_f32_e32 v103, v103
	v_rcp_f32_e32 v104, v104
	v_rcp_f32_e32 v105, v105
	v_pk_add_f32 v[86:87], v[86:87], v[62:63]
	v_pk_add_f32 v[84:85], v[84:85], v[60:61]
	v_pk_add_f32 v[82:83], v[82:83], v[58:59]
	v_pk_add_f32 v[80:81], v[80:81], v[56:57]
	v_mul_f32_e32 v85, 0xbfb8aa3b, v85
	v_mul_f32_e32 v87, 0xbfb8aa3b, v87
	v_mul_f32_e32 v81, 0xbfb8aa3b, v81
	v_mul_f32_e32 v83, 0xbfb8aa3b, v83
	v_mul_f32_e32 v84, 0xbfb8aa3b, v84
	v_mul_f32_e32 v86, 0xbfb8aa3b, v86
	v_mul_f32_e32 v80, 0xbfb8aa3b, v80
	v_mul_f32_e32 v82, 0xbfb8aa3b, v82
	v_exp_f32_e32 v85, v85
	v_exp_f32_e32 v87, v87
	v_exp_f32_e32 v81, v81
	v_exp_f32_e32 v83, v83
	v_exp_f32_e32 v84, v84
	v_exp_f32_e32 v86, v86
	v_exp_f32_e32 v80, v80
	v_exp_f32_e32 v82, v82
	v_add_f32_e32 v85, 1.0, v85
	v_add_f32_e32 v87, 1.0, v87
	v_add_f32_e32 v81, 1.0, v81
	v_add_f32_e32 v83, 1.0, v83
	v_add_f32_e32 v84, 1.0, v84
	v_add_f32_e32 v86, 1.0, v86
	v_add_f32_e32 v80, 1.0, v80
	v_add_f32_e32 v82, 1.0, v82
	v_rcp_f32_e32 v85, v85
	v_rcp_f32_e32 v87, v87
	v_rcp_f32_e32 v81, v81
	v_rcp_f32_e32 v83, v83
	v_rcp_f32_e32 v84, v84
	v_rcp_f32_e32 v86, v86
	v_rcp_f32_e32 v80, v80
	v_rcp_f32_e32 v82, v82
	s_waitcnt vmcnt(0)
	v_lshlrev_b32_e32 v106, 16, v98
	v_and_b32_e32 v98, 0xffff0000, v98
	v_lshlrev_b32_e32 v107, 16, v99
	v_and_b32_e32 v99, 0xffff0000, v99
	v_lshlrev_b32_e32 v108, 16, v100
	v_and_b32_e32 v100, 0xffff0000, v100
	v_lshlrev_b32_e32 v109, 16, v101
	v_and_b32_e32 v101, 0xffff0000, v101
	v_mul_f32_e32 v106, v88, v106
	v_mul_f32_e32 v98, v89, v98
	v_mul_f32_e32 v107, v90, v107
	v_mul_f32_e32 v99, v91, v99
	v_mul_f32_e32 v102, v102, v108
	v_mul_f32_e32 v100, v103, v100
	v_mul_f32_e32 v103, v104, v109
	v_mul_f32_e32 v101, v105, v101
	v_cvt_pk_bf16_f32 v88, v106, v98
	v_cvt_pk_bf16_f32 v89, v107, v99
	v_cvt_pk_bf16_f32 v90, v102, v100
	v_cvt_pk_bf16_f32 v91, v103, v101
	global_store_dwordx4 v[92:93], v[88:91], off
	global_load_dwordx4 v[88:91], v[94:95], off nt
	v_mul_f32_e32 v94, v98, v98
	v_mul_f32_e32 v95, v99, v99
	v_mul_f32_e32 v98, v100, v100
	v_mul_f32_e32 v99, v101, v101
	v_fmac_f32_e32 v94, v106, v106
	v_fmac_f32_e32 v95, v107, v107
	v_fmac_f32_e32 v98, v102, v102
	v_fmac_f32_e32 v99, v103, v103
	v_add_f32_e32 v94, v94, v95
	v_add_f32_e32 v95, v98, v99
	v_add_f32_e32 v94, v94, v95
	s_waitcnt vmcnt(0)
	v_lshlrev_b32_e32 v95, 16, v88
	v_and_b32_e32 v88, 0xffff0000, v88
	v_lshlrev_b32_e32 v98, 16, v89
	v_and_b32_e32 v89, 0xffff0000, v89
	v_lshlrev_b32_e32 v99, 16, v90
	v_and_b32_e32 v90, 0xffff0000, v90
	v_lshlrev_b32_e32 v100, 16, v91
	v_and_b32_e32 v91, 0xffff0000, v91
	v_mul_f32_e32 v85, v85, v88
	v_mul_f32_e32 v87, v87, v89
	v_mul_f32_e32 v89, v81, v90
	v_mul_f32_e32 v91, v83, v91
	v_mul_f32_e32 v84, v84, v95
	v_mul_f32_e32 v86, v86, v98
	v_mul_f32_e32 v88, v80, v99
	v_mul_f32_e32 v90, v82, v100
	v_mul_f32_e32 v80, v85, v85
	v_mul_f32_e32 v81, v87, v87
	v_mul_f32_e32 v82, v89, v89
	v_mul_f32_e32 v83, v91, v91
	v_fmac_f32_e32 v80, v84, v84
	v_fmac_f32_e32 v81, v86, v86
	v_fmac_f32_e32 v82, v88, v88
	v_fmac_f32_e32 v83, v90, v90
	v_add_f32_e32 v80, v80, v81
	v_add_f32_e32 v81, v82, v83
	v_add_f32_e32 v80, v80, v81
	v_add_f32_e32 v80, v94, v80
	ds_bpermute_b32 v81, v136, v80
	v_cvt_pk_bf16_f32 v82, v84, v85
	v_cvt_pk_bf16_f32 v83, v86, v87
	v_cvt_pk_bf16_f32 v84, v88, v89
	v_cvt_pk_bf16_f32 v85, v90, v91
	s_waitcnt lgkmcnt(0)
	v_add_f32_e32 v80, v80, v81
	ds_bpermute_b32 v81, v130, v80
	global_store_dwordx4 v[92:93], v[82:85], off offset:256
	s_and_saveexec_b64 s[52:53], s[4:5]
	s_cbranch_execz .LBB0_646
	v_lshl_add_u64 v[82:83], s[18:19], 0, v[96:97]
	v_lshl_add_u64 v[82:83], s[50:51], 2, v[82:83]
	s_lshl_b32 s20, s66, 2
	v_lshl_add_u64 v[82:83], v[82:83], 0, s[20:21]
	s_waitcnt lgkmcnt(0)
	v_add_f32_e32 v80, v80, v81
	global_store_dword v[82:83], v80, off
.LBB0_646:
	s_or_b64 exec, exec, s[52:53]
	v_add_u32_e32 v86, 0x80, v166
	v_ashrrev_i32_e32 v87, 31, v86
	s_waitcnt lgkmcnt(0)
	v_lshlrev_b64 v[80:81], 5, v[86:87]
	v_lshl_add_u64 v[82:83], v[168:169], 0, v[80:81]
	v_lshl_add_u64 v[82:83], v[82:83], 0, v[152:153]
	global_load_dwordx4 v[82:85], v[82:83], off nt
	v_pk_add_f32 v[78:79], v[78:79], v[70:71]
	v_pk_add_f32 v[76:77], v[76:77], v[68:69]
	v_pk_add_f32 v[74:75], v[74:75], v[66:67]
	v_pk_add_f32 v[72:73], v[72:73], v[64:65]
	v_mul_f32_e32 v76, 0xbfb8aa3b, v76
	v_mul_f32_e32 v77, 0xbfb8aa3b, v77
	v_mul_f32_e32 v78, 0xbfb8aa3b, v78
	v_mul_f32_e32 v79, 0xbfb8aa3b, v79
	v_mul_f32_e32 v88, 0xbfb8aa3b, v72
	v_mul_f32_e32 v89, 0xbfb8aa3b, v73
	v_mul_f32_e32 v74, 0xbfb8aa3b, v74
	v_mul_f32_e32 v75, 0xbfb8aa3b, v75
	v_lshlrev_b64 v[72:73], 11, v[86:87]
	v_exp_f32_e32 v86, v76
	v_exp_f32_e32 v87, v77
	v_exp_f32_e32 v90, v78
	v_exp_f32_e32 v91, v79
	v_exp_f32_e32 v88, v88
	v_exp_f32_e32 v89, v89
	v_exp_f32_e32 v92, v74
	v_exp_f32_e32 v93, v75
	v_lshl_add_u64 v[72:73], s[0:1], 0, v[72:73]
	v_lshl_add_u64 v[74:75], v[170:171], 0, v[80:81]
	v_lshl_add_u64 v[76:77], v[164:165], 1, v[72:73]
	v_lshl_add_u64 v[78:79], v[74:75], 0, v[152:153]
	v_add_f32_e32 v72, 1.0, v86
	v_add_f32_e32 v73, 1.0, v87
	v_add_f32_e32 v74, 1.0, v90
	v_add_f32_e32 v75, 1.0, v91
	v_add_f32_e32 v86, 1.0, v88
	v_add_f32_e32 v87, 1.0, v89
	v_add_f32_e32 v88, 1.0, v92
	v_add_f32_e32 v89, 1.0, v93
	v_rcp_f32_e32 v72, v72
	v_rcp_f32_e32 v73, v73
	v_rcp_f32_e32 v74, v74
	v_rcp_f32_e32 v75, v75
	v_rcp_f32_e32 v86, v86
	v_rcp_f32_e32 v87, v87
	v_rcp_f32_e32 v88, v88
	v_rcp_f32_e32 v89, v89
	v_pk_add_f32 v[54:55], v[54:55], v[62:63]
	v_pk_add_f32 v[52:53], v[52:53], v[60:61]
	v_pk_add_f32 v[50:51], v[50:51], v[58:59]
	v_pk_add_f32 v[48:49], v[48:49], v[56:57]
	v_mul_f32_e32 v53, 0xbfb8aa3b, v53
	v_mul_f32_e32 v55, 0xbfb8aa3b, v55
	v_mul_f32_e32 v49, 0xbfb8aa3b, v49
	v_mul_f32_e32 v51, 0xbfb8aa3b, v51
	v_mul_f32_e32 v52, 0xbfb8aa3b, v52
	v_mul_f32_e32 v54, 0xbfb8aa3b, v54
	v_mul_f32_e32 v48, 0xbfb8aa3b, v48
	v_mul_f32_e32 v50, 0xbfb8aa3b, v50
	v_exp_f32_e32 v53, v53
	v_exp_f32_e32 v55, v55
	v_exp_f32_e32 v49, v49
	v_exp_f32_e32 v51, v51
	v_exp_f32_e32 v52, v52
	v_exp_f32_e32 v54, v54
	v_exp_f32_e32 v48, v48
	v_exp_f32_e32 v50, v50
	v_add_f32_e32 v53, 1.0, v53
	v_add_f32_e32 v55, 1.0, v55
	v_add_f32_e32 v49, 1.0, v49
	v_add_f32_e32 v51, 1.0, v51
	v_add_f32_e32 v52, 1.0, v52
	v_add_f32_e32 v54, 1.0, v54
	v_add_f32_e32 v48, 1.0, v48
	v_add_f32_e32 v50, 1.0, v50
	v_rcp_f32_e32 v53, v53
	v_rcp_f32_e32 v55, v55
	v_rcp_f32_e32 v49, v49
	v_rcp_f32_e32 v51, v51
	v_rcp_f32_e32 v52, v52
	v_rcp_f32_e32 v54, v54
	v_rcp_f32_e32 v48, v48
	v_rcp_f32_e32 v50, v50
	s_waitcnt vmcnt(0)
	v_lshlrev_b32_e32 v90, 16, v82
	v_and_b32_e32 v82, 0xffff0000, v82
	v_lshlrev_b32_e32 v91, 16, v83
	v_and_b32_e32 v83, 0xffff0000, v83
	v_lshlrev_b32_e32 v92, 16, v84
	v_and_b32_e32 v84, 0xffff0000, v84
	v_lshlrev_b32_e32 v93, 16, v85
	v_and_b32_e32 v85, 0xffff0000, v85
	v_mul_f32_e32 v90, v72, v90
	v_mul_f32_e32 v82, v73, v82
	v_mul_f32_e32 v91, v74, v91
	v_mul_f32_e32 v83, v75, v83
	v_mul_f32_e32 v86, v86, v92
	v_mul_f32_e32 v84, v87, v84
	v_mul_f32_e32 v87, v88, v93
	v_mul_f32_e32 v85, v89, v85
	v_cvt_pk_bf16_f32 v72, v90, v82
	v_cvt_pk_bf16_f32 v73, v91, v83
	v_cvt_pk_bf16_f32 v74, v86, v84
	v_cvt_pk_bf16_f32 v75, v87, v85
	global_store_dwordx4 v[76:77], v[72:75], off
	global_load_dwordx4 v[72:75], v[78:79], off nt
	v_mul_f32_e32 v78, v82, v82
	v_mul_f32_e32 v79, v83, v83
	v_mul_f32_e32 v82, v84, v84
	v_mul_f32_e32 v83, v85, v85
	v_fmac_f32_e32 v78, v90, v90
	v_fmac_f32_e32 v79, v91, v91
	v_fmac_f32_e32 v82, v86, v86
	v_fmac_f32_e32 v83, v87, v87
	v_add_f32_e32 v78, v78, v79
	v_add_f32_e32 v79, v82, v83
	v_add_f32_e32 v78, v78, v79
	s_waitcnt vmcnt(0)
	v_lshlrev_b32_e32 v79, 16, v72
	v_and_b32_e32 v72, 0xffff0000, v72
	v_lshlrev_b32_e32 v82, 16, v73
	v_and_b32_e32 v73, 0xffff0000, v73
	v_lshlrev_b32_e32 v83, 16, v74
	v_and_b32_e32 v74, 0xffff0000, v74
	v_lshlrev_b32_e32 v84, 16, v75
	v_and_b32_e32 v75, 0xffff0000, v75
	v_mul_f32_e32 v53, v53, v72
	v_mul_f32_e32 v55, v55, v73
	v_mul_f32_e32 v73, v49, v74
	v_mul_f32_e32 v75, v51, v75
	v_mul_f32_e32 v52, v52, v79
	v_mul_f32_e32 v54, v54, v82
	v_mul_f32_e32 v72, v48, v83
	v_mul_f32_e32 v74, v50, v84
	v_mul_f32_e32 v48, v53, v53
	v_mul_f32_e32 v49, v55, v55
	v_mul_f32_e32 v50, v73, v73
	v_mul_f32_e32 v51, v75, v75
	v_fmac_f32_e32 v48, v52, v52
	v_fmac_f32_e32 v49, v54, v54
	v_fmac_f32_e32 v50, v72, v72
	v_fmac_f32_e32 v51, v74, v74
	v_add_f32_e32 v48, v48, v49
	v_add_f32_e32 v49, v50, v51
	v_add_f32_e32 v48, v48, v49
	v_add_f32_e32 v48, v78, v48
	ds_bpermute_b32 v49, v136, v48
	v_cvt_pk_bf16_f32 v50, v52, v53
	v_cvt_pk_bf16_f32 v51, v54, v55
	v_cvt_pk_bf16_f32 v52, v72, v73
	v_cvt_pk_bf16_f32 v53, v74, v75
	s_waitcnt lgkmcnt(0)
	v_add_f32_e32 v48, v48, v49
	ds_bpermute_b32 v49, v130, v48
	global_store_dwordx4 v[76:77], v[50:53], off offset:256
	s_and_saveexec_b64 s[52:53], s[4:5]
	s_cbranch_execz .LBB0_648
	v_lshl_add_u64 v[50:51], s[18:19], 0, v[80:81]
	v_lshl_add_u64 v[50:51], s[50:51], 2, v[50:51]
	s_lshl_b32 s20, s66, 2
	v_lshl_add_u64 v[50:51], v[50:51], 0, s[20:21]
	s_waitcnt lgkmcnt(0)
	v_add_f32_e32 v48, v48, v49
	global_store_dword v[50:51], v48, off
.LBB0_648:
	s_or_b64 exec, exec, s[52:53]
	v_add_u32_e32 v54, 0x90, v166
	v_ashrrev_i32_e32 v55, 31, v54
	s_waitcnt lgkmcnt(0)
	v_lshlrev_b64 v[48:49], 5, v[54:55]
	v_lshl_add_u64 v[50:51], v[168:169], 0, v[48:49]
	v_lshl_add_u64 v[50:51], v[50:51], 0, v[152:153]
	global_load_dwordx4 v[50:53], v[50:51], off nt
	v_pk_add_f32 v[46:47], v[46:47], v[70:71]
	v_pk_add_f32 v[44:45], v[44:45], v[68:69]
	v_pk_add_f32 v[42:43], v[42:43], v[66:67]
	v_pk_add_f32 v[40:41], v[40:41], v[64:65]
	v_mul_f32_e32 v44, 0xbfb8aa3b, v44
	v_mul_f32_e32 v45, 0xbfb8aa3b, v45
	v_mul_f32_e32 v46, 0xbfb8aa3b, v46
	v_mul_f32_e32 v47, 0xbfb8aa3b, v47
	v_mul_f32_e32 v72, 0xbfb8aa3b, v40
	v_mul_f32_e32 v73, 0xbfb8aa3b, v41
	v_mul_f32_e32 v42, 0xbfb8aa3b, v42
	v_mul_f32_e32 v43, 0xbfb8aa3b, v43
	v_lshlrev_b64 v[40:41], 11, v[54:55]
	v_exp_f32_e32 v54, v44
	v_exp_f32_e32 v55, v45
	v_exp_f32_e32 v74, v46
	v_exp_f32_e32 v75, v47
	v_exp_f32_e32 v72, v72
	v_exp_f32_e32 v73, v73
	v_exp_f32_e32 v76, v42
	v_exp_f32_e32 v77, v43
	v_lshl_add_u64 v[40:41], s[0:1], 0, v[40:41]
	v_lshl_add_u64 v[42:43], v[170:171], 0, v[48:49]
	v_lshl_add_u64 v[44:45], v[164:165], 1, v[40:41]
	v_lshl_add_u64 v[46:47], v[42:43], 0, v[152:153]
	v_add_f32_e32 v40, 1.0, v54
	v_add_f32_e32 v41, 1.0, v55
	v_add_f32_e32 v42, 1.0, v74
	v_add_f32_e32 v43, 1.0, v75
	v_add_f32_e32 v54, 1.0, v72
	v_add_f32_e32 v55, 1.0, v73
	v_add_f32_e32 v72, 1.0, v76
	v_add_f32_e32 v73, 1.0, v77
	v_rcp_f32_e32 v40, v40
	v_rcp_f32_e32 v41, v41
	v_rcp_f32_e32 v42, v42
	v_rcp_f32_e32 v43, v43
	v_rcp_f32_e32 v54, v54
	v_rcp_f32_e32 v55, v55
	v_rcp_f32_e32 v72, v72
	v_rcp_f32_e32 v73, v73
	v_pk_add_f32 v[38:39], v[38:39], v[62:63]
	v_pk_add_f32 v[36:37], v[36:37], v[60:61]
	v_pk_add_f32 v[34:35], v[34:35], v[58:59]
	v_pk_add_f32 v[32:33], v[32:33], v[56:57]
	v_mul_f32_e32 v37, 0xbfb8aa3b, v37
	v_mul_f32_e32 v39, 0xbfb8aa3b, v39
	v_mul_f32_e32 v33, 0xbfb8aa3b, v33
	v_mul_f32_e32 v35, 0xbfb8aa3b, v35
	v_mul_f32_e32 v36, 0xbfb8aa3b, v36
	v_mul_f32_e32 v38, 0xbfb8aa3b, v38
	v_mul_f32_e32 v32, 0xbfb8aa3b, v32
	v_mul_f32_e32 v34, 0xbfb8aa3b, v34
	v_exp_f32_e32 v37, v37
	v_exp_f32_e32 v39, v39
	v_exp_f32_e32 v33, v33
	v_exp_f32_e32 v35, v35
	v_exp_f32_e32 v36, v36
	v_exp_f32_e32 v38, v38
	v_exp_f32_e32 v32, v32
	v_exp_f32_e32 v34, v34
	v_add_f32_e32 v37, 1.0, v37
	v_add_f32_e32 v39, 1.0, v39
	v_add_f32_e32 v33, 1.0, v33
	v_add_f32_e32 v35, 1.0, v35
	v_add_f32_e32 v36, 1.0, v36
	v_add_f32_e32 v38, 1.0, v38
	v_add_f32_e32 v32, 1.0, v32
	v_add_f32_e32 v34, 1.0, v34
	v_rcp_f32_e32 v37, v37
	v_rcp_f32_e32 v39, v39
	v_rcp_f32_e32 v33, v33
	v_rcp_f32_e32 v35, v35
	v_rcp_f32_e32 v36, v36
	v_rcp_f32_e32 v38, v38
	v_rcp_f32_e32 v32, v32
	v_rcp_f32_e32 v34, v34
	s_waitcnt vmcnt(0)
	v_lshlrev_b32_e32 v74, 16, v50
	v_and_b32_e32 v50, 0xffff0000, v50
	v_lshlrev_b32_e32 v75, 16, v51
	v_and_b32_e32 v51, 0xffff0000, v51
	v_lshlrev_b32_e32 v76, 16, v52
	v_and_b32_e32 v52, 0xffff0000, v52
	v_lshlrev_b32_e32 v77, 16, v53
	v_and_b32_e32 v53, 0xffff0000, v53
	v_mul_f32_e32 v74, v40, v74
	v_mul_f32_e32 v50, v41, v50
	v_mul_f32_e32 v75, v42, v75
	v_mul_f32_e32 v51, v43, v51
	v_mul_f32_e32 v54, v54, v76
	v_mul_f32_e32 v52, v55, v52
	v_mul_f32_e32 v55, v72, v77
	v_mul_f32_e32 v53, v73, v53
	v_cvt_pk_bf16_f32 v40, v74, v50
	v_cvt_pk_bf16_f32 v41, v75, v51
	v_cvt_pk_bf16_f32 v42, v54, v52
	v_cvt_pk_bf16_f32 v43, v55, v53
	global_store_dwordx4 v[44:45], v[40:43], off
	global_load_dwordx4 v[40:43], v[46:47], off nt
	v_mul_f32_e32 v46, v50, v50
	v_mul_f32_e32 v47, v51, v51
	v_mul_f32_e32 v50, v52, v52
	v_mul_f32_e32 v51, v53, v53
	v_fmac_f32_e32 v46, v74, v74
	v_fmac_f32_e32 v47, v75, v75
	v_fmac_f32_e32 v50, v54, v54
	v_fmac_f32_e32 v51, v55, v55
	v_add_f32_e32 v46, v46, v47
	v_add_f32_e32 v47, v50, v51
	v_add_f32_e32 v46, v46, v47
	s_waitcnt vmcnt(0)
	v_lshlrev_b32_e32 v47, 16, v40
	v_and_b32_e32 v40, 0xffff0000, v40
	v_lshlrev_b32_e32 v50, 16, v41
	v_and_b32_e32 v41, 0xffff0000, v41
	v_lshlrev_b32_e32 v51, 16, v42
	v_and_b32_e32 v42, 0xffff0000, v42
	v_lshlrev_b32_e32 v52, 16, v43
	v_and_b32_e32 v43, 0xffff0000, v43
	v_mul_f32_e32 v37, v37, v40
	v_mul_f32_e32 v39, v39, v41
	v_mul_f32_e32 v41, v33, v42
	v_mul_f32_e32 v43, v35, v43
	v_mul_f32_e32 v36, v36, v47
	v_mul_f32_e32 v38, v38, v50
	v_mul_f32_e32 v40, v32, v51
	v_mul_f32_e32 v42, v34, v52
	v_mul_f32_e32 v32, v37, v37
	v_mul_f32_e32 v33, v39, v39
	v_mul_f32_e32 v34, v41, v41
	v_mul_f32_e32 v35, v43, v43
	v_fmac_f32_e32 v32, v36, v36
	v_fmac_f32_e32 v33, v38, v38
	v_fmac_f32_e32 v34, v40, v40
	v_fmac_f32_e32 v35, v42, v42
	v_add_f32_e32 v32, v32, v33
	v_add_f32_e32 v33, v34, v35
	v_add_f32_e32 v32, v32, v33
	v_add_f32_e32 v32, v46, v32
	ds_bpermute_b32 v33, v136, v32
	v_cvt_pk_bf16_f32 v34, v36, v37
	v_cvt_pk_bf16_f32 v35, v38, v39
	v_cvt_pk_bf16_f32 v36, v40, v41
	v_cvt_pk_bf16_f32 v37, v42, v43
	s_waitcnt lgkmcnt(0)
	v_add_f32_e32 v32, v32, v33
	ds_bpermute_b32 v33, v130, v32
	global_store_dwordx4 v[44:45], v[34:37], off offset:256
	s_and_saveexec_b64 s[52:53], s[4:5]
	s_cbranch_execz .LBB0_650
	v_lshl_add_u64 v[34:35], s[18:19], 0, v[48:49]
	v_lshl_add_u64 v[34:35], s[50:51], 2, v[34:35]
	s_lshl_b32 s20, s66, 2
	v_lshl_add_u64 v[34:35], v[34:35], 0, s[20:21]
	s_waitcnt lgkmcnt(0)
	v_add_f32_e32 v32, v32, v33
	global_store_dword v[34:35], v32, off
.LBB0_650:
	s_or_b64 exec, exec, s[52:53]
	v_add_u32_e32 v38, 0xa0, v166
	v_ashrrev_i32_e32 v39, 31, v38
	s_waitcnt lgkmcnt(0)
	v_lshlrev_b64 v[32:33], 5, v[38:39]
	v_lshl_add_u64 v[34:35], v[168:169], 0, v[32:33]
	v_lshl_add_u64 v[34:35], v[34:35], 0, v[152:153]
	global_load_dwordx4 v[34:37], v[34:35], off nt
	v_pk_add_f32 v[30:31], v[30:31], v[70:71]
	v_pk_add_f32 v[28:29], v[28:29], v[68:69]
	v_pk_add_f32 v[26:27], v[26:27], v[66:67]
	v_pk_add_f32 v[24:25], v[24:25], v[64:65]
	v_mul_f32_e32 v28, 0xbfb8aa3b, v28
	v_mul_f32_e32 v29, 0xbfb8aa3b, v29
	v_mul_f32_e32 v30, 0xbfb8aa3b, v30
	v_mul_f32_e32 v31, 0xbfb8aa3b, v31
	v_mul_f32_e32 v40, 0xbfb8aa3b, v24
	v_mul_f32_e32 v41, 0xbfb8aa3b, v25
	v_mul_f32_e32 v26, 0xbfb8aa3b, v26
	v_mul_f32_e32 v27, 0xbfb8aa3b, v27
	v_lshlrev_b64 v[24:25], 11, v[38:39]
	v_exp_f32_e32 v38, v28
	v_exp_f32_e32 v39, v29
	v_exp_f32_e32 v42, v30
	v_exp_f32_e32 v43, v31
	v_exp_f32_e32 v40, v40
	v_exp_f32_e32 v41, v41
	v_exp_f32_e32 v44, v26
	v_exp_f32_e32 v45, v27
	v_lshl_add_u64 v[24:25], s[0:1], 0, v[24:25]
	v_lshl_add_u64 v[26:27], v[170:171], 0, v[32:33]
	v_lshl_add_u64 v[28:29], v[164:165], 1, v[24:25]
	v_lshl_add_u64 v[30:31], v[26:27], 0, v[152:153]
	v_add_f32_e32 v24, 1.0, v38
	v_add_f32_e32 v25, 1.0, v39
	v_add_f32_e32 v26, 1.0, v42
	v_add_f32_e32 v27, 1.0, v43
	v_add_f32_e32 v38, 1.0, v40
	v_add_f32_e32 v39, 1.0, v41
	v_add_f32_e32 v40, 1.0, v44
	v_add_f32_e32 v41, 1.0, v45
	v_rcp_f32_e32 v24, v24
	v_rcp_f32_e32 v25, v25
	v_rcp_f32_e32 v26, v26
	v_rcp_f32_e32 v27, v27
	v_rcp_f32_e32 v38, v38
	v_rcp_f32_e32 v39, v39
	v_rcp_f32_e32 v40, v40
	v_rcp_f32_e32 v41, v41
	v_pk_add_f32 v[22:23], v[22:23], v[62:63]
	v_pk_add_f32 v[20:21], v[20:21], v[60:61]
	v_pk_add_f32 v[18:19], v[18:19], v[58:59]
	v_pk_add_f32 v[16:17], v[16:17], v[56:57]
	v_mul_f32_e32 v21, 0xbfb8aa3b, v21
	v_mul_f32_e32 v23, 0xbfb8aa3b, v23
	v_mul_f32_e32 v17, 0xbfb8aa3b, v17
	v_mul_f32_e32 v19, 0xbfb8aa3b, v19
	v_mul_f32_e32 v20, 0xbfb8aa3b, v20
	v_mul_f32_e32 v22, 0xbfb8aa3b, v22
	v_mul_f32_e32 v16, 0xbfb8aa3b, v16
	v_mul_f32_e32 v18, 0xbfb8aa3b, v18
	v_exp_f32_e32 v21, v21
	v_exp_f32_e32 v23, v23
	v_exp_f32_e32 v17, v17
	v_exp_f32_e32 v19, v19
	v_exp_f32_e32 v20, v20
	v_exp_f32_e32 v22, v22
	v_exp_f32_e32 v16, v16
	v_exp_f32_e32 v18, v18
	v_add_f32_e32 v21, 1.0, v21
	v_add_f32_e32 v23, 1.0, v23
	v_add_f32_e32 v17, 1.0, v17
	v_add_f32_e32 v19, 1.0, v19
	v_add_f32_e32 v20, 1.0, v20
	v_add_f32_e32 v22, 1.0, v22
	v_add_f32_e32 v16, 1.0, v16
	v_add_f32_e32 v18, 1.0, v18
	v_rcp_f32_e32 v21, v21
	v_rcp_f32_e32 v23, v23
	v_rcp_f32_e32 v17, v17
	v_rcp_f32_e32 v19, v19
	v_rcp_f32_e32 v20, v20
	v_rcp_f32_e32 v22, v22
	v_rcp_f32_e32 v16, v16
	v_rcp_f32_e32 v18, v18
	s_waitcnt vmcnt(0)
	v_lshlrev_b32_e32 v42, 16, v34
	v_and_b32_e32 v34, 0xffff0000, v34
	v_lshlrev_b32_e32 v43, 16, v35
	v_and_b32_e32 v35, 0xffff0000, v35
	v_lshlrev_b32_e32 v44, 16, v36
	v_and_b32_e32 v36, 0xffff0000, v36
	v_lshlrev_b32_e32 v45, 16, v37
	v_and_b32_e32 v37, 0xffff0000, v37
	v_mul_f32_e32 v42, v24, v42
	v_mul_f32_e32 v34, v25, v34
	v_mul_f32_e32 v43, v26, v43
	v_mul_f32_e32 v35, v27, v35
	v_mul_f32_e32 v38, v38, v44
	v_mul_f32_e32 v36, v39, v36
	v_mul_f32_e32 v39, v40, v45
	v_mul_f32_e32 v37, v41, v37
	v_cvt_pk_bf16_f32 v24, v42, v34
	v_cvt_pk_bf16_f32 v25, v43, v35
	v_cvt_pk_bf16_f32 v26, v38, v36
	v_cvt_pk_bf16_f32 v27, v39, v37
	global_store_dwordx4 v[28:29], v[24:27], off
	global_load_dwordx4 v[24:27], v[30:31], off nt
	v_mul_f32_e32 v30, v34, v34
	v_mul_f32_e32 v31, v35, v35
	v_mul_f32_e32 v34, v36, v36
	v_mul_f32_e32 v35, v37, v37
	v_fmac_f32_e32 v30, v42, v42
	v_fmac_f32_e32 v31, v43, v43
	v_fmac_f32_e32 v34, v38, v38
	v_fmac_f32_e32 v35, v39, v39
	v_add_f32_e32 v30, v30, v31
	v_add_f32_e32 v31, v34, v35
	v_add_f32_e32 v30, v30, v31
	s_waitcnt vmcnt(0)
	v_lshlrev_b32_e32 v31, 16, v24
	v_and_b32_e32 v24, 0xffff0000, v24
	v_lshlrev_b32_e32 v34, 16, v25
	v_and_b32_e32 v25, 0xffff0000, v25
	v_lshlrev_b32_e32 v35, 16, v26
	v_and_b32_e32 v26, 0xffff0000, v26
	v_lshlrev_b32_e32 v36, 16, v27
	v_and_b32_e32 v27, 0xffff0000, v27
	v_mul_f32_e32 v21, v21, v24
	v_mul_f32_e32 v23, v23, v25
	v_mul_f32_e32 v25, v17, v26
	v_mul_f32_e32 v27, v19, v27
	v_mul_f32_e32 v20, v20, v31
	v_mul_f32_e32 v22, v22, v34
	v_mul_f32_e32 v24, v16, v35
	v_mul_f32_e32 v26, v18, v36
	v_mul_f32_e32 v16, v21, v21
	v_mul_f32_e32 v17, v23, v23
	v_mul_f32_e32 v18, v25, v25
	v_mul_f32_e32 v19, v27, v27
	v_fmac_f32_e32 v16, v20, v20
	v_fmac_f32_e32 v17, v22, v22
	v_fmac_f32_e32 v18, v24, v24
	v_fmac_f32_e32 v19, v26, v26
	v_add_f32_e32 v16, v16, v17
	v_add_f32_e32 v17, v18, v19
	v_add_f32_e32 v16, v16, v17
	v_add_f32_e32 v16, v30, v16
	ds_bpermute_b32 v17, v136, v16
	v_cvt_pk_bf16_f32 v18, v20, v21
	v_cvt_pk_bf16_f32 v19, v22, v23
	v_cvt_pk_bf16_f32 v20, v24, v25
	v_cvt_pk_bf16_f32 v21, v26, v27
	s_waitcnt lgkmcnt(0)
	v_add_f32_e32 v16, v16, v17
	ds_bpermute_b32 v17, v130, v16
	global_store_dwordx4 v[28:29], v[18:21], off offset:256
	s_and_saveexec_b64 s[52:53], s[4:5]
	s_cbranch_execz .LBB0_652
	v_lshl_add_u64 v[18:19], s[18:19], 0, v[32:33]
	v_lshl_add_u64 v[18:19], s[50:51], 2, v[18:19]
	s_lshl_b32 s20, s66, 2
	v_lshl_add_u64 v[18:19], v[18:19], 0, s[20:21]
	s_waitcnt lgkmcnt(0)
	v_add_f32_e32 v16, v16, v17
	global_store_dword v[18:19], v16, off
.LBB0_652:
	s_or_b64 exec, exec, s[52:53]
	v_add_u32_e32 v22, 0xb0, v166
	v_ashrrev_i32_e32 v23, 31, v22
	s_waitcnt lgkmcnt(0)
	v_lshlrev_b64 v[16:17], 5, v[22:23]
	v_lshl_add_u64 v[18:19], v[168:169], 0, v[16:17]
	v_lshl_add_u64 v[18:19], v[18:19], 0, v[152:153]
	global_load_dwordx4 v[18:21], v[18:19], off nt
	v_pk_add_f32 v[14:15], v[14:15], v[70:71]
	v_pk_add_f32 v[12:13], v[12:13], v[68:69]
	v_pk_add_f32 v[10:11], v[10:11], v[66:67]
	v_pk_add_f32 v[8:9], v[8:9], v[64:65]
	v_mul_f32_e32 v12, 0xbfb8aa3b, v12
	v_mul_f32_e32 v13, 0xbfb8aa3b, v13
	v_mul_f32_e32 v14, 0xbfb8aa3b, v14
	v_mul_f32_e32 v15, 0xbfb8aa3b, v15
	v_mul_f32_e32 v24, 0xbfb8aa3b, v8
	v_mul_f32_e32 v25, 0xbfb8aa3b, v9
	v_mul_f32_e32 v10, 0xbfb8aa3b, v10
	v_mul_f32_e32 v11, 0xbfb8aa3b, v11
	v_lshlrev_b64 v[8:9], 11, v[22:23]
	v_exp_f32_e32 v22, v12
	v_exp_f32_e32 v23, v13
	v_exp_f32_e32 v26, v14
	v_exp_f32_e32 v27, v15
	v_exp_f32_e32 v24, v24
	v_exp_f32_e32 v25, v25
	v_exp_f32_e32 v28, v10
	v_exp_f32_e32 v29, v11
	v_lshl_add_u64 v[8:9], s[0:1], 0, v[8:9]
	v_lshl_add_u64 v[10:11], v[170:171], 0, v[16:17]
	v_lshl_add_u64 v[12:13], v[164:165], 1, v[8:9]
	v_lshl_add_u64 v[14:15], v[10:11], 0, v[152:153]
	v_add_f32_e32 v8, 1.0, v22
	v_add_f32_e32 v9, 1.0, v23
	v_add_f32_e32 v10, 1.0, v26
	v_add_f32_e32 v11, 1.0, v27
	v_add_f32_e32 v22, 1.0, v24
	v_add_f32_e32 v23, 1.0, v25
	v_add_f32_e32 v24, 1.0, v28
	v_add_f32_e32 v25, 1.0, v29
	v_rcp_f32_e32 v8, v8
	v_rcp_f32_e32 v9, v9
	v_rcp_f32_e32 v10, v10
	v_rcp_f32_e32 v11, v11
	v_rcp_f32_e32 v22, v22
	v_rcp_f32_e32 v23, v23
	v_rcp_f32_e32 v24, v24
	v_rcp_f32_e32 v25, v25
	v_pk_add_f32 v[6:7], v[6:7], v[62:63]
	v_pk_add_f32 v[4:5], v[4:5], v[60:61]
	v_pk_add_f32 v[2:3], v[2:3], v[58:59]
	v_pk_add_f32 v[0:1], v[0:1], v[56:57]
	v_mul_f32_e32 v5, 0xbfb8aa3b, v5
	v_mul_f32_e32 v7, 0xbfb8aa3b, v7
	v_mul_f32_e32 v1, 0xbfb8aa3b, v1
	v_mul_f32_e32 v3, 0xbfb8aa3b, v3
	v_mul_f32_e32 v4, 0xbfb8aa3b, v4
	v_mul_f32_e32 v6, 0xbfb8aa3b, v6
	v_mul_f32_e32 v0, 0xbfb8aa3b, v0
	v_mul_f32_e32 v2, 0xbfb8aa3b, v2
	v_exp_f32_e32 v5, v5
	v_exp_f32_e32 v7, v7
	v_exp_f32_e32 v1, v1
	v_exp_f32_e32 v3, v3
	v_exp_f32_e32 v4, v4
	v_exp_f32_e32 v6, v6
	v_exp_f32_e32 v0, v0
	v_exp_f32_e32 v2, v2
	v_add_f32_e32 v5, 1.0, v5
	v_add_f32_e32 v7, 1.0, v7
	v_add_f32_e32 v1, 1.0, v1
	v_add_f32_e32 v3, 1.0, v3
	v_add_f32_e32 v4, 1.0, v4
	v_add_f32_e32 v6, 1.0, v6
	v_add_f32_e32 v0, 1.0, v0
	v_add_f32_e32 v2, 1.0, v2
	v_rcp_f32_e32 v5, v5
	v_rcp_f32_e32 v7, v7
	v_rcp_f32_e32 v1, v1
	v_rcp_f32_e32 v3, v3
	v_rcp_f32_e32 v4, v4
	v_rcp_f32_e32 v6, v6
	v_rcp_f32_e32 v0, v0
	v_rcp_f32_e32 v2, v2
	s_waitcnt vmcnt(0)
	v_lshlrev_b32_e32 v26, 16, v18
	v_and_b32_e32 v18, 0xffff0000, v18
	v_lshlrev_b32_e32 v27, 16, v19
	v_and_b32_e32 v19, 0xffff0000, v19
	v_lshlrev_b32_e32 v28, 16, v20
	v_and_b32_e32 v20, 0xffff0000, v20
	v_lshlrev_b32_e32 v29, 16, v21
	v_and_b32_e32 v21, 0xffff0000, v21
	v_mul_f32_e32 v26, v8, v26
	v_mul_f32_e32 v18, v9, v18
	v_mul_f32_e32 v27, v10, v27
	v_mul_f32_e32 v19, v11, v19
	v_mul_f32_e32 v22, v22, v28
	v_mul_f32_e32 v20, v23, v20
	v_mul_f32_e32 v23, v24, v29
	v_mul_f32_e32 v21, v25, v21
	v_cvt_pk_bf16_f32 v8, v26, v18
	v_cvt_pk_bf16_f32 v9, v27, v19
	v_cvt_pk_bf16_f32 v10, v22, v20
	v_cvt_pk_bf16_f32 v11, v23, v21
	global_store_dwordx4 v[12:13], v[8:11], off
	global_load_dwordx4 v[8:11], v[14:15], off nt
	v_mul_f32_e32 v14, v18, v18
	v_mul_f32_e32 v15, v19, v19
	v_mul_f32_e32 v18, v20, v20
	v_mul_f32_e32 v19, v21, v21
	v_fmac_f32_e32 v14, v26, v26
	v_fmac_f32_e32 v15, v27, v27
	v_fmac_f32_e32 v18, v22, v22
	v_fmac_f32_e32 v19, v23, v23
	v_add_f32_e32 v14, v14, v15
	v_add_f32_e32 v15, v18, v19
	v_add_f32_e32 v14, v14, v15
	s_waitcnt vmcnt(0)
	v_lshlrev_b32_e32 v15, 16, v8
	v_and_b32_e32 v8, 0xffff0000, v8
	v_lshlrev_b32_e32 v18, 16, v9
	v_and_b32_e32 v9, 0xffff0000, v9
	v_lshlrev_b32_e32 v19, 16, v10
	v_and_b32_e32 v10, 0xffff0000, v10
	v_lshlrev_b32_e32 v20, 16, v11
	v_and_b32_e32 v11, 0xffff0000, v11
	v_mul_f32_e32 v5, v5, v8
	v_mul_f32_e32 v7, v7, v9
	v_mul_f32_e32 v9, v1, v10
	v_mul_f32_e32 v11, v3, v11
	v_mul_f32_e32 v4, v4, v15
	v_mul_f32_e32 v6, v6, v18
	v_mul_f32_e32 v8, v0, v19
	v_mul_f32_e32 v10, v2, v20
	v_mul_f32_e32 v0, v5, v5
	v_mul_f32_e32 v1, v7, v7
	v_mul_f32_e32 v2, v9, v9
	v_mul_f32_e32 v3, v11, v11
	v_fmac_f32_e32 v0, v4, v4
	v_fmac_f32_e32 v1, v6, v6
	v_fmac_f32_e32 v2, v8, v8
	v_fmac_f32_e32 v3, v10, v10
	v_add_f32_e32 v0, v0, v1
	v_add_f32_e32 v1, v2, v3
	v_add_f32_e32 v0, v0, v1
	v_add_f32_e32 v0, v14, v0
	ds_bpermute_b32 v1, v136, v0
	v_cvt_pk_bf16_f32 v2, v4, v5
	v_cvt_pk_bf16_f32 v3, v6, v7
	v_cvt_pk_bf16_f32 v4, v8, v9
	v_cvt_pk_bf16_f32 v5, v10, v11
	s_waitcnt lgkmcnt(0)
	v_add_f32_e32 v0, v0, v1
	ds_bpermute_b32 v1, v130, v0
	global_store_dwordx4 v[12:13], v[2:5], off offset:256
	s_and_saveexec_b64 s[52:53], s[4:5]
	s_cbranch_execz .LBB0_654
	v_lshl_add_u64 v[2:3], s[18:19], 0, v[16:17]
	v_lshl_add_u64 v[2:3], s[50:51], 2, v[2:3]
	s_lshl_b32 s20, s66, 2
	v_lshl_add_u64 v[2:3], v[2:3], 0, s[20:21]
	s_waitcnt lgkmcnt(0)
	v_add_f32_e32 v0, v0, v1
	global_store_dword v[2:3], v0, off

.LBB0_720:
	s_or_b64 exec, exec, s[36:37]
	s_waitcnt vmcnt(0)
	s_barrier
	v_mbcnt_lo_u32_b32 v1, -1, 0
	v_mbcnt_hi_u32_b32 v1, -1, v1
	v_cndmask_b32_e64 v2, 0, 1, s[10:11]
	v_add_u32_e32 v0, s33, v1
	v_cmp_ne_u32_e64 s[4:5], 1, v2
	s_andn2_b64 vcc, exec, s[10:11]
	v_readfirstlane_b32 s8, v0
	s_cbranch_vccnz .LBB0_726
	s_lshr_b32 s6, s3, 29
	s_add_i32 s9, s2, s6
	s_and_b32 s6, s9, -8
	s_sub_i32 s10, s2, s6
	s_cmp_gt_i32 s10, -1
	s_cbranch_scc0 .LBB0_723
	s_lshl_b32 s11, s10, 6
	s_cbranch_execz .LBB0_724
	s_branch .LBB0_725

.LBB0_744:
	v_lshl_or_b32 v2, s10, 8, v164
	v_readlane_b32 s80, v255, 2
	v_ashrrev_i32_e32 v3, 31, v2
	v_readlane_b32 s82, v255, 4
	v_readlane_b32 s83, v255, 5
	v_lshlrev_b64 v[156:157], 11, v[148:149]
	v_lshl_add_u64 v[156:157], s[12:13], 0, v[156:157]
	v_lshl_add_u64 v[150:151], v[2:3], 2, s[82:83]
	global_load_dwordx4 v[152:155], v[150:151], off
	global_load_dwordx4 v[168:171], v[150:151], off offset:16
	v_lshl_add_u64 v[184:185], v[2:3], 1, v[156:157]
	global_load_dwordx4 v[172:175], v[184:185], off nt
	v_lshlrev_b64 v[156:157], 2, v[148:149]
	v_lshl_add_u64 v[158:159], s[36:37], 0, v[156:157]
	global_load_dword v186, v[158:159], off
	v_lshl_add_u64 v[160:161], s[24:25], 0, v[156:157]
	global_load_dword v188, v[160:161], off
	global_load_dwordx4 v[176:179], v[150:151], off offset:528
	global_load_dwordx4 v[180:183], v[150:151], off offset:512
	v_xor_b32_e32 v1, 16, v166
	v_xor_b32_e32 v167, 32, v166
	s_lshl_b32 s58, s10, 2
	s_ashr_i32 s59, s58, 31
	v_readlane_b32 s81, v255, 3
	v_readlane_b32 s84, v255, 6
	v_readlane_b32 s85, v255, 7
	v_readlane_b32 s86, v255, 8
	v_readlane_b32 s87, v255, 9
	v_readlane_b32 s88, v255, 10
	v_readlane_b32 s89, v255, 11
	v_readlane_b32 s90, v255, 12
	v_readlane_b32 s91, v255, 13
	v_readlane_b32 s92, v255, 14
	v_readlane_b32 s93, v255, 15
	v_readlane_b32 s94, v255, 16
	v_readlane_b32 s95, v255, 17
	s_waitcnt vmcnt(0)
	v_rcp_f32_e32 v152, v152
	v_rcp_f32_e32 v153, v153
	v_rcp_f32_e32 v156, v154
	v_rcp_f32_e32 v157, v155
	v_rcp_f32_e32 v150, v168
	v_rcp_f32_e32 v151, v169
	v_rcp_f32_e32 v154, v170
	v_rcp_f32_e32 v155, v171
	v_lshlrev_b32_e32 v168, 16, v172
	v_and_b32_e32 v169, 0xffff0000, v172
	v_lshlrev_b32_e32 v170, 16, v173
	v_and_b32_e32 v171, 0xffff0000, v173
	v_lshlrev_b32_e32 v172, 16, v174
	v_and_b32_e32 v173, 0xffff0000, v174
	v_lshlrev_b32_e32 v174, 16, v175
	v_and_b32_e32 v175, 0xffff0000, v175
	v_pk_mul_f32 v[170:171], v[156:157], v[170:171]
	v_pk_mul_f32 v[168:169], v[152:153], v[168:169]
	v_pk_mul_f32 v[174:175], v[154:155], v[174:175]
	v_pk_mul_f32 v[172:173], v[150:151], v[172:173]
	v_pk_mul_f32 v[168:169], v[186:187], v[168:169] op_sel_hi:[0,1]
	v_pk_mul_f32 v[170:171], v[186:187], v[170:171] op_sel_hi:[0,1]
	v_pk_mul_f32 v[172:173], v[186:187], v[172:173] op_sel_hi:[0,1]
	v_pk_mul_f32 v[174:175], v[186:187], v[174:175] op_sel_hi:[0,1]
	v_pk_fma_f32 v[190:191], v[130:131], v[188:189], v[170:171] op_sel_hi:[1,0,1]
	v_pk_fma_f32 v[192:193], v[128:129], v[188:189], v[168:169] op_sel_hi:[1,0,1]
	v_pk_fma_f32 v[194:195], v[126:127], v[188:189], v[174:175] op_sel_hi:[1,0,1]
	v_pk_fma_f32 v[196:197], v[124:125], v[188:189], v[172:173] op_sel_hi:[1,0,1]
	v_cvt_pk_bf16_f32 v168, v192, v193
	v_cvt_pk_bf16_f32 v169, v190, v191
	v_and_b32_e32 v124, 64, v166
	v_cvt_pk_bf16_f32 v170, v196, v197
	v_cvt_pk_bf16_f32 v171, v194, v195
	global_load_dwordx4 v[172:175], v[184:185], off offset:256 nt
	v_add_u32_e32 v187, 64, v124
	v_rcp_f32_e32 v126, v180
	v_rcp_f32_e32 v127, v181
	v_rcp_f32_e32 v130, v182
	v_rcp_f32_e32 v131, v183
	v_rcp_f32_e32 v124, v176
	v_rcp_f32_e32 v125, v177
	v_rcp_f32_e32 v128, v178
	v_rcp_f32_e32 v129, v179
	v_mul_f32_e32 v176, v193, v193
	v_mul_f32_e32 v177, v191, v191
	v_mul_f32_e32 v178, v197, v197
	v_mul_f32_e32 v179, v195, v195
	v_fmac_f32_e32 v176, v192, v192
	v_fmac_f32_e32 v177, v190, v190
	v_fmac_f32_e32 v178, v196, v196
	v_fmac_f32_e32 v179, v194, v194
	v_add_f32_e32 v176, v176, v177
	v_add_f32_e32 v177, v178, v179
	v_add_f32_e32 v180, v176, v177
	v_cmp_lt_i32_e32 vcc, v1, v187
	global_store_dwordx4 v[184:185], v[168:171], off
	s_waitcnt vmcnt(1)
	v_lshlrev_b32_e32 v176, 16, v172
	v_and_b32_e32 v177, 0xffff0000, v172
	v_lshlrev_b32_e32 v172, 16, v173
	v_and_b32_e32 v173, 0xffff0000, v173
	v_lshlrev_b32_e32 v178, 16, v174
	v_and_b32_e32 v179, 0xffff0000, v174
	v_lshlrev_b32_e32 v174, 16, v175
	v_and_b32_e32 v175, 0xffff0000, v175
	v_pk_mul_f32 v[172:173], v[130:131], v[172:173]
	v_pk_mul_f32 v[176:177], v[126:127], v[176:177]
	v_pk_mul_f32 v[174:175], v[128:129], v[174:175]
	v_pk_mul_f32 v[178:179], v[124:125], v[178:179]
	v_pk_mul_f32 v[176:177], v[186:187], v[176:177] op_sel_hi:[0,1]
	v_pk_mul_f32 v[172:173], v[186:187], v[172:173] op_sel_hi:[0,1]
	v_pk_mul_f32 v[178:179], v[186:187], v[178:179] op_sel_hi:[0,1]
	v_pk_mul_f32 v[174:175], v[186:187], v[174:175] op_sel_hi:[0,1]
	v_pk_fma_f32 v[122:123], v[122:123], v[188:189], v[172:173] op_sel_hi:[1,0,1]
	v_pk_fma_f32 v[120:121], v[120:121], v[188:189], v[176:177] op_sel_hi:[1,0,1]
	v_pk_fma_f32 v[172:173], v[118:119], v[188:189], v[174:175] op_sel_hi:[1,0,1]
	v_pk_fma_f32 v[174:175], v[116:117], v[188:189], v[178:179] op_sel_hi:[1,0,1]
	v_mul_f32_e32 v116, v121, v121
	v_mul_f32_e32 v117, v123, v123
	v_mul_f32_e32 v118, v175, v175
	v_mul_f32_e32 v119, v173, v173
	v_fmac_f32_e32 v116, v120, v120
	v_fmac_f32_e32 v117, v122, v122
	v_fmac_f32_e32 v118, v174, v174
	v_fmac_f32_e32 v119, v172, v172
	v_add_f32_e32 v116, v116, v117
	v_add_f32_e32 v117, v118, v119
	v_cndmask_b32_e32 v1, v166, v1, vcc
	v_add_f32_e32 v116, v116, v117
	v_lshlrev_b32_e32 v1, 2, v1
	v_add_f32_e32 v116, v180, v116
	ds_bpermute_b32 v117, v1, v116
	v_cmp_lt_i32_e32 vcc, v167, v187
	v_cvt_pk_bf16_f32 v120, v120, v121
	v_cvt_pk_bf16_f32 v121, v122, v123
	v_cvt_pk_bf16_f32 v122, v174, v175
	s_waitcnt lgkmcnt(0)
	v_add_f32_e32 v116, v116, v117
	v_cvt_pk_bf16_f32 v123, v172, v173
	v_cndmask_b32_e32 v118, v166, v167, vcc
	v_lshlrev_b32_e32 v118, 2, v118
	ds_bpermute_b32 v117, v118, v116
	global_store_dwordx4 v[184:185], v[120:123], off offset:256
	s_and_saveexec_b64 s[60:61], s[6:7]
	s_cbranch_execz .LBB0_746
	v_lshlrev_b64 v[120:121], 6, v[148:149]
	v_lshl_add_u64 v[120:121], s[38:39], 0, v[120:121]
	v_lshl_add_u64 v[120:121], s[58:59], 2, v[120:121]
	s_lshl_b32 s10, s71, 2
	v_lshl_add_u64 v[120:121], v[120:121], 0, s[10:11]
	s_waitcnt lgkmcnt(0)
	v_add_f32_e32 v116, v116, v117
	global_store_dword v[120:121], v116, off
.LBB0_746:
	s_or_b64 exec, exec, s[60:61]
	v_or_b32_e32 v116, 16, v148
	s_waitcnt lgkmcnt(0)
	v_ashrrev_i32_e32 v117, 31, v116
	v_lshlrev_b64 v[120:121], 11, v[116:117]
	v_lshl_add_u64 v[120:121], s[12:13], 0, v[120:121]
	v_lshl_add_u64 v[168:169], v[2:3], 1, v[120:121]
	global_load_dwordx4 v[120:123], v[168:169], off nt
	v_lshlrev_b64 v[170:171], 2, v[116:117]
	v_lshl_add_u64 v[172:173], s[36:37], 0, v[170:171]
	global_load_dword v172, v[172:173], off
	v_lshl_add_u64 v[170:171], s[24:25], 0, v[170:171]
	global_load_dword v170, v[170:171], off
	s_waitcnt vmcnt(2)
	v_lshlrev_b32_e32 v174, 16, v120
	v_and_b32_e32 v175, 0xffff0000, v120
	v_lshlrev_b32_e32 v120, 16, v121
	v_and_b32_e32 v121, 0xffff0000, v121
	v_lshlrev_b32_e32 v176, 16, v122
	v_and_b32_e32 v177, 0xffff0000, v122
	v_lshlrev_b32_e32 v122, 16, v123
	v_and_b32_e32 v123, 0xffff0000, v123
	v_pk_mul_f32 v[120:121], v[156:157], v[120:121]
	v_pk_mul_f32 v[174:175], v[152:153], v[174:175]
	v_pk_mul_f32 v[122:123], v[154:155], v[122:123]
	v_pk_mul_f32 v[176:177], v[150:151], v[176:177]
	s_waitcnt vmcnt(1)
	v_pk_mul_f32 v[174:175], v[172:173], v[174:175] op_sel_hi:[0,1]
	v_pk_mul_f32 v[120:121], v[172:173], v[120:121] op_sel_hi:[0,1]
	v_pk_mul_f32 v[176:177], v[172:173], v[176:177] op_sel_hi:[0,1]
	v_pk_mul_f32 v[122:123], v[172:173], v[122:123] op_sel_hi:[0,1]
	s_waitcnt vmcnt(0)
	v_pk_fma_f32 v[120:121], v[114:115], v[170:171], v[120:121] op_sel_hi:[1,0,1]
	v_pk_fma_f32 v[174:175], v[112:113], v[170:171], v[174:175] op_sel_hi:[1,0,1]
	v_pk_fma_f32 v[122:123], v[110:111], v[170:171], v[122:123] op_sel_hi:[1,0,1]
	v_pk_fma_f32 v[176:177], v[108:109], v[170:171], v[176:177] op_sel_hi:[1,0,1]
	v_cvt_pk_bf16_f32 v108, v174, v175
	v_cvt_pk_bf16_f32 v109, v120, v121
	v_mul_f32_e32 v119, v175, v175
	v_cvt_pk_bf16_f32 v110, v176, v177
	v_cvt_pk_bf16_f32 v111, v122, v123
	global_load_dwordx4 v[112:115], v[168:169], off offset:256 nt
	v_mul_f32_e32 v121, v121, v121
	v_mul_f32_e32 v149, v177, v177
	v_mul_f32_e32 v123, v123, v123
	v_fmac_f32_e32 v119, v174, v174
	v_fmac_f32_e32 v121, v120, v120
	v_fmac_f32_e32 v149, v176, v176
	v_fmac_f32_e32 v123, v122, v122
	v_add_f32_e32 v119, v119, v121
	v_add_f32_e32 v120, v149, v123
	v_add_f32_e32 v119, v119, v120
	global_store_dwordx4 v[168:169], v[108:111], off
	s_waitcnt vmcnt(1)
	v_lshlrev_b32_e32 v120, 16, v112
	v_and_b32_e32 v121, 0xffff0000, v112
	v_lshlrev_b32_e32 v112, 16, v113
	v_and_b32_e32 v113, 0xffff0000, v113
	v_lshlrev_b32_e32 v122, 16, v114
	v_and_b32_e32 v123, 0xffff0000, v114
	v_lshlrev_b32_e32 v114, 16, v115
	v_and_b32_e32 v115, 0xffff0000, v115
	v_pk_mul_f32 v[112:113], v[130:131], v[112:113]
	v_pk_mul_f32 v[120:121], v[126:127], v[120:121]
	v_pk_mul_f32 v[114:115], v[128:129], v[114:115]
	v_pk_mul_f32 v[122:123], v[124:125], v[122:123]
	v_pk_mul_f32 v[120:121], v[172:173], v[120:121] op_sel_hi:[0,1]
	v_pk_mul_f32 v[112:113], v[172:173], v[112:113] op_sel_hi:[0,1]
	v_pk_mul_f32 v[122:123], v[172:173], v[122:123] op_sel_hi:[0,1]
	v_pk_mul_f32 v[114:115], v[172:173], v[114:115] op_sel_hi:[0,1]
	v_pk_fma_f32 v[106:107], v[106:107], v[170:171], v[112:113] op_sel_hi:[1,0,1]
	v_pk_fma_f32 v[104:105], v[104:105], v[170:171], v[120:121] op_sel_hi:[1,0,1]
	v_pk_fma_f32 v[112:113], v[102:103], v[170:171], v[114:115] op_sel_hi:[1,0,1]
	v_pk_fma_f32 v[114:115], v[100:101], v[170:171], v[122:123] op_sel_hi:[1,0,1]
	v_mul_f32_e32 v100, v105, v105
	v_mul_f32_e32 v101, v107, v107
	v_mul_f32_e32 v102, v115, v115
	v_mul_f32_e32 v103, v113, v113
	v_fmac_f32_e32 v100, v104, v104
	v_fmac_f32_e32 v101, v106, v106
	v_fmac_f32_e32 v102, v114, v114
	v_fmac_f32_e32 v103, v112, v112
	v_add_f32_e32 v100, v100, v101
	v_add_f32_e32 v101, v102, v103
	v_add_f32_e32 v100, v100, v101
	v_add_f32_e32 v100, v119, v100
	ds_bpermute_b32 v101, v1, v100
	v_cvt_pk_bf16_f32 v102, v104, v105
	v_cvt_pk_bf16_f32 v103, v106, v107
	v_cvt_pk_bf16_f32 v104, v114, v115
	v_cvt_pk_bf16_f32 v105, v112, v113
	s_waitcnt lgkmcnt(0)
	v_add_f32_e32 v100, v100, v101
	ds_bpermute_b32 v101, v118, v100
	global_store_dwordx4 v[168:169], v[102:105], off offset:256
	s_and_saveexec_b64 s[60:61], s[6:7]
	s_cbranch_execz .LBB0_748
	v_lshlrev_b64 v[102:103], 6, v[116:117]
	v_lshl_add_u64 v[102:103], s[38:39], 0, v[102:103]
	v_lshl_add_u64 v[102:103], s[58:59], 2, v[102:103]
	s_lshl_b32 s10, s71, 2
	v_lshl_add_u64 v[102:103], v[102:103], 0, s[10:11]
	s_waitcnt lgkmcnt(0)
	v_add_f32_e32 v100, v100, v101
	global_store_dword v[102:103], v100, off
.LBB0_748:
	s_or_b64 exec, exec, s[60:61]
	v_or_b32_e32 v100, 32, v148
	s_waitcnt lgkmcnt(0)
	v_ashrrev_i32_e32 v101, 31, v100
	v_lshlrev_b64 v[102:103], 11, v[100:101]
	v_lshl_add_u64 v[102:103], s[12:13], 0, v[102:103]
	v_lshl_add_u64 v[106:107], v[2:3], 1, v[102:103]
	global_load_dwordx4 v[102:105], v[106:107], off nt
	v_lshlrev_b64 v[108:109], 2, v[100:101]
	v_lshl_add_u64 v[110:111], s[36:37], 0, v[108:109]
	global_load_dword v110, v[110:111], off
	v_lshl_add_u64 v[108:109], s[24:25], 0, v[108:109]
	global_load_dword v108, v[108:109], off
	s_waitcnt vmcnt(2)
	v_lshlrev_b32_e32 v112, 16, v102
	v_and_b32_e32 v113, 0xffff0000, v102
	v_lshlrev_b32_e32 v102, 16, v103
	v_and_b32_e32 v103, 0xffff0000, v103
	v_lshlrev_b32_e32 v114, 16, v104
	v_and_b32_e32 v115, 0xffff0000, v104
	v_lshlrev_b32_e32 v104, 16, v105
	v_and_b32_e32 v105, 0xffff0000, v105
	v_pk_mul_f32 v[102:103], v[156:157], v[102:103]
	v_pk_mul_f32 v[112:113], v[152:153], v[112:113]
	v_pk_mul_f32 v[104:105], v[154:155], v[104:105]
	v_pk_mul_f32 v[114:115], v[150:151], v[114:115]
	s_waitcnt vmcnt(1)
	v_pk_mul_f32 v[112:113], v[110:111], v[112:113] op_sel_hi:[0,1]
	v_pk_mul_f32 v[102:103], v[110:111], v[102:103] op_sel_hi:[0,1]
	v_pk_mul_f32 v[114:115], v[110:111], v[114:115] op_sel_hi:[0,1]
	v_pk_mul_f32 v[104:105], v[110:111], v[104:105] op_sel_hi:[0,1]
	s_waitcnt vmcnt(0)
	v_pk_fma_f32 v[102:103], v[98:99], v[108:109], v[102:103] op_sel_hi:[1,0,1]
	v_pk_fma_f32 v[112:113], v[96:97], v[108:109], v[112:113] op_sel_hi:[1,0,1]
	v_pk_fma_f32 v[104:105], v[94:95], v[108:109], v[104:105] op_sel_hi:[1,0,1]
	v_pk_fma_f32 v[114:115], v[92:93], v[108:109], v[114:115] op_sel_hi:[1,0,1]
	v_cvt_pk_bf16_f32 v92, v112, v113
	v_cvt_pk_bf16_f32 v93, v102, v103
	v_mul_f32_e32 v109, v113, v113
	v_cvt_pk_bf16_f32 v94, v114, v115
	v_cvt_pk_bf16_f32 v95, v104, v105
	global_load_dwordx4 v[96:99], v[106:107], off offset:256 nt
	v_mul_f32_e32 v103, v103, v103
	v_mul_f32_e32 v111, v115, v115
	v_mul_f32_e32 v105, v105, v105
	v_fmac_f32_e32 v109, v112, v112
	v_fmac_f32_e32 v103, v102, v102
	v_fmac_f32_e32 v111, v114, v114
	v_fmac_f32_e32 v105, v104, v104
	v_add_f32_e32 v102, v109, v103
	v_add_f32_e32 v103, v111, v105
	v_add_f32_e32 v109, v102, v103
	global_store_dwordx4 v[106:107], v[92:95], off
	s_waitcnt vmcnt(1)
	v_lshlrev_b32_e32 v102, 16, v96
	v_and_b32_e32 v103, 0xffff0000, v96
	v_lshlrev_b32_e32 v96, 16, v97
	v_and_b32_e32 v97, 0xffff0000, v97
	v_lshlrev_b32_e32 v104, 16, v98
	v_and_b32_e32 v105, 0xffff0000, v98
	v_lshlrev_b32_e32 v98, 16, v99
	v_and_b32_e32 v99, 0xffff0000, v99
	v_pk_mul_f32 v[96:97], v[130:131], v[96:97]
	v_pk_mul_f32 v[102:103], v[126:127], v[102:103]
	v_pk_mul_f32 v[98:99], v[128:129], v[98:99]
	v_pk_mul_f32 v[104:105], v[124:125], v[104:105]
	v_pk_mul_f32 v[102:103], v[110:111], v[102:103] op_sel_hi:[0,1]
	v_pk_mul_f32 v[96:97], v[110:111], v[96:97] op_sel_hi:[0,1]
	v_pk_mul_f32 v[104:105], v[110:111], v[104:105] op_sel_hi:[0,1]
	v_pk_mul_f32 v[98:99], v[110:111], v[98:99] op_sel_hi:[0,1]
	v_pk_fma_f32 v[90:91], v[90:91], v[108:109], v[96:97] op_sel_hi:[1,0,1]
	v_pk_fma_f32 v[88:89], v[88:89], v[108:109], v[102:103] op_sel_hi:[1,0,1]
	v_pk_fma_f32 v[96:97], v[86:87], v[108:109], v[98:99] op_sel_hi:[1,0,1]
	v_pk_fma_f32 v[98:99], v[84:85], v[108:109], v[104:105] op_sel_hi:[1,0,1]
	v_mul_f32_e32 v84, v89, v89
	v_mul_f32_e32 v85, v91, v91
	v_mul_f32_e32 v86, v99, v99
	v_mul_f32_e32 v87, v97, v97
	v_fmac_f32_e32 v84, v88, v88
	v_fmac_f32_e32 v85, v90, v90
	v_fmac_f32_e32 v86, v98, v98
	v_fmac_f32_e32 v87, v96, v96
	v_add_f32_e32 v84, v84, v85
	v_add_f32_e32 v85, v86, v87
	v_add_f32_e32 v84, v84, v85
	v_add_f32_e32 v84, v109, v84
	ds_bpermute_b32 v85, v1, v84
	v_cvt_pk_bf16_f32 v86, v88, v89
	v_cvt_pk_bf16_f32 v87, v90, v91
	v_cvt_pk_bf16_f32 v88, v98, v99
	v_cvt_pk_bf16_f32 v89, v96, v97
	s_waitcnt lgkmcnt(0)
	v_add_f32_e32 v84, v84, v85
	ds_bpermute_b32 v85, v118, v84
	global_store_dwordx4 v[106:107], v[86:89], off offset:256
	s_and_saveexec_b64 s[60:61], s[6:7]
	s_mov_b64 s[84:85], s[54:55]
	s_mov_b64 s[86:87], s[62:63]
	s_cbranch_execz .LBB0_750
	v_lshlrev_b64 v[86:87], 6, v[100:101]
	v_lshl_add_u64 v[86:87], s[38:39], 0, v[86:87]
	v_lshl_add_u64 v[86:87], s[58:59], 2, v[86:87]
	s_lshl_b32 s10, s71, 2
	v_lshl_add_u64 v[86:87], v[86:87], 0, s[10:11]
	s_waitcnt lgkmcnt(0)
	v_add_f32_e32 v84, v84, v85
	global_store_dword v[86:87], v84, off
.LBB0_750:
	s_or_b64 exec, exec, s[60:61]
	v_or_b32_e32 v84, 48, v148
	s_waitcnt lgkmcnt(0)
	v_ashrrev_i32_e32 v85, 31, v84
	v_lshlrev_b64 v[86:87], 11, v[84:85]
	v_lshl_add_u64 v[86:87], s[12:13], 0, v[86:87]
	v_lshl_add_u64 v[90:91], v[2:3], 1, v[86:87]
	global_load_dwordx4 v[86:89], v[90:91], off nt
	v_lshlrev_b64 v[92:93], 2, v[84:85]
	v_lshl_add_u64 v[94:95], s[36:37], 0, v[92:93]
	global_load_dword v94, v[94:95], off
	v_lshl_add_u64 v[92:93], s[24:25], 0, v[92:93]
	global_load_dword v92, v[92:93], off
	s_waitcnt vmcnt(2)
	v_lshlrev_b32_e32 v96, 16, v86
	v_and_b32_e32 v97, 0xffff0000, v86
	v_lshlrev_b32_e32 v86, 16, v87
	v_and_b32_e32 v87, 0xffff0000, v87
	v_lshlrev_b32_e32 v98, 16, v88
	v_and_b32_e32 v99, 0xffff0000, v88
	v_lshlrev_b32_e32 v88, 16, v89
	v_and_b32_e32 v89, 0xffff0000, v89
	v_pk_mul_f32 v[86:87], v[156:157], v[86:87]
	v_pk_mul_f32 v[96:97], v[152:153], v[96:97]
	v_pk_mul_f32 v[88:89], v[154:155], v[88:89]
	v_pk_mul_f32 v[98:99], v[150:151], v[98:99]
	s_waitcnt vmcnt(1)
	v_pk_mul_f32 v[96:97], v[94:95], v[96:97] op_sel_hi:[0,1]
	v_pk_mul_f32 v[86:87], v[94:95], v[86:87] op_sel_hi:[0,1]
	v_pk_mul_f32 v[98:99], v[94:95], v[98:99] op_sel_hi:[0,1]
	v_pk_mul_f32 v[88:89], v[94:95], v[88:89] op_sel_hi:[0,1]
	s_waitcnt vmcnt(0)
	v_pk_fma_f32 v[86:87], v[82:83], v[92:93], v[86:87] op_sel_hi:[1,0,1]
	v_pk_fma_f32 v[96:97], v[80:81], v[92:93], v[96:97] op_sel_hi:[1,0,1]
	v_pk_fma_f32 v[88:89], v[78:79], v[92:93], v[88:89] op_sel_hi:[1,0,1]
	v_pk_fma_f32 v[98:99], v[76:77], v[92:93], v[98:99] op_sel_hi:[1,0,1]
	v_cvt_pk_bf16_f32 v76, v96, v97
	v_cvt_pk_bf16_f32 v77, v86, v87
	v_mul_f32_e32 v93, v97, v97
	v_cvt_pk_bf16_f32 v78, v98, v99
	v_cvt_pk_bf16_f32 v79, v88, v89
	global_load_dwordx4 v[80:83], v[90:91], off offset:256 nt
	v_mul_f32_e32 v87, v87, v87
	v_mul_f32_e32 v95, v99, v99
	v_mul_f32_e32 v89, v89, v89
	v_fmac_f32_e32 v93, v96, v96
	v_fmac_f32_e32 v87, v86, v86
	v_fmac_f32_e32 v95, v98, v98
	v_fmac_f32_e32 v89, v88, v88
	v_add_f32_e32 v86, v93, v87
	v_add_f32_e32 v87, v95, v89
	v_add_f32_e32 v93, v86, v87
	global_store_dwordx4 v[90:91], v[76:79], off
	s_waitcnt vmcnt(1)
	v_lshlrev_b32_e32 v86, 16, v80
	v_and_b32_e32 v87, 0xffff0000, v80
	v_lshlrev_b32_e32 v80, 16, v81
	v_and_b32_e32 v81, 0xffff0000, v81
	v_lshlrev_b32_e32 v88, 16, v82
	v_and_b32_e32 v89, 0xffff0000, v82
	v_lshlrev_b32_e32 v82, 16, v83
	v_and_b32_e32 v83, 0xffff0000, v83
	v_pk_mul_f32 v[80:81], v[130:131], v[80:81]
	v_pk_mul_f32 v[86:87], v[126:127], v[86:87]
	v_pk_mul_f32 v[82:83], v[128:129], v[82:83]
	v_pk_mul_f32 v[88:89], v[124:125], v[88:89]
	v_pk_mul_f32 v[86:87], v[94:95], v[86:87] op_sel_hi:[0,1]
	v_pk_mul_f32 v[80:81], v[94:95], v[80:81] op_sel_hi:[0,1]
	v_pk_mul_f32 v[88:89], v[94:95], v[88:89] op_sel_hi:[0,1]
	v_pk_mul_f32 v[82:83], v[94:95], v[82:83] op_sel_hi:[0,1]
	v_pk_fma_f32 v[74:75], v[74:75], v[92:93], v[80:81] op_sel_hi:[1,0,1]
	v_pk_fma_f32 v[72:73], v[72:73], v[92:93], v[86:87] op_sel_hi:[1,0,1]
	v_pk_fma_f32 v[80:81], v[70:71], v[92:93], v[82:83] op_sel_hi:[1,0,1]
	v_pk_fma_f32 v[82:83], v[68:69], v[92:93], v[88:89] op_sel_hi:[1,0,1]
	v_mul_f32_e32 v68, v73, v73
	v_mul_f32_e32 v69, v75, v75
	v_mul_f32_e32 v70, v83, v83
	v_mul_f32_e32 v71, v81, v81
	v_fmac_f32_e32 v68, v72, v72
	v_fmac_f32_e32 v69, v74, v74
	v_fmac_f32_e32 v70, v82, v82
	v_fmac_f32_e32 v71, v80, v80
	v_add_f32_e32 v68, v68, v69
	v_add_f32_e32 v69, v70, v71
	v_add_f32_e32 v68, v68, v69
	v_add_f32_e32 v68, v93, v68
	ds_bpermute_b32 v69, v1, v68
	v_cvt_pk_bf16_f32 v70, v72, v73
	v_cvt_pk_bf16_f32 v71, v74, v75
	v_cvt_pk_bf16_f32 v72, v82, v83
	v_cvt_pk_bf16_f32 v73, v80, v81
	s_waitcnt lgkmcnt(0)
	v_add_f32_e32 v68, v68, v69
	ds_bpermute_b32 v69, v118, v68
	global_store_dwordx4 v[90:91], v[70:73], off offset:256
	s_and_saveexec_b64 s[60:61], s[6:7]
	s_cbranch_execz .LBB0_752
	v_lshlrev_b64 v[70:71], 6, v[84:85]
	v_lshl_add_u64 v[70:71], s[38:39], 0, v[70:71]
	v_lshl_add_u64 v[70:71], s[58:59], 2, v[70:71]
	s_lshl_b32 s10, s71, 2
	v_lshl_add_u64 v[70:71], v[70:71], 0, s[10:11]
	s_waitcnt lgkmcnt(0)
	v_add_f32_e32 v68, v68, v69
	global_store_dword v[70:71], v68, off
.LBB0_752:
	s_or_b64 exec, exec, s[60:61]
	v_add_u32_e32 v68, 0x80, v148
	s_waitcnt lgkmcnt(0)
	v_ashrrev_i32_e32 v69, 31, v68
	v_lshlrev_b64 v[70:71], 11, v[68:69]
	v_lshl_add_u64 v[70:71], s[12:13], 0, v[70:71]
	v_lshl_add_u64 v[74:75], v[2:3], 1, v[70:71]
	global_load_dwordx4 v[70:73], v[74:75], off nt
	global_load_dword v76, v[158:159], off offset:512
	global_load_dword v78, v[160:161], off offset:512
	s_waitcnt vmcnt(2)
	v_lshlrev_b32_e32 v80, 16, v70
	v_and_b32_e32 v81, 0xffff0000, v70
	v_lshlrev_b32_e32 v70, 16, v71
	v_and_b32_e32 v71, 0xffff0000, v71
	v_lshlrev_b32_e32 v82, 16, v72
	v_and_b32_e32 v83, 0xffff0000, v72
	v_lshlrev_b32_e32 v72, 16, v73
	v_and_b32_e32 v73, 0xffff0000, v73
	v_pk_mul_f32 v[70:71], v[156:157], v[70:71]
	v_pk_mul_f32 v[80:81], v[152:153], v[80:81]
	v_pk_mul_f32 v[72:73], v[154:155], v[72:73]
	v_pk_mul_f32 v[82:83], v[150:151], v[82:83]
	s_waitcnt vmcnt(1)
	v_pk_mul_f32 v[80:81], v[76:77], v[80:81] op_sel_hi:[0,1]
	v_pk_mul_f32 v[70:71], v[76:77], v[70:71] op_sel_hi:[0,1]
	v_pk_mul_f32 v[82:83], v[76:77], v[82:83] op_sel_hi:[0,1]
	v_pk_mul_f32 v[72:73], v[76:77], v[72:73] op_sel_hi:[0,1]
	s_waitcnt vmcnt(0)
	v_pk_fma_f32 v[70:71], v[66:67], v[78:79], v[70:71] op_sel_hi:[1,0,1]
	v_pk_fma_f32 v[80:81], v[64:65], v[78:79], v[80:81] op_sel_hi:[1,0,1]
	v_pk_fma_f32 v[72:73], v[62:63], v[78:79], v[72:73] op_sel_hi:[1,0,1]
	v_pk_fma_f32 v[82:83], v[60:61], v[78:79], v[82:83] op_sel_hi:[1,0,1]
	v_cvt_pk_bf16_f32 v60, v80, v81
	v_cvt_pk_bf16_f32 v61, v70, v71
	v_mul_f32_e32 v77, v81, v81
	v_cvt_pk_bf16_f32 v62, v82, v83
	v_cvt_pk_bf16_f32 v63, v72, v73
	global_load_dwordx4 v[64:67], v[74:75], off offset:256 nt
	v_mul_f32_e32 v71, v71, v71
	v_mul_f32_e32 v79, v83, v83
	v_mul_f32_e32 v73, v73, v73
	v_fmac_f32_e32 v77, v80, v80
	v_fmac_f32_e32 v71, v70, v70
	v_fmac_f32_e32 v79, v82, v82
	v_fmac_f32_e32 v73, v72, v72
	v_add_f32_e32 v70, v77, v71
	v_add_f32_e32 v71, v79, v73
	v_add_f32_e32 v77, v70, v71
	global_store_dwordx4 v[74:75], v[60:63], off
	s_waitcnt vmcnt(1)
	v_lshlrev_b32_e32 v70, 16, v64
	v_and_b32_e32 v71, 0xffff0000, v64
	v_lshlrev_b32_e32 v64, 16, v65
	v_and_b32_e32 v65, 0xffff0000, v65
	v_lshlrev_b32_e32 v72, 16, v66
	v_and_b32_e32 v73, 0xffff0000, v66
	v_lshlrev_b32_e32 v66, 16, v67
	v_and_b32_e32 v67, 0xffff0000, v67
	v_pk_mul_f32 v[64:65], v[130:131], v[64:65]
	v_pk_mul_f32 v[70:71], v[126:127], v[70:71]
	v_pk_mul_f32 v[66:67], v[128:129], v[66:67]
	v_pk_mul_f32 v[72:73], v[124:125], v[72:73]
	v_pk_mul_f32 v[70:71], v[76:77], v[70:71] op_sel_hi:[0,1]
	v_pk_mul_f32 v[64:65], v[76:77], v[64:65] op_sel_hi:[0,1]
	v_pk_mul_f32 v[72:73], v[76:77], v[72:73] op_sel_hi:[0,1]
	v_pk_mul_f32 v[66:67], v[76:77], v[66:67] op_sel_hi:[0,1]
	v_pk_fma_f32 v[58:59], v[58:59], v[78:79], v[64:65] op_sel_hi:[1,0,1]
	v_pk_fma_f32 v[56:57], v[56:57], v[78:79], v[70:71] op_sel_hi:[1,0,1]
	v_pk_fma_f32 v[64:65], v[54:55], v[78:79], v[66:67] op_sel_hi:[1,0,1]
	v_pk_fma_f32 v[66:67], v[52:53], v[78:79], v[72:73] op_sel_hi:[1,0,1]
	v_mul_f32_e32 v52, v57, v57
	v_mul_f32_e32 v53, v59, v59
	v_mul_f32_e32 v54, v67, v67
	v_mul_f32_e32 v55, v65, v65
	v_fmac_f32_e32 v52, v56, v56
	v_fmac_f32_e32 v53, v58, v58
	v_fmac_f32_e32 v54, v66, v66
	v_fmac_f32_e32 v55, v64, v64
	v_add_f32_e32 v52, v52, v53
	v_add_f32_e32 v53, v54, v55
	v_add_f32_e32 v52, v52, v53
	v_add_f32_e32 v52, v77, v52
	ds_bpermute_b32 v53, v1, v52
	v_cvt_pk_bf16_f32 v54, v56, v57
	v_cvt_pk_bf16_f32 v55, v58, v59
	v_cvt_pk_bf16_f32 v56, v66, v67
	v_cvt_pk_bf16_f32 v57, v64, v65
	s_waitcnt lgkmcnt(0)
	v_add_f32_e32 v52, v52, v53
	ds_bpermute_b32 v53, v118, v52
	global_store_dwordx4 v[74:75], v[54:57], off offset:256
	s_and_saveexec_b64 s[60:61], s[6:7]
	s_cbranch_execz .LBB0_754
	v_lshlrev_b64 v[54:55], 6, v[68:69]
	v_lshl_add_u64 v[54:55], s[38:39], 0, v[54:55]
	v_lshl_add_u64 v[54:55], s[58:59], 2, v[54:55]
	s_lshl_b32 s10, s71, 2
	v_lshl_add_u64 v[54:55], v[54:55], 0, s[10:11]
	s_waitcnt lgkmcnt(0)
	v_add_f32_e32 v52, v52, v53
	global_store_dword v[54:55], v52, off
.LBB0_754:
	s_or_b64 exec, exec, s[60:61]
	v_add_u32_e32 v52, 0x90, v148
	s_waitcnt lgkmcnt(0)
	v_ashrrev_i32_e32 v53, 31, v52
	v_lshlrev_b64 v[54:55], 11, v[52:53]
	v_lshl_add_u64 v[54:55], s[12:13], 0, v[54:55]
	v_lshl_add_u64 v[58:59], v[2:3], 1, v[54:55]
	global_load_dwordx4 v[54:57], v[58:59], off nt
	global_load_dword v60, v[158:159], off offset:576
	global_load_dword v62, v[160:161], off offset:576
	s_waitcnt vmcnt(2)
	v_lshlrev_b32_e32 v64, 16, v54
	v_and_b32_e32 v65, 0xffff0000, v54
	v_lshlrev_b32_e32 v54, 16, v55
	v_and_b32_e32 v55, 0xffff0000, v55
	v_lshlrev_b32_e32 v66, 16, v56
	v_and_b32_e32 v67, 0xffff0000, v56
	v_lshlrev_b32_e32 v56, 16, v57
	v_and_b32_e32 v57, 0xffff0000, v57
	v_pk_mul_f32 v[54:55], v[156:157], v[54:55]
	v_pk_mul_f32 v[64:65], v[152:153], v[64:65]
	v_pk_mul_f32 v[56:57], v[154:155], v[56:57]
	v_pk_mul_f32 v[66:67], v[150:151], v[66:67]
	s_waitcnt vmcnt(1)
	v_pk_mul_f32 v[64:65], v[60:61], v[64:65] op_sel_hi:[0,1]
	v_pk_mul_f32 v[54:55], v[60:61], v[54:55] op_sel_hi:[0,1]
	v_pk_mul_f32 v[66:67], v[60:61], v[66:67] op_sel_hi:[0,1]
	v_pk_mul_f32 v[56:57], v[60:61], v[56:57] op_sel_hi:[0,1]
	s_waitcnt vmcnt(0)
	v_pk_fma_f32 v[54:55], v[50:51], v[62:63], v[54:55] op_sel_hi:[1,0,1]
	v_pk_fma_f32 v[64:65], v[48:49], v[62:63], v[64:65] op_sel_hi:[1,0,1]
	v_pk_fma_f32 v[56:57], v[46:47], v[62:63], v[56:57] op_sel_hi:[1,0,1]
	v_pk_fma_f32 v[66:67], v[44:45], v[62:63], v[66:67] op_sel_hi:[1,0,1]
	v_cvt_pk_bf16_f32 v44, v64, v65
	v_cvt_pk_bf16_f32 v45, v54, v55
	v_mul_f32_e32 v61, v65, v65
	v_cvt_pk_bf16_f32 v46, v66, v67
	v_cvt_pk_bf16_f32 v47, v56, v57
	global_load_dwordx4 v[48:51], v[58:59], off offset:256 nt
	v_mul_f32_e32 v55, v55, v55
	v_mul_f32_e32 v63, v67, v67
	v_mul_f32_e32 v57, v57, v57
	v_fmac_f32_e32 v61, v64, v64
	v_fmac_f32_e32 v55, v54, v54
	v_fmac_f32_e32 v63, v66, v66
	v_fmac_f32_e32 v57, v56, v56
	v_add_f32_e32 v54, v61, v55
	v_add_f32_e32 v55, v63, v57
	v_add_f32_e32 v61, v54, v55
	global_store_dwordx4 v[58:59], v[44:47], off
	s_waitcnt vmcnt(1)
	v_lshlrev_b32_e32 v54, 16, v48
	v_and_b32_e32 v55, 0xffff0000, v48
	v_lshlrev_b32_e32 v48, 16, v49
	v_and_b32_e32 v49, 0xffff0000, v49
	v_lshlrev_b32_e32 v56, 16, v50
	v_and_b32_e32 v57, 0xffff0000, v50
	v_lshlrev_b32_e32 v50, 16, v51
	v_and_b32_e32 v51, 0xffff0000, v51
	v_pk_mul_f32 v[48:49], v[130:131], v[48:49]
	v_pk_mul_f32 v[54:55], v[126:127], v[54:55]
	v_pk_mul_f32 v[50:51], v[128:129], v[50:51]
	v_pk_mul_f32 v[56:57], v[124:125], v[56:57]
	v_pk_mul_f32 v[54:55], v[60:61], v[54:55] op_sel_hi:[0,1]
	v_pk_mul_f32 v[48:49], v[60:61], v[48:49] op_sel_hi:[0,1]
	v_pk_mul_f32 v[56:57], v[60:61], v[56:57] op_sel_hi:[0,1]
	v_pk_mul_f32 v[50:51], v[60:61], v[50:51] op_sel_hi:[0,1]
	v_pk_fma_f32 v[42:43], v[42:43], v[62:63], v[48:49] op_sel_hi:[1,0,1]
	v_pk_fma_f32 v[40:41], v[40:41], v[62:63], v[54:55] op_sel_hi:[1,0,1]
	v_pk_fma_f32 v[48:49], v[38:39], v[62:63], v[50:51] op_sel_hi:[1,0,1]
	v_pk_fma_f32 v[50:51], v[36:37], v[62:63], v[56:57] op_sel_hi:[1,0,1]
	v_mul_f32_e32 v36, v41, v41
	v_mul_f32_e32 v37, v43, v43
	v_mul_f32_e32 v38, v51, v51
	v_mul_f32_e32 v39, v49, v49
	v_fmac_f32_e32 v36, v40, v40
	v_fmac_f32_e32 v37, v42, v42
	v_fmac_f32_e32 v38, v50, v50
	v_fmac_f32_e32 v39, v48, v48
	v_add_f32_e32 v36, v36, v37
	v_add_f32_e32 v37, v38, v39
	v_add_f32_e32 v36, v36, v37
	v_add_f32_e32 v36, v61, v36
	ds_bpermute_b32 v37, v1, v36
	v_cvt_pk_bf16_f32 v38, v40, v41
	v_cvt_pk_bf16_f32 v39, v42, v43
	v_cvt_pk_bf16_f32 v40, v50, v51
	v_cvt_pk_bf16_f32 v41, v48, v49
	s_waitcnt lgkmcnt(0)
	v_add_f32_e32 v36, v36, v37
	ds_bpermute_b32 v37, v118, v36
	global_store_dwordx4 v[58:59], v[38:41], off offset:256
	s_and_saveexec_b64 s[60:61], s[6:7]
	s_cbranch_execz .LBB0_756
	v_lshlrev_b64 v[38:39], 6, v[52:53]
	v_lshl_add_u64 v[38:39], s[38:39], 0, v[38:39]
	v_lshl_add_u64 v[38:39], s[58:59], 2, v[38:39]
	s_lshl_b32 s10, s71, 2
	v_lshl_add_u64 v[38:39], v[38:39], 0, s[10:11]
	s_waitcnt lgkmcnt(0)
	v_add_f32_e32 v36, v36, v37
	global_store_dword v[38:39], v36, off
.LBB0_756:
	s_or_b64 exec, exec, s[60:61]
	v_add_u32_e32 v36, 0xa0, v148
	s_waitcnt lgkmcnt(0)
	v_ashrrev_i32_e32 v37, 31, v36
	v_lshlrev_b64 v[38:39], 11, v[36:37]
	v_lshl_add_u64 v[38:39], s[12:13], 0, v[38:39]
	v_lshl_add_u64 v[42:43], v[2:3], 1, v[38:39]
	global_load_dwordx4 v[38:41], v[42:43], off nt
	global_load_dword v44, v[158:159], off offset:640
	global_load_dword v46, v[160:161], off offset:640
	s_waitcnt vmcnt(2)
	v_lshlrev_b32_e32 v48, 16, v38
	v_and_b32_e32 v49, 0xffff0000, v38
	v_lshlrev_b32_e32 v38, 16, v39
	v_and_b32_e32 v39, 0xffff0000, v39
	v_lshlrev_b32_e32 v50, 16, v40
	v_and_b32_e32 v51, 0xffff0000, v40
	v_lshlrev_b32_e32 v40, 16, v41
	v_and_b32_e32 v41, 0xffff0000, v41
	v_pk_mul_f32 v[38:39], v[156:157], v[38:39]
	v_pk_mul_f32 v[48:49], v[152:153], v[48:49]
	v_pk_mul_f32 v[40:41], v[154:155], v[40:41]
	v_pk_mul_f32 v[50:51], v[150:151], v[50:51]
	s_waitcnt vmcnt(1)
	v_pk_mul_f32 v[48:49], v[44:45], v[48:49] op_sel_hi:[0,1]
	v_pk_mul_f32 v[38:39], v[44:45], v[38:39] op_sel_hi:[0,1]
	v_pk_mul_f32 v[50:51], v[44:45], v[50:51] op_sel_hi:[0,1]
	v_pk_mul_f32 v[40:41], v[44:45], v[40:41] op_sel_hi:[0,1]
	s_waitcnt vmcnt(0)
	v_pk_fma_f32 v[38:39], v[34:35], v[46:47], v[38:39] op_sel_hi:[1,0,1]
	v_pk_fma_f32 v[48:49], v[32:33], v[46:47], v[48:49] op_sel_hi:[1,0,1]
	v_pk_fma_f32 v[40:41], v[30:31], v[46:47], v[40:41] op_sel_hi:[1,0,1]
	v_pk_fma_f32 v[50:51], v[28:29], v[46:47], v[50:51] op_sel_hi:[1,0,1]
	v_cvt_pk_bf16_f32 v28, v48, v49
	v_cvt_pk_bf16_f32 v29, v38, v39
	v_mul_f32_e32 v45, v49, v49
	v_cvt_pk_bf16_f32 v30, v50, v51
	v_cvt_pk_bf16_f32 v31, v40, v41
	global_load_dwordx4 v[32:35], v[42:43], off offset:256 nt
	v_mul_f32_e32 v39, v39, v39
	v_mul_f32_e32 v47, v51, v51
	v_mul_f32_e32 v41, v41, v41
	v_fmac_f32_e32 v45, v48, v48
	v_fmac_f32_e32 v39, v38, v38
	v_fmac_f32_e32 v47, v50, v50
	v_fmac_f32_e32 v41, v40, v40
	v_add_f32_e32 v38, v45, v39
	v_add_f32_e32 v39, v47, v41
	v_add_f32_e32 v45, v38, v39
	global_store_dwordx4 v[42:43], v[28:31], off
	s_waitcnt vmcnt(1)
	v_lshlrev_b32_e32 v38, 16, v32
	v_and_b32_e32 v39, 0xffff0000, v32
	v_lshlrev_b32_e32 v32, 16, v33
	v_and_b32_e32 v33, 0xffff0000, v33
	v_lshlrev_b32_e32 v40, 16, v34
	v_and_b32_e32 v41, 0xffff0000, v34
	v_lshlrev_b32_e32 v34, 16, v35
	v_and_b32_e32 v35, 0xffff0000, v35
	v_pk_mul_f32 v[32:33], v[130:131], v[32:33]
	v_pk_mul_f32 v[38:39], v[126:127], v[38:39]
	v_pk_mul_f32 v[34:35], v[128:129], v[34:35]
	v_pk_mul_f32 v[40:41], v[124:125], v[40:41]
	v_pk_mul_f32 v[38:39], v[44:45], v[38:39] op_sel_hi:[0,1]
	v_pk_mul_f32 v[32:33], v[44:45], v[32:33] op_sel_hi:[0,1]
	v_pk_mul_f32 v[40:41], v[44:45], v[40:41] op_sel_hi:[0,1]
	v_pk_mul_f32 v[34:35], v[44:45], v[34:35] op_sel_hi:[0,1]
	v_pk_fma_f32 v[26:27], v[26:27], v[46:47], v[32:33] op_sel_hi:[1,0,1]
	v_pk_fma_f32 v[24:25], v[24:25], v[46:47], v[38:39] op_sel_hi:[1,0,1]
	v_pk_fma_f32 v[32:33], v[22:23], v[46:47], v[34:35] op_sel_hi:[1,0,1]
	v_pk_fma_f32 v[34:35], v[20:21], v[46:47], v[40:41] op_sel_hi:[1,0,1]
	v_mul_f32_e32 v20, v25, v25
	v_mul_f32_e32 v21, v27, v27
	v_mul_f32_e32 v22, v35, v35
	v_mul_f32_e32 v23, v33, v33
	v_fmac_f32_e32 v20, v24, v24
	v_fmac_f32_e32 v21, v26, v26
	v_fmac_f32_e32 v22, v34, v34
	v_fmac_f32_e32 v23, v32, v32
	v_add_f32_e32 v20, v20, v21
	v_add_f32_e32 v21, v22, v23
	v_add_f32_e32 v20, v20, v21
	v_add_f32_e32 v20, v45, v20
	ds_bpermute_b32 v21, v1, v20
	v_cvt_pk_bf16_f32 v22, v24, v25
	v_cvt_pk_bf16_f32 v23, v26, v27
	v_cvt_pk_bf16_f32 v24, v34, v35
	v_cvt_pk_bf16_f32 v25, v32, v33
	s_waitcnt lgkmcnt(0)
	v_add_f32_e32 v20, v20, v21
	ds_bpermute_b32 v21, v118, v20
	global_store_dwordx4 v[42:43], v[22:25], off offset:256
	s_and_saveexec_b64 s[60:61], s[6:7]
	s_cbranch_execz .LBB0_758
	v_lshlrev_b64 v[22:23], 6, v[36:37]
	v_lshl_add_u64 v[22:23], s[38:39], 0, v[22:23]
	v_lshl_add_u64 v[22:23], s[58:59], 2, v[22:23]
	s_lshl_b32 s10, s71, 2
	v_lshl_add_u64 v[22:23], v[22:23], 0, s[10:11]
	s_waitcnt lgkmcnt(0)
	v_add_f32_e32 v20, v20, v21
	global_store_dword v[22:23], v20, off
.LBB0_758:
	s_or_b64 exec, exec, s[60:61]
	v_add_u32_e32 v20, 0xb0, v148
	s_waitcnt lgkmcnt(0)
	v_ashrrev_i32_e32 v21, 31, v20
	v_lshlrev_b64 v[22:23], 11, v[20:21]
	v_lshl_add_u64 v[22:23], s[12:13], 0, v[22:23]
	v_lshl_add_u64 v[26:27], v[2:3], 1, v[22:23]
	global_load_dwordx4 v[22:25], v[26:27], off nt
	global_load_dword v2, v[158:159], off offset:704
	global_load_dword v28, v[160:161], off offset:704
	s_waitcnt vmcnt(2)
	v_lshlrev_b32_e32 v30, 16, v22
	v_and_b32_e32 v31, 0xffff0000, v22
	v_lshlrev_b32_e32 v22, 16, v23
	v_and_b32_e32 v23, 0xffff0000, v23
	v_lshlrev_b32_e32 v32, 16, v24
	v_and_b32_e32 v33, 0xffff0000, v24
	v_lshlrev_b32_e32 v24, 16, v25
	v_and_b32_e32 v25, 0xffff0000, v25
	v_pk_mul_f32 v[22:23], v[156:157], v[22:23]
	v_pk_mul_f32 v[30:31], v[152:153], v[30:31]
	v_pk_mul_f32 v[24:25], v[154:155], v[24:25]
	v_pk_mul_f32 v[32:33], v[150:151], v[32:33]
	s_waitcnt vmcnt(1)
	v_pk_mul_f32 v[30:31], v[2:3], v[30:31] op_sel_hi:[0,1]
	v_pk_mul_f32 v[22:23], v[2:3], v[22:23] op_sel_hi:[0,1]
	v_pk_mul_f32 v[32:33], v[2:3], v[32:33] op_sel_hi:[0,1]
	v_pk_mul_f32 v[24:25], v[2:3], v[24:25] op_sel_hi:[0,1]
	s_waitcnt vmcnt(0)
	v_pk_fma_f32 v[22:23], v[18:19], v[28:29], v[22:23] op_sel_hi:[1,0,1]
	v_pk_fma_f32 v[30:31], v[16:17], v[28:29], v[30:31] op_sel_hi:[1,0,1]
	v_pk_fma_f32 v[24:25], v[14:15], v[28:29], v[24:25] op_sel_hi:[1,0,1]
	v_pk_fma_f32 v[32:33], v[12:13], v[28:29], v[32:33] op_sel_hi:[1,0,1]
	v_cvt_pk_bf16_f32 v12, v30, v31
	v_cvt_pk_bf16_f32 v13, v22, v23
	v_mul_f32_e32 v3, v31, v31
	v_cvt_pk_bf16_f32 v14, v32, v33
	v_cvt_pk_bf16_f32 v15, v24, v25
	global_load_dwordx4 v[16:19], v[26:27], off offset:256 nt
	v_mul_f32_e32 v23, v23, v23
	v_mul_f32_e32 v29, v33, v33
	v_mul_f32_e32 v25, v25, v25
	v_fmac_f32_e32 v3, v30, v30
	v_fmac_f32_e32 v23, v22, v22
	v_fmac_f32_e32 v29, v32, v32
	v_fmac_f32_e32 v25, v24, v24
	v_add_f32_e32 v3, v3, v23
	v_add_f32_e32 v22, v29, v25
	v_add_f32_e32 v29, v3, v22
	global_store_dwordx4 v[26:27], v[12:15], off
	s_waitcnt vmcnt(1)
	v_lshlrev_b32_e32 v22, 16, v16
	v_and_b32_e32 v23, 0xffff0000, v16
	v_lshlrev_b32_e32 v16, 16, v17
	v_and_b32_e32 v17, 0xffff0000, v17
	v_lshlrev_b32_e32 v24, 16, v18
	v_and_b32_e32 v25, 0xffff0000, v18
	v_lshlrev_b32_e32 v18, 16, v19
	v_and_b32_e32 v19, 0xffff0000, v19
	v_pk_mul_f32 v[16:17], v[130:131], v[16:17]
	v_pk_mul_f32 v[22:23], v[126:127], v[22:23]
	v_pk_mul_f32 v[18:19], v[128:129], v[18:19]
	v_pk_mul_f32 v[24:25], v[124:125], v[24:25]
	v_pk_mul_f32 v[22:23], v[2:3], v[22:23] op_sel_hi:[0,1]
	v_pk_mul_f32 v[16:17], v[2:3], v[16:17] op_sel_hi:[0,1]
	v_pk_mul_f32 v[24:25], v[2:3], v[24:25] op_sel_hi:[0,1]
	v_pk_mul_f32 v[2:3], v[2:3], v[18:19] op_sel_hi:[0,1]
	v_pk_fma_f32 v[10:11], v[10:11], v[28:29], v[16:17] op_sel_hi:[1,0,1]
	v_pk_fma_f32 v[8:9], v[8:9], v[28:29], v[22:23] op_sel_hi:[1,0,1]
	v_pk_fma_f32 v[16:17], v[6:7], v[28:29], v[2:3] op_sel_hi:[1,0,1]
	v_pk_fma_f32 v[6:7], v[4:5], v[28:29], v[24:25] op_sel_hi:[1,0,1]
	v_mul_f32_e32 v2, v9, v9
	v_mul_f32_e32 v3, v11, v11
	v_mul_f32_e32 v4, v7, v7
	v_mul_f32_e32 v5, v17, v17
	v_fmac_f32_e32 v2, v8, v8
	v_fmac_f32_e32 v3, v10, v10
	v_fmac_f32_e32 v4, v6, v6
	v_fmac_f32_e32 v5, v16, v16
	v_add_f32_e32 v2, v2, v3
	v_add_f32_e32 v3, v4, v5
	v_add_f32_e32 v2, v2, v3
	v_add_f32_e32 v2, v29, v2
	ds_bpermute_b32 v1, v1, v2
	v_cvt_pk_bf16_f32 v4, v8, v9
	v_cvt_pk_bf16_f32 v5, v10, v11
	v_cvt_pk_bf16_f32 v6, v6, v7
	v_cvt_pk_bf16_f32 v7, v16, v17
	s_waitcnt lgkmcnt(0)
	v_add_f32_e32 v1, v2, v1
	ds_bpermute_b32 v2, v118, v1
	global_store_dwordx4 v[26:27], v[4:7], off offset:256
	s_and_saveexec_b64 s[60:61], s[6:7]
	s_cbranch_execz .LBB0_760
	v_lshlrev_b64 v[4:5], 6, v[20:21]
	v_lshl_add_u64 v[4:5], s[38:39], 0, v[4:5]
	v_lshl_add_u64 v[4:5], s[58:59], 2, v[4:5]
	s_lshl_b32 s10, s71, 2
	v_lshl_add_u64 v[4:5], v[4:5], 0, s[10:11]
	s_waitcnt lgkmcnt(0)
	v_add_f32_e32 v1, v1, v2
	global_store_dword v[4:5], v1, off

.LBB0_1070:
	s_and_b64 vcc, exec, s[0:1]
	s_mov_b64 s[0:1], -1
	v_mbcnt_lo_u32_b32 v144, -1, 0
	v_mbcnt_hi_u32_b32 v144, -1, v144
	s_lshr_b32 s60, s33, 12
	s_lshl_b32 s61, s53, 2
	s_add_i32 s60, s60, s61
	s_lshr_b32 s61, s33, 10
	s_and_b32 s61, s61, 3
	s_lshl_b32 s62, s60, 18
	s_lshl_b32 s60, s60, 17
	s_lshl_b32 s63, s54, 9
	s_add_i32 s60, s60, s63
	s_lshl_b32 s63, s54, 10
	s_add_i32 s62, s62, s63
	s_lshl_b32 s63, s61, 6
	s_add_i32 s60, s60, s63
	s_lshl_b32 s63, s61, 7
	s_add_i32 s62, s62, s63
	s_lshr_b32 s61, s33, 10
	s_mulk_i32 s61, 0x500
	s_add_i32 s61, s61, 0x20400
	v_lshrrev_b32_e32 v140, 2, v144
	v_and_b32_e32 v145, 3, v144
	v_mul_u32_u24_e32 v141, 0x50, v140
	v_lshl_add_u32 v141, v145, 4, v141
	v_add_u32_e32 v141, s61, v141
	v_lshlrev_b32_e32 v143, 12, v140
	v_lshl_add_u32 v143, v145, 4, v143
	v_add_u32_e32 v143, s62, v143
	v_lshlrev_b32_e32 v140, 11, v140
	v_lshl_add_u32 v140, v145, 4, v140
	v_add_u32_e32 v140, s60, v140
	v_and_b32_e32 v145, 15, v144
	v_lshrrev_b32_e32 v144, 4, v144
	v_mul_u32_u24_e32 v142, 0x50, v145
	v_add_u32_e32 v142, s61, v142
	v_lshl_add_u32 v152, v144, 4, v142
	v_lshl_add_u32 v142, v144, 3, v142
	global_load_dwordx4 v[160:163], v140, s[12:13] nt
	global_load_dwordx4 v[164:167], v140, s[12:13] offset:256 nt
	v_add_u32_e32 v144, 0x8000, v140
	global_load_dwordx4 v[168:171], v144, s[12:13] nt
	global_load_dwordx4 v[172:175], v144, s[12:13] offset:256 nt
	v_add_u32_e32 v144, 0x10000, v140
	global_load_dwordx4 v[176:179], v144, s[12:13] nt
	global_load_dwordx4 v[180:183], v144, s[12:13] offset:256 nt
	v_add_u32_e32 v144, 0x18000, v140
	global_load_dwordx4 v[184:187], v144, s[12:13] nt
	global_load_dwordx4 v[188:191], v144, s[12:13] offset:256 nt
	v_add_u32_e32 v144, 0x40000, v140
	global_load_dwordx4 v[192:195], v144, s[12:13] nt
	global_load_dwordx4 v[196:199], v144, s[12:13] offset:256 nt
	v_add_u32_e32 v144, 0x48000, v140
	global_load_dwordx4 v[200:203], v144, s[12:13] nt
	global_load_dwordx4 v[204:207], v144, s[12:13] offset:256 nt
	v_add_u32_e32 v144, 0x50000, v140
	global_load_dwordx4 v[208:211], v144, s[12:13] nt
	global_load_dwordx4 v[212:215], v144, s[12:13] offset:256 nt
	v_add_u32_e32 v144, 0x58000, v140
	global_load_dwordx4 v[216:219], v144, s[12:13] nt
	global_load_dwordx4 v[220:223], v144, s[12:13] offset:256 nt
	s_waitcnt vmcnt(15)
	ds_write_b128 v141, v[160:163]
	ds_read2_b64 v[232:235], v142 offset1:4
	s_waitcnt lgkmcnt(0)
	v_lshlrev_b32_e32 v224, 16, v232
	v_and_b32_e32 v225, 0xffff0000, v232
	v_lshlrev_b32_e32 v226, 16, v233
	v_and_b32_e32 v227, 0xffff0000, v233
	v_pk_add_f32 v[124:125], v[124:125], v[224:225]
	v_pk_add_f32 v[126:127], v[126:127], v[226:227]
	v_lshlrev_b32_e32 v228, 16, v234
	v_and_b32_e32 v229, 0xffff0000, v234
	v_lshlrev_b32_e32 v230, 16, v235
	v_and_b32_e32 v231, 0xffff0000, v235
	v_pk_add_f32 v[120:121], v[120:121], v[228:229]
	v_pk_add_f32 v[122:123], v[122:123], v[230:231]
	ds_write_b128 v152, v[124:127]
	ds_read_b128 v[236:239], v141
	s_waitcnt lgkmcnt(0)
	global_store_dwordx4 v143, v[236:239], s[28:29]
	ds_write_b128 v152, v[120:123]
	ds_read_b128 v[240:243], v141
	s_waitcnt lgkmcnt(0)
	global_store_dwordx4 v143, v[240:243], s[28:29] offset:64
	s_waitcnt vmcnt(16)
	ds_write_b128 v141, v[164:167]
	ds_read2_b64 v[232:235], v142 offset1:4
	s_waitcnt lgkmcnt(0)
	v_lshlrev_b32_e32 v224, 16, v232
	v_and_b32_e32 v225, 0xffff0000, v232
	v_lshlrev_b32_e32 v226, 16, v233
	v_and_b32_e32 v227, 0xffff0000, v233
	v_pk_add_f32 v[116:117], v[116:117], v[224:225]
	v_pk_add_f32 v[118:119], v[118:119], v[226:227]
	v_lshlrev_b32_e32 v228, 16, v234
	v_and_b32_e32 v229, 0xffff0000, v234
	v_lshlrev_b32_e32 v230, 16, v235
	v_and_b32_e32 v231, 0xffff0000, v235
	v_pk_add_f32 v[108:109], v[108:109], v[228:229]
	v_pk_add_f32 v[110:111], v[110:111], v[230:231]
	ds_write_b128 v152, v[116:119]
	ds_read_b128 v[236:239], v141
	s_waitcnt lgkmcnt(0)
	global_store_dwordx4 v143, v[236:239], s[28:29] offset:512
	ds_write_b128 v152, v[108:111]
	ds_read_b128 v[240:243], v141
	s_waitcnt lgkmcnt(0)
	global_store_dwordx4 v143, v[240:243], s[28:29] offset:576
	v_add_u32_e32 v144, 0x10000, v143
	s_waitcnt vmcnt(17)
	ds_write_b128 v141, v[168:171]
	ds_read2_b64 v[232:235], v142 offset1:4
	s_waitcnt lgkmcnt(0)
	v_lshlrev_b32_e32 v224, 16, v232
	v_and_b32_e32 v225, 0xffff0000, v232
	v_lshlrev_b32_e32 v226, 16, v233
	v_and_b32_e32 v227, 0xffff0000, v233
	v_pk_add_f32 v[112:113], v[112:113], v[224:225]
	v_pk_add_f32 v[114:115], v[114:115], v[226:227]
	v_lshlrev_b32_e32 v228, 16, v234
	v_and_b32_e32 v229, 0xffff0000, v234
	v_lshlrev_b32_e32 v230, 16, v235
	v_and_b32_e32 v231, 0xffff0000, v235
	v_pk_add_f32 v[104:105], v[104:105], v[228:229]
	v_pk_add_f32 v[106:107], v[106:107], v[230:231]
	ds_write_b128 v152, v[112:115]
	ds_read_b128 v[236:239], v141
	s_waitcnt lgkmcnt(0)
	global_store_dwordx4 v144, v[236:239], s[28:29]
	ds_write_b128 v152, v[104:107]
	ds_read_b128 v[240:243], v141
	s_waitcnt lgkmcnt(0)
	global_store_dwordx4 v144, v[240:243], s[28:29] offset:64
	s_waitcnt vmcnt(18)
	ds_write_b128 v141, v[172:175]
	ds_read2_b64 v[232:235], v142 offset1:4
	s_waitcnt lgkmcnt(0)
	v_lshlrev_b32_e32 v224, 16, v232
	v_and_b32_e32 v225, 0xffff0000, v232
	v_lshlrev_b32_e32 v226, 16, v233
	v_and_b32_e32 v227, 0xffff0000, v233
	v_pk_add_f32 v[100:101], v[100:101], v[224:225]
	v_pk_add_f32 v[102:103], v[102:103], v[226:227]
	v_lshlrev_b32_e32 v228, 16, v234
	v_and_b32_e32 v229, 0xffff0000, v234
	v_lshlrev_b32_e32 v230, 16, v235
	v_and_b32_e32 v231, 0xffff0000, v235
	v_pk_add_f32 v[92:93], v[92:93], v[228:229]
	v_pk_add_f32 v[94:95], v[94:95], v[230:231]
	ds_write_b128 v152, v[100:103]
	ds_read_b128 v[236:239], v141
	s_waitcnt lgkmcnt(0)
	global_store_dwordx4 v144, v[236:239], s[28:29] offset:512
	ds_write_b128 v152, v[92:95]
	ds_read_b128 v[240:243], v141
	s_waitcnt lgkmcnt(0)
	global_store_dwordx4 v144, v[240:243], s[28:29] offset:576
	v_add_u32_e32 v144, 0x20000, v143
	s_waitcnt vmcnt(19)
	ds_write_b128 v141, v[176:179]
	ds_read2_b64 v[232:235], v142 offset1:4
	s_waitcnt lgkmcnt(0)
	v_lshlrev_b32_e32 v224, 16, v232
	v_and_b32_e32 v225, 0xffff0000, v232
	v_lshlrev_b32_e32 v226, 16, v233
	v_and_b32_e32 v227, 0xffff0000, v233
	v_pk_add_f32 v[96:97], v[96:97], v[224:225]
	v_pk_add_f32 v[98:99], v[98:99], v[226:227]
	v_lshlrev_b32_e32 v228, 16, v234
	v_and_b32_e32 v229, 0xffff0000, v234
	v_lshlrev_b32_e32 v230, 16, v235
	v_and_b32_e32 v231, 0xffff0000, v235
	v_pk_add_f32 v[88:89], v[88:89], v[228:229]
	v_pk_add_f32 v[90:91], v[90:91], v[230:231]
	ds_write_b128 v152, v[96:99]
	ds_read_b128 v[236:239], v141
	s_waitcnt lgkmcnt(0)
	global_store_dwordx4 v144, v[236:239], s[28:29]
	ds_write_b128 v152, v[88:91]
	ds_read_b128 v[240:243], v141
	s_waitcnt lgkmcnt(0)
	global_store_dwordx4 v144, v[240:243], s[28:29] offset:64
	s_waitcnt vmcnt(20)
	ds_write_b128 v141, v[180:183]
	ds_read2_b64 v[232:235], v142 offset1:4
	s_waitcnt lgkmcnt(0)
	v_lshlrev_b32_e32 v224, 16, v232
	v_and_b32_e32 v225, 0xffff0000, v232
	v_lshlrev_b32_e32 v226, 16, v233
	v_and_b32_e32 v227, 0xffff0000, v233
	v_pk_add_f32 v[84:85], v[84:85], v[224:225]
	v_pk_add_f32 v[86:87], v[86:87], v[226:227]
	v_lshlrev_b32_e32 v228, 16, v234
	v_and_b32_e32 v229, 0xffff0000, v234
	v_lshlrev_b32_e32 v230, 16, v235
	v_and_b32_e32 v231, 0xffff0000, v235
	v_pk_add_f32 v[76:77], v[76:77], v[228:229]
	v_pk_add_f32 v[78:79], v[78:79], v[230:231]
	ds_write_b128 v152, v[84:87]
	ds_read_b128 v[236:239], v141
	s_waitcnt lgkmcnt(0)
	global_store_dwordx4 v144, v[236:239], s[28:29] offset:512
	ds_write_b128 v152, v[76:79]
	ds_read_b128 v[240:243], v141
	s_waitcnt lgkmcnt(0)
	global_store_dwordx4 v144, v[240:243], s[28:29] offset:576
	v_add_u32_e32 v144, 0x30000, v143
	s_waitcnt vmcnt(21)
	ds_write_b128 v141, v[184:187]
	ds_read2_b64 v[232:235], v142 offset1:4
	s_waitcnt lgkmcnt(0)
	v_lshlrev_b32_e32 v224, 16, v232
	v_and_b32_e32 v225, 0xffff0000, v232
	v_lshlrev_b32_e32 v226, 16, v233
	v_and_b32_e32 v227, 0xffff0000, v233
	v_pk_add_f32 v[80:81], v[80:81], v[224:225]
	v_pk_add_f32 v[82:83], v[82:83], v[226:227]
	v_lshlrev_b32_e32 v228, 16, v234
	v_and_b32_e32 v229, 0xffff0000, v234
	v_lshlrev_b32_e32 v230, 16, v235
	v_and_b32_e32 v231, 0xffff0000, v235
	v_pk_add_f32 v[72:73], v[72:73], v[228:229]
	v_pk_add_f32 v[74:75], v[74:75], v[230:231]
	ds_write_b128 v152, v[80:83]
	ds_read_b128 v[236:239], v141
	s_waitcnt lgkmcnt(0)
	global_store_dwordx4 v144, v[236:239], s[28:29]
	ds_write_b128 v152, v[72:75]
	ds_read_b128 v[240:243], v141
	s_waitcnt lgkmcnt(0)
	global_store_dwordx4 v144, v[240:243], s[28:29] offset:64
	s_waitcnt vmcnt(22)
	ds_write_b128 v141, v[188:191]
	ds_read2_b64 v[232:235], v142 offset1:4
	s_waitcnt lgkmcnt(0)
	v_lshlrev_b32_e32 v224, 16, v232
	v_and_b32_e32 v225, 0xffff0000, v232
	v_lshlrev_b32_e32 v226, 16, v233
	v_and_b32_e32 v227, 0xffff0000, v233
	v_pk_add_f32 v[68:69], v[68:69], v[224:225]
	v_pk_add_f32 v[70:71], v[70:71], v[226:227]
	v_lshlrev_b32_e32 v228, 16, v234
	v_and_b32_e32 v229, 0xffff0000, v234
	v_lshlrev_b32_e32 v230, 16, v235
	v_and_b32_e32 v231, 0xffff0000, v235
	v_pk_add_f32 v[64:65], v[64:65], v[228:229]
	v_pk_add_f32 v[66:67], v[66:67], v[230:231]
	ds_write_b128 v152, v[68:71]
	ds_read_b128 v[236:239], v141
	s_waitcnt lgkmcnt(0)
	global_store_dwordx4 v144, v[236:239], s[28:29] offset:512
	ds_write_b128 v152, v[64:67]
	ds_read_b128 v[240:243], v141
	s_waitcnt lgkmcnt(0)
	global_store_dwordx4 v144, v[240:243], s[28:29] offset:576
	v_add_u32_e32 v144, 0x80000, v143
	s_waitcnt vmcnt(23)
	ds_write_b128 v141, v[192:195]
	ds_read2_b64 v[232:235], v142 offset1:4
	s_waitcnt lgkmcnt(0)
	v_lshlrev_b32_e32 v224, 16, v232
	v_and_b32_e32 v225, 0xffff0000, v232
	v_lshlrev_b32_e32 v226, 16, v233
	v_and_b32_e32 v227, 0xffff0000, v233
	v_pk_add_f32 v[60:61], v[60:61], v[224:225]
	v_pk_add_f32 v[62:63], v[62:63], v[226:227]
	v_lshlrev_b32_e32 v228, 16, v234
	v_and_b32_e32 v229, 0xffff0000, v234
	v_lshlrev_b32_e32 v230, 16, v235
	v_and_b32_e32 v231, 0xffff0000, v235
	v_pk_add_f32 v[56:57], v[56:57], v[228:229]
	v_pk_add_f32 v[58:59], v[58:59], v[230:231]
	ds_write_b128 v152, v[60:63]
	ds_read_b128 v[236:239], v141
	s_waitcnt lgkmcnt(0)
	global_store_dwordx4 v144, v[236:239], s[28:29]
	ds_write_b128 v152, v[56:59]
	ds_read_b128 v[240:243], v141
	s_waitcnt lgkmcnt(0)
	global_store_dwordx4 v144, v[240:243], s[28:29] offset:64
	s_waitcnt vmcnt(24)
	ds_write_b128 v141, v[196:199]
	ds_read2_b64 v[232:235], v142 offset1:4
	s_waitcnt lgkmcnt(0)
	v_lshlrev_b32_e32 v224, 16, v232
	v_and_b32_e32 v225, 0xffff0000, v232
	v_lshlrev_b32_e32 v226, 16, v233
	v_and_b32_e32 v227, 0xffff0000, v233
	v_pk_add_f32 v[52:53], v[52:53], v[224:225]
	v_pk_add_f32 v[54:55], v[54:55], v[226:227]
	v_lshlrev_b32_e32 v228, 16, v234
	v_and_b32_e32 v229, 0xffff0000, v234
	v_lshlrev_b32_e32 v230, 16, v235
	v_and_b32_e32 v231, 0xffff0000, v235
	v_pk_add_f32 v[44:45], v[44:45], v[228:229]
	v_pk_add_f32 v[46:47], v[46:47], v[230:231]
	ds_write_b128 v152, v[52:55]
	ds_read_b128 v[236:239], v141
	s_waitcnt lgkmcnt(0)
	global_store_dwordx4 v144, v[236:239], s[28:29] offset:512
	ds_write_b128 v152, v[44:47]
	ds_read_b128 v[240:243], v141
	s_waitcnt lgkmcnt(0)
	global_store_dwordx4 v144, v[240:243], s[28:29] offset:576
	v_add_u32_e32 v144, 0x90000, v143
	s_waitcnt vmcnt(25)
	ds_write_b128 v141, v[200:203]
	ds_read2_b64 v[232:235], v142 offset1:4
	s_waitcnt lgkmcnt(0)
	v_lshlrev_b32_e32 v224, 16, v232
	v_and_b32_e32 v225, 0xffff0000, v232
	v_lshlrev_b32_e32 v226, 16, v233
	v_and_b32_e32 v227, 0xffff0000, v233
	v_pk_add_f32 v[48:49], v[48:49], v[224:225]
	v_pk_add_f32 v[50:51], v[50:51], v[226:227]
	v_lshlrev_b32_e32 v228, 16, v234
	v_and_b32_e32 v229, 0xffff0000, v234
	v_lshlrev_b32_e32 v230, 16, v235
	v_and_b32_e32 v231, 0xffff0000, v235
	v_pk_add_f32 v[40:41], v[40:41], v[228:229]
	v_pk_add_f32 v[42:43], v[42:43], v[230:231]
	ds_write_b128 v152, v[48:51]
	ds_read_b128 v[236:239], v141
	s_waitcnt lgkmcnt(0)
	global_store_dwordx4 v144, v[236:239], s[28:29]
	ds_write_b128 v152, v[40:43]
	ds_read_b128 v[240:243], v141
	s_waitcnt lgkmcnt(0)
	global_store_dwordx4 v144, v[240:243], s[28:29] offset:64
	s_waitcnt vmcnt(26)
	ds_write_b128 v141, v[204:207]
	ds_read2_b64 v[232:235], v142 offset1:4
	s_waitcnt lgkmcnt(0)
	v_lshlrev_b32_e32 v224, 16, v232
	v_and_b32_e32 v225, 0xffff0000, v232
	v_lshlrev_b32_e32 v226, 16, v233
	v_and_b32_e32 v227, 0xffff0000, v233
	v_pk_add_f32 v[36:37], v[36:37], v[224:225]
	v_pk_add_f32 v[38:39], v[38:39], v[226:227]
	v_lshlrev_b32_e32 v228, 16, v234
	v_and_b32_e32 v229, 0xffff0000, v234
	v_lshlrev_b32_e32 v230, 16, v235
	v_and_b32_e32 v231, 0xffff0000, v235
	v_pk_add_f32 v[28:29], v[28:29], v[228:229]
	v_pk_add_f32 v[30:31], v[30:31], v[230:231]
	ds_write_b128 v152, v[36:39]
	ds_read_b128 v[236:239], v141
	s_waitcnt lgkmcnt(0)
	global_store_dwordx4 v144, v[236:239], s[28:29] offset:512
	ds_write_b128 v152, v[28:31]
	ds_read_b128 v[240:243], v141
	s_waitcnt lgkmcnt(0)
	global_store_dwordx4 v144, v[240:243], s[28:29] offset:576
	v_add_u32_e32 v144, 0xa0000, v143
	s_waitcnt vmcnt(27)
	ds_write_b128 v141, v[208:211]
	ds_read2_b64 v[232:235], v142 offset1:4
	s_waitcnt lgkmcnt(0)
	v_lshlrev_b32_e32 v224, 16, v232
	v_and_b32_e32 v225, 0xffff0000, v232
	v_lshlrev_b32_e32 v226, 16, v233
	v_and_b32_e32 v227, 0xffff0000, v233
	v_pk_add_f32 v[32:33], v[32:33], v[224:225]
	v_pk_add_f32 v[34:35], v[34:35], v[226:227]
	v_lshlrev_b32_e32 v228, 16, v234
	v_and_b32_e32 v229, 0xffff0000, v234
	v_lshlrev_b32_e32 v230, 16, v235
	v_and_b32_e32 v231, 0xffff0000, v235
	v_pk_add_f32 v[24:25], v[24:25], v[228:229]
	v_pk_add_f32 v[26:27], v[26:27], v[230:231]
	ds_write_b128 v152, v[32:35]
	ds_read_b128 v[236:239], v141
	s_waitcnt lgkmcnt(0)
	global_store_dwordx4 v144, v[236:239], s[28:29]
	ds_write_b128 v152, v[24:27]
	ds_read_b128 v[240:243], v141
	s_waitcnt lgkmcnt(0)
	global_store_dwordx4 v144, v[240:243], s[28:29] offset:64
	s_waitcnt vmcnt(28)
	ds_write_b128 v141, v[212:215]
	ds_read2_b64 v[232:235], v142 offset1:4
	s_waitcnt lgkmcnt(0)
	v_lshlrev_b32_e32 v224, 16, v232
	v_and_b32_e32 v225, 0xffff0000, v232
	v_lshlrev_b32_e32 v226, 16, v233
	v_and_b32_e32 v227, 0xffff0000, v233
	v_pk_add_f32 v[20:21], v[20:21], v[224:225]
	v_pk_add_f32 v[22:23], v[22:23], v[226:227]
	v_lshlrev_b32_e32 v228, 16, v234
	v_and_b32_e32 v229, 0xffff0000, v234
	v_lshlrev_b32_e32 v230, 16, v235
	v_and_b32_e32 v231, 0xffff0000, v235
	v_pk_add_f32 v[12:13], v[12:13], v[228:229]
	v_pk_add_f32 v[14:15], v[14:15], v[230:231]
	ds_write_b128 v152, v[20:23]
	ds_read_b128 v[236:239], v141
	s_waitcnt lgkmcnt(0)
	global_store_dwordx4 v144, v[236:239], s[28:29] offset:512
	ds_write_b128 v152, v[12:15]
	ds_read_b128 v[240:243], v141
	s_waitcnt lgkmcnt(0)
	global_store_dwordx4 v144, v[240:243], s[28:29] offset:576
	v_add_u32_e32 v144, 0xb0000, v143
	s_waitcnt vmcnt(29)
	ds_write_b128 v141, v[216:219]
	ds_read2_b64 v[232:235], v142 offset1:4
	s_waitcnt lgkmcnt(0)
	v_lshlrev_b32_e32 v224, 16, v232
	v_and_b32_e32 v225, 0xffff0000, v232
	v_lshlrev_b32_e32 v226, 16, v233
	v_and_b32_e32 v227, 0xffff0000, v233
	v_pk_add_f32 v[16:17], v[16:17], v[224:225]
	v_pk_add_f32 v[18:19], v[18:19], v[226:227]
	v_lshlrev_b32_e32 v228, 16, v234
	v_and_b32_e32 v229, 0xffff0000, v234
	v_lshlrev_b32_e32 v230, 16, v235
	v_and_b32_e32 v231, 0xffff0000, v235
	v_pk_add_f32 v[8:9], v[8:9], v[228:229]
	v_pk_add_f32 v[10:11], v[10:11], v[230:231]
	ds_write_b128 v152, v[16:19]
	ds_read_b128 v[236:239], v141
	s_waitcnt lgkmcnt(0)
	global_store_dwordx4 v144, v[236:239], s[28:29]
	ds_write_b128 v152, v[8:11]
	ds_read_b128 v[240:243], v141
	s_waitcnt lgkmcnt(0)
	global_store_dwordx4 v144, v[240:243], s[28:29] offset:64
	s_waitcnt vmcnt(30)
	ds_write_b128 v141, v[220:223]
	ds_read2_b64 v[232:235], v142 offset1:4
	s_waitcnt lgkmcnt(0)
	v_lshlrev_b32_e32 v224, 16, v232
	v_and_b32_e32 v225, 0xffff0000, v232
	v_lshlrev_b32_e32 v226, 16, v233
	v_and_b32_e32 v227, 0xffff0000, v233
	v_pk_add_f32 v[4:5], v[4:5], v[224:225]
	v_pk_add_f32 v[6:7], v[6:7], v[226:227]
	v_lshlrev_b32_e32 v228, 16, v234
	v_and_b32_e32 v229, 0xffff0000, v234
	v_lshlrev_b32_e32 v230, 16, v235
	v_and_b32_e32 v231, 0xffff0000, v235
	v_pk_add_f32 v[0:1], v[0:1], v[228:229]
	v_pk_add_f32 v[2:3], v[2:3], v[230:231]
	ds_write_b128 v152, v[4:7]
	ds_read_b128 v[236:239], v141
	s_waitcnt lgkmcnt(0)
	global_store_dwordx4 v144, v[236:239], s[28:29] offset:512
	ds_write_b128 v152, v[0:3]
	ds_read_b128 v[240:243], v141
	s_waitcnt lgkmcnt(0)
	global_store_dwordx4 v144, v[240:243], s[28:29] offset:576
	s_cbranch_vccnz .LBB0_1055
	s_andn2_b64 vcc, exec, s[6:7]
	s_cbranch_vccnz .LBB0_1054
	s_barrier
	s_branch .LBB0_1054
